# speedup vs baseline: 1.0194x; 1.0010x over previous
; __device__ __forceinline__ uint4 pk8(f32x4 a, f32x4 b) { return make_uint4(cvt_pk_bf16(a[0], a[1]), cvt_pk_bf16(a[2], a[3]), cvt_pk_bf16(b[0], b[1]), cvt_pk_bf16(b[2], b[3])); }
;     __device__ __forceinline__ void operator()(AccRef acc, const Unit& u, int wr, int wc, int fr, int fq) const {
;         const int pi = u.pn / tpp; bf16_t* base = pi == 0 ? pl[0] : (pi == 1 ? pl[1] : (pi == 2 ? pl[2] : pl[3]));
;         const int cbase = (u.pn - pi * tpp) * 256 + wc * 32 + 8 * fq;
; #pragma unroll
;         for (int ai = 0; ai < 2; ++ai)
; #pragma unroll
;             for (int m = 0; m < 4; ++m) {
;                 const int r = u.pm * 256 + ai * 128 + wr * 64 + m * 16 + fr;
;                 float s = 1.f;
;                 if (SCALE == 1) s = rs[r];
;                 if (SCALE == 2) s = rsqrtf(rs[r] * (1.f / D) + EPS);
;                 bf16_t* rowp = base + (size_t)r * ldc + cbase;
; #pragma unroll
;                 for (int bj = 0; bj < 2; ++bj) *(uint4*)(rowp + bj * 128) = pk8(acc[ai][bj][m][0] * s, acc[ai][bj][m][1] * s);
;             }
.LBB0_107:
	s_cmp_lt_u32 s13, 2
	s_cselect_b32 s99, -1, 0
	s_lshl_b32 s11, s18, 8
	v_add_u32_e32 v138, s11, v158
	v_ashrrev_i32_e32 v139, 31, v138
	v_lshl_add_u64 v[136:137], v[138:139], 2, s[28:29]
	global_load_dword v168, v[136:137], off
	s_lshl_b32 s13, s13, 10
	s_lshl_b32 s18, s50, 8
	s_sub_i32 s13, s18, s13
	v_or_b32_e32 v136, s13, v163
	v_ashrrev_i32_e32 v137, 31, v136
	v_add_u32_e32 v170, s11, v160
	v_lshlrev_b64 v[172:173], 11, v[138:139]
	v_lshl_add_u64 v[136:137], v[136:137], 1, s[20:21]
	v_bfe_i32 v200, v144, 0, 1
	v_and_b32_e32 v200, 0xfffff840, v200
	v_bfe_u32 v201, v146, 1, 1
	v_mul_u32_u24_e32 v201, 0x780, v201
	v_add_u32_e32 v200, v200, v201
	v_and_b32_e32 v201, 1, v146
	v_lshl_add_u32 v200, v201, 6, v200
	v_and_b32_e32 v200, s99, v200
	v_ashrrev_i32_e32 v201, 31, v200
	v_lshl_add_u64 v[136:137], v[200:201], 0, v[136:137]
	v_ashrrev_i32_e32 v171, 31, v170
	v_lshl_add_u64 v[172:173], v[136:137], 0, v[172:173]
	v_lshl_add_u64 v[174:175], v[170:171], 2, s[28:29]
	s_and_b64 vcc, exec, s[4:5]
	s_mov_b32 s50, s10
	s_mov_b32 s18, s12
	s_mov_b64 s[22:23], s[16:17]
	s_mov_b64 s[20:21], s[14:15]
	global_load_dword v178, v[174:175], off
	v_add_u32_e32 v200, s11, v161
	v_ashrrev_i32_e32 v201, 31, v200
	v_lshl_add_u64 v[202:203], v[200:201], 2, s[28:29]
	global_load_dword v180, v[202:203], off
	v_add_u32_e32 v200, s11, v162
	v_ashrrev_i32_e32 v201, 31, v200
	v_lshl_add_u64 v[202:203], v[200:201], 2, s[28:29]
	global_load_dword v182, v[202:203], off
	v_add_u32_e32 v200, 0x80, v138
	v_ashrrev_i32_e32 v201, 31, v200
	v_lshl_add_u64 v[202:203], v[200:201], 2, s[28:29]
	global_load_dword v184, v[202:203], off
	v_add_u32_e32 v200, 0x90, v138
	v_ashrrev_i32_e32 v201, 31, v200
	v_lshl_add_u64 v[202:203], v[200:201], 2, s[28:29]
	global_load_dword v186, v[202:203], off
	v_add_u32_e32 v200, 0xa0, v138
	v_ashrrev_i32_e32 v201, 31, v200
	v_lshl_add_u64 v[202:203], v[200:201], 2, s[28:29]
	global_load_dword v188, v[202:203], off
	v_add_u32_e32 v200, 0xb0, v138
	v_ashrrev_i32_e32 v201, 31, v200
	v_lshl_add_u64 v[202:203], v[200:201], 2, s[28:29]
	global_load_dword v190, v[202:203], off
	s_waitcnt vmcnt(7)
	v_pk_mul_f32 v[126:127], v[126:127], v[168:169] op_sel_hi:[1,0]
	v_pk_mul_f32 v[124:125], v[124:125], v[168:169] op_sel_hi:[1,0]
	v_pk_mul_f32 v[122:123], v[122:123], v[168:169] op_sel_hi:[1,0]
	v_pk_mul_f32 v[120:121], v[120:121], v[168:169] op_sel_hi:[1,0]
	v_pk_mul_f32 v[118:119], v[118:119], v[168:169] op_sel_hi:[1,0]
	v_pk_mul_f32 v[116:117], v[116:117], v[168:169] op_sel_hi:[1,0]
	v_pk_mul_f32 v[176:177], v[114:115], v[168:169] op_sel_hi:[1,0]
	v_pk_mul_f32 v[168:169], v[112:113], v[168:169] op_sel_hi:[1,0]
	v_cvt_pk_bf16_f32 v112, v124, v125
	v_cvt_pk_bf16_f32 v113, v126, v127
	v_cvt_pk_bf16_f32 v114, v120, v121
	v_cvt_pk_bf16_f32 v115, v122, v123
	global_store_dwordx4 v[172:173], v[112:115], off
	s_nop 1
	v_cvt_pk_bf16_f32 v112, v116, v117
	v_cvt_pk_bf16_f32 v113, v118, v119
	v_cvt_pk_bf16_f32 v114, v168, v169
	v_cvt_pk_bf16_f32 v115, v176, v177
	global_store_dwordx4 v[172:173], v[112:115], off offset:256
	v_lshlrev_b64 v[116:117], 11, v[170:171]
	v_add_u32_e32 v114, s11, v161
	v_ashrrev_i32_e32 v115, 31, v114
	v_lshl_add_u64 v[116:117], v[136:137], 0, v[116:117]
	v_lshl_add_u64 v[118:119], v[114:115], 2, s[28:29]
	s_waitcnt vmcnt(8)
	v_pk_mul_f32 v[110:111], v[110:111], v[178:179] op_sel_hi:[1,0]
	v_pk_mul_f32 v[108:109], v[108:109], v[178:179] op_sel_hi:[1,0]
	v_pk_mul_f32 v[106:107], v[106:107], v[178:179] op_sel_hi:[1,0]
	v_pk_mul_f32 v[104:105], v[104:105], v[178:179] op_sel_hi:[1,0]
	v_pk_mul_f32 v[102:103], v[102:103], v[178:179] op_sel_hi:[1,0]
	v_pk_mul_f32 v[100:101], v[100:101], v[178:179] op_sel_hi:[1,0]
	v_pk_mul_f32 v[120:121], v[98:99], v[178:179] op_sel_hi:[1,0]
	v_pk_mul_f32 v[112:113], v[96:97], v[178:179] op_sel_hi:[1,0]
	v_cvt_pk_bf16_f32 v96, v108, v109
	v_cvt_pk_bf16_f32 v97, v110, v111
	v_cvt_pk_bf16_f32 v98, v104, v105
	v_cvt_pk_bf16_f32 v99, v106, v107
	global_store_dwordx4 v[116:117], v[96:99], off
	s_nop 1
	v_cvt_pk_bf16_f32 v96, v100, v101
	v_cvt_pk_bf16_f32 v97, v102, v103
	v_cvt_pk_bf16_f32 v98, v112, v113
	v_cvt_pk_bf16_f32 v99, v120, v121
	global_store_dwordx4 v[116:117], v[96:99], off offset:256
	v_lshlrev_b64 v[100:101], 11, v[114:115]
	v_add_u32_e32 v98, s11, v162
	v_ashrrev_i32_e32 v99, 31, v98
	v_lshl_add_u64 v[100:101], v[136:137], 0, v[100:101]
	v_lshl_add_u64 v[102:103], v[98:99], 2, s[28:29]
	s_waitcnt vmcnt(9)
	v_pk_mul_f32 v[94:95], v[94:95], v[180:181] op_sel_hi:[1,0]
	v_pk_mul_f32 v[92:93], v[92:93], v[180:181] op_sel_hi:[1,0]
	v_pk_mul_f32 v[90:91], v[90:91], v[180:181] op_sel_hi:[1,0]
	v_pk_mul_f32 v[88:89], v[88:89], v[180:181] op_sel_hi:[1,0]
	v_pk_mul_f32 v[86:87], v[86:87], v[180:181] op_sel_hi:[1,0]
	v_pk_mul_f32 v[84:85], v[84:85], v[180:181] op_sel_hi:[1,0]
	v_pk_mul_f32 v[104:105], v[82:83], v[180:181] op_sel_hi:[1,0]
	v_pk_mul_f32 v[96:97], v[80:81], v[180:181] op_sel_hi:[1,0]
	v_cvt_pk_bf16_f32 v80, v92, v93
	v_cvt_pk_bf16_f32 v81, v94, v95
	v_cvt_pk_bf16_f32 v82, v88, v89
	v_cvt_pk_bf16_f32 v83, v90, v91
	global_store_dwordx4 v[100:101], v[80:83], off
	s_nop 1
	v_cvt_pk_bf16_f32 v80, v84, v85
	v_cvt_pk_bf16_f32 v81, v86, v87
	v_cvt_pk_bf16_f32 v82, v96, v97
	v_cvt_pk_bf16_f32 v83, v104, v105
	global_store_dwordx4 v[100:101], v[80:83], off offset:256
	v_lshlrev_b64 v[84:85], 11, v[98:99]
	v_add_u32_e32 v82, 0x80, v138
	v_ashrrev_i32_e32 v83, 31, v82
	v_lshl_add_u64 v[84:85], v[136:137], 0, v[84:85]
	v_lshl_add_u64 v[86:87], v[82:83], 2, s[28:29]
	s_waitcnt vmcnt(10)
; __device__ __forceinline__ uint4 pk8(f32x4 a, f32x4 b) { return make_uint4(cvt_pk_bf16(a[0], a[1]), cvt_pk_bf16(a[2], a[3]), cvt_pk_bf16(b[0], b[1]), cvt_pk_bf16(b[2], b[3])); }
;     __device__ __forceinline__ void operator()(AccRef acc, const Unit& u, int wr, int wc, int fr, int fq) const {
;     ...
;             for (int m = 0; m < 4; ++m) {
;                 const int r = u.pm * 256 + ai * 128 + wr * 64 + m * 16 + fr;
;                 float s = 1.f;
;                 if (SCALE == 1) s = rs[r];
;                 if (SCALE == 2) s = rsqrtf(rs[r] * (1.f / D) + EPS);
;                 bf16_t* rowp = base + (size_t)r * ldc + cbase;
; #pragma unroll
;                 for (int bj = 0; bj < 2; ++bj) *(uint4*)(rowp + bj * 128) = pk8(acc[ai][bj][m][0] * s, acc[ai][bj][m][1] * s);
;             }
	v_pk_mul_f32 v[78:79], v[78:79], v[182:183] op_sel_hi:[1,0]
	v_pk_mul_f32 v[76:77], v[76:77], v[182:183] op_sel_hi:[1,0]
	v_pk_mul_f32 v[74:75], v[74:75], v[182:183] op_sel_hi:[1,0]
	v_pk_mul_f32 v[72:73], v[72:73], v[182:183] op_sel_hi:[1,0]
	v_pk_mul_f32 v[70:71], v[70:71], v[182:183] op_sel_hi:[1,0]
	v_pk_mul_f32 v[68:69], v[68:69], v[182:183] op_sel_hi:[1,0]
	v_pk_mul_f32 v[88:89], v[66:67], v[182:183] op_sel_hi:[1,0]
	v_pk_mul_f32 v[80:81], v[64:65], v[182:183] op_sel_hi:[1,0]
	v_cvt_pk_bf16_f32 v64, v76, v77
	v_cvt_pk_bf16_f32 v65, v78, v79
	v_cvt_pk_bf16_f32 v66, v72, v73
	v_cvt_pk_bf16_f32 v67, v74, v75
	global_store_dwordx4 v[84:85], v[64:67], off
	s_nop 1
	v_cvt_pk_bf16_f32 v64, v68, v69
	v_cvt_pk_bf16_f32 v65, v70, v71
	v_cvt_pk_bf16_f32 v66, v80, v81
	v_cvt_pk_bf16_f32 v67, v88, v89
	global_store_dwordx4 v[84:85], v[64:67], off offset:256
	v_lshlrev_b64 v[68:69], 11, v[82:83]
	v_add_u32_e32 v66, 0x90, v138
	v_ashrrev_i32_e32 v67, 31, v66
	v_lshl_add_u64 v[68:69], v[136:137], 0, v[68:69]
	v_lshl_add_u64 v[70:71], v[66:67], 2, s[28:29]
	s_waitcnt vmcnt(11)
	v_pk_mul_f32 v[62:63], v[62:63], v[184:185] op_sel_hi:[1,0]
	v_pk_mul_f32 v[60:61], v[60:61], v[184:185] op_sel_hi:[1,0]
	v_pk_mul_f32 v[58:59], v[58:59], v[184:185] op_sel_hi:[1,0]
	v_pk_mul_f32 v[56:57], v[56:57], v[184:185] op_sel_hi:[1,0]
	v_pk_mul_f32 v[54:55], v[54:55], v[184:185] op_sel_hi:[1,0]
	v_pk_mul_f32 v[52:53], v[52:53], v[184:185] op_sel_hi:[1,0]
	v_pk_mul_f32 v[72:73], v[50:51], v[184:185] op_sel_hi:[1,0]
	v_pk_mul_f32 v[64:65], v[48:49], v[184:185] op_sel_hi:[1,0]
	v_cvt_pk_bf16_f32 v48, v60, v61
	v_cvt_pk_bf16_f32 v49, v62, v63
	v_cvt_pk_bf16_f32 v50, v56, v57
	v_cvt_pk_bf16_f32 v51, v58, v59
	global_store_dwordx4 v[68:69], v[48:51], off
	s_nop 1
	v_cvt_pk_bf16_f32 v48, v52, v53
	v_cvt_pk_bf16_f32 v49, v54, v55
	v_cvt_pk_bf16_f32 v50, v64, v65
	v_cvt_pk_bf16_f32 v51, v72, v73
	global_store_dwordx4 v[68:69], v[48:51], off offset:256
	v_lshlrev_b64 v[52:53], 11, v[66:67]
	v_add_u32_e32 v50, 0xa0, v138
	v_ashrrev_i32_e32 v51, 31, v50
	v_lshl_add_u64 v[52:53], v[136:137], 0, v[52:53]
	v_lshl_add_u64 v[54:55], v[50:51], 2, s[28:29]
	s_waitcnt vmcnt(12)
	v_pk_mul_f32 v[46:47], v[46:47], v[186:187] op_sel_hi:[1,0]
	v_pk_mul_f32 v[44:45], v[44:45], v[186:187] op_sel_hi:[1,0]
	v_pk_mul_f32 v[42:43], v[42:43], v[186:187] op_sel_hi:[1,0]
	v_pk_mul_f32 v[40:41], v[40:41], v[186:187] op_sel_hi:[1,0]
	v_pk_mul_f32 v[38:39], v[38:39], v[186:187] op_sel_hi:[1,0]
	v_pk_mul_f32 v[36:37], v[36:37], v[186:187] op_sel_hi:[1,0]
	v_pk_mul_f32 v[56:57], v[34:35], v[186:187] op_sel_hi:[1,0]
	v_pk_mul_f32 v[48:49], v[32:33], v[186:187] op_sel_hi:[1,0]
	v_cvt_pk_bf16_f32 v32, v44, v45
	v_cvt_pk_bf16_f32 v33, v46, v47
	v_cvt_pk_bf16_f32 v34, v40, v41
	v_cvt_pk_bf16_f32 v35, v42, v43
	global_store_dwordx4 v[52:53], v[32:35], off
	s_nop 1
	v_cvt_pk_bf16_f32 v32, v36, v37
	v_cvt_pk_bf16_f32 v33, v38, v39
	v_cvt_pk_bf16_f32 v34, v48, v49
	v_cvt_pk_bf16_f32 v35, v56, v57
	global_store_dwordx4 v[52:53], v[32:35], off offset:256
	v_lshlrev_b64 v[36:37], 11, v[50:51]
	v_add_u32_e32 v34, 0xb0, v138
	v_ashrrev_i32_e32 v35, 31, v34
	v_lshl_add_u64 v[36:37], v[136:137], 0, v[36:37]
	v_lshl_add_u64 v[38:39], v[34:35], 2, s[28:29]
	s_waitcnt vmcnt(13)
	v_pk_mul_f32 v[30:31], v[30:31], v[188:189] op_sel_hi:[1,0]
	v_pk_mul_f32 v[28:29], v[28:29], v[188:189] op_sel_hi:[1,0]
	v_pk_mul_f32 v[26:27], v[26:27], v[188:189] op_sel_hi:[1,0]
	v_pk_mul_f32 v[24:25], v[24:25], v[188:189] op_sel_hi:[1,0]
	v_pk_mul_f32 v[22:23], v[22:23], v[188:189] op_sel_hi:[1,0]
	v_pk_mul_f32 v[20:21], v[20:21], v[188:189] op_sel_hi:[1,0]
	v_pk_mul_f32 v[40:41], v[18:19], v[188:189] op_sel_hi:[1,0]
	v_pk_mul_f32 v[32:33], v[16:17], v[188:189] op_sel_hi:[1,0]
	v_cvt_pk_bf16_f32 v16, v28, v29
	v_cvt_pk_bf16_f32 v17, v30, v31
	v_cvt_pk_bf16_f32 v18, v24, v25
	v_cvt_pk_bf16_f32 v19, v26, v27
	global_store_dwordx4 v[36:37], v[16:19], off
	s_nop 1
	v_cvt_pk_bf16_f32 v16, v20, v21
	v_cvt_pk_bf16_f32 v17, v22, v23
	v_cvt_pk_bf16_f32 v18, v32, v33
	v_cvt_pk_bf16_f32 v19, v40, v41
	global_store_dwordx4 v[36:37], v[16:19], off offset:256
	s_waitcnt vmcnt(14)
	v_pk_mul_f32 v[14:15], v[14:15], v[190:191] op_sel_hi:[1,0]
	v_lshlrev_b64 v[18:19], 11, v[34:35]
	v_lshl_add_u64 v[18:19], v[136:137], 0, v[18:19]
	v_pk_mul_f32 v[12:13], v[12:13], v[190:191] op_sel_hi:[1,0]
	v_pk_mul_f32 v[10:11], v[10:11], v[190:191] op_sel_hi:[1,0]
	v_pk_mul_f32 v[8:9], v[8:9], v[190:191] op_sel_hi:[1,0]
	v_pk_mul_f32 v[6:7], v[6:7], v[190:191] op_sel_hi:[1,0]
	v_pk_mul_f32 v[4:5], v[4:5], v[190:191] op_sel_hi:[1,0]
	v_pk_mul_f32 v[20:21], v[2:3], v[190:191] op_sel_hi:[1,0]
	v_pk_mul_f32 v[16:17], v[0:1], v[190:191] op_sel_hi:[1,0]
	v_cvt_pk_bf16_f32 v0, v12, v13
	v_cvt_pk_bf16_f32 v1, v14, v15
	v_cvt_pk_bf16_f32 v2, v8, v9
	v_cvt_pk_bf16_f32 v3, v10, v11
	global_store_dwordx4 v[18:19], v[0:3], off
	s_nop 1
	v_cvt_pk_bf16_f32 v0, v4, v5
	v_cvt_pk_bf16_f32 v1, v6, v7
	v_cvt_pk_bf16_f32 v2, v16, v17
	v_cvt_pk_bf16_f32 v3, v20, v21
	global_store_dwordx4 v[18:19], v[0:3], off offset:256
	s_cbranch_vccnz .LBB0_126

; __device__ void phase_na(const Params& P, unsigned char* smem) {
;     const int tid = threadIdx.x, lane = tid & 63, wid = tid >> 6, l15 = lane & 15, l4 = lane >> 4;
;     float* rpb_s = (float*)smem;
;     for (int i = tid; i < 8 * 15 * 31; i += 512) rpb_s[i] = P.in[I_RPB][i];
;     __syncthreads();
;     const bf16_t* Qp = (const bf16_t*)(P.ws + O_R2);
;     const bf16_t* Kp = (const bf16_t*)P.out;
;     const bf16_t* Vt = (const bf16_t*)((const unsigned char*)P.out + 128 * MiB);
;     const int h = blockIdx.x & 7, nbh = ((int)gridDim.x - h + 7) >> 3;
;     const float scale = 0.08838834764831845f;
;     for (int uu = ((int)blockIdx.x >> 3) * 8 + wid; uu < 2048; uu += nbh * 8) {
;         const int grow = uu >> 2, j = uu & 3;
;         int rows, r, tokbase;
;         if (grow < 256) { rows = 256; r = grow; tokbase = 0; } else { const int s = (grow - 256) >> 6; r = (grow - 256) & 63; rows = 64; tokbase = TP + s * 4096; }
;         const int rs = min(max(r - 4, 0), rows - 8);
;         const int q0 = j * 16, k0 = min(max(q0 - 8, 0), 32);
;         const size_t qtok = (size_t)tokbase + r * 64 + q0 + l15;
;         const bf16_t* qptr = Qp + qtok * 1024 + h * 128 + l4 * 8;
.LBB0_207:
	s_or_b64 exec, exec, s[0:1]
	s_and_b32 s0, s2, -8
	v_bfe_u32 v65, v144, 4, 2
	v_add_u32_e32 v84, s0, v146
	s_and_b32 s3, s2, 7
	v_lshlrev_b32_e32 v68, 3, v65
	s_movk_i32 s0, 0x800
	v_and_b32_e32 v64, 15, v144
	s_lshl_b32 s24, s3, 7
	v_lshlrev_b32_e32 v69, 2, v65
	v_cmp_gt_i32_e32 vcc, s0, v84
	v_lshlrev_b32_e32 v66, 1, v68
	s_waitcnt lgkmcnt(0)
	s_barrier
	s_and_saveexec_b64 s[4:5], vcc
	s_cbranch_execz .LBB0_338
	s_xor_b32 s8, s3, 7
	s_lshl_b32 s9, s24, 1
	v_lshlrev_b32_e32 v0, 1, v144
	s_add_u32 s0, s88, s9
	v_mov_b32_e32 v71, 0
	s_addc_u32 s1, s89, 0
	v_or_b32_sdwa v70, s24, v64 dst_sel:WORD_1 dst_unused:UNUSED_PAD src0_sel:DWORD src1_sel:DWORD
	v_mov_b32_e32 v67, v71
	v_and_b32_e32 v0, 24, v0
	v_and_or_b32 v85, v144, 3, v0
	v_lshl_add_u64 v[74:75], s[0:1], 0, v[66:67]
	v_bfe_i32 v0, v144, 0, 1
	v_and_b32_e32 v0, 0xfffff840, v0
	v_ashrrev_i32_e32 v1, 31, v0
	v_lshl_add_u64 v[74:75], v[0:1], 0, v[74:75]
	v_lshl_add_u64 v[0:1], s[88:89], 0, v[70:71]
	s_mov_b64 s[0:1], 0x8000000
	v_lshl_add_u64 v[76:77], v[0:1], 0, s[0:1]
	v_lshrrev_b32_e32 v0, 12, v70
	v_mov_b32_e32 v1, 0
	v_lshl_add_u64 v[0:1], s[88:89], 0, v[0:1]
	v_lshl_add_u64 v[76:77], v[0:1], 0, s[0:1]
	v_mbcnt_lo_u32_b32 v0, -1, 0
	v_mbcnt_hi_u32_b32 v0, -1, v0
	v_and_b32_e32 v2, 64, v0
	s_add_u32 s6, s40, s9
	v_xor_b32_e32 v1, 16, v0
	v_add_u32_e32 v2, 64, v2
	s_addc_u32 s7, s41, 0
	s_add_i32 s10, s94, s8
	v_cmp_lt_i32_e32 vcc, v1, v2
	s_add_u32 s8, s36, s9
	s_addc_u32 s9, s37, 0
	v_cndmask_b32_e32 v1, v0, v1, vcc
	v_lshlrev_b32_e32 v86, 2, v1
	v_xor_b32_e32 v1, 32, v0
	s_lshl_b32 s0, s2, 4
	v_cmp_lt_i32_e32 vcc, v1, v2
	s_and_b32 s0, s0, 0xffffff80
	s_mul_i32 s25, s3, 15
	v_lshlrev_b32_e32 v70, 1, v69
	v_cndmask_b32_e32 v0, v0, v1, vcc
	v_lshl_add_u32 v88, v146, 4, s0
	s_lshl_b32 s0, s10, 4
	v_lshl_add_u64 v[72:73], s[8:9], 0, v[66:67]
	v_bfe_i32 v254, v144, 0, 1
	v_and_b32_e32 v254, 0xfffff840, v254
	v_ashrrev_i32_e32 v255, 31, v254
	v_lshl_add_u64 v[72:73], v[254:255], 0, v[72:73]
	s_add_i32 s25, s25, 7
	s_and_b32 s26, s10, -8
	v_lshl_add_u64 v[78:79], s[6:7], 0, v[70:71]
	v_lshlrev_b32_e32 v87, 2, v0
	s_and_b32 s27, s0, 0xffffff80
	s_mov_b64 s[6:7], 0
	s_movk_i32 s42, 0x100
	v_mov_b32_e32 v89, 0xf8
	s_movk_i32 s43, 0x2000
	s_movk_i32 s44, 0x7c
	s_mov_b32 s45, 0xf149f2ca
	s_mov_b32 s46, 0x28000
	s_mov_b32 s47, 0x50000
	s_mov_b32 s48, 0x78000
	s_mov_b32 s49, 0xa0000
	s_mov_b32 s50, 0xc8000
	s_mov_b32 s51, 0xf0000
	s_mov_b32 s56, 0x118000
	s_movk_i32 s57, 0x7ff
	s_branch .LBB0_210

; __device__ __forceinline__ f32x4 mfma16(bf16x8 a, bf16x8 b, f32x4 c) { return __builtin_amdgcn_mfma_f32_16x16x32_bf16(a, b, c, 0, 0, 0); }
; __device__ void phase_na(const Params& P, unsigned char* smem) {
;     ...
;         const int rs = min(max(r - 4, 0), rows - 8);
;         const int q0 = j * 16, k0 = min(max(q0 - 8, 0), 32);
;         const size_t qtok = (size_t)tokbase + r * 64 + q0 + l15;
;         const bf16_t* qptr = Qp + qtok * 1024 + h * 128 + l4 * 8;
;         bf16x8 qf[4];
; #pragma unroll
;         for (int ks = 0; ks < 4; ++ks) qf[ks] = *(const bf16x8*)(qptr + ks * 32);
;         f32x4 st[8][2];
; #pragma unroll
;         for (int i = 0; i < 8; ++i)
; #pragma unroll
;             for (int a = 0; a < 2; ++a) {
;                 const size_t ktok = (size_t)tokbase + (rs + i) * 64 + k0 + (l15 >> 2) * 8 + a * 4 + (l15 & 3);
;                 const bf16_t* kptr = Kp + ktok * 1024 + h * 128 + l4 * 8;
;                 f32x4 c = {0.f, 0.f, 0.f, 0.f};
; #pragma unroll
;                 for (int ks = 0; ks < 4; ++ks) c = mfma16(*(const bf16x8*)(kptr + ks * 32), qf[ks], c);
;                 st[i][a] = c;
;             }
.LBB0_210:
	v_ashrrev_i32_e32 v0, 2, v84
	v_and_b32_e32 v1, 63, v0
	v_cmp_gt_i32_e32 vcc, s42, v0
	v_lshlrev_b32_e32 v2, 6, v0
	v_and_b32_e32 v2, 0xfffff000, v2
	v_cndmask_b32_e32 v136, v1, v0, vcc
	v_max_i32_e32 v0, 4, v136
	v_and_b32_e32 v137, 48, v88
	v_cndmask_b32_e64 v70, v2, 0, vcc
	v_add_u32_e32 v4, -4, v0
	v_sub_u32_e64 v5, v137, 8 clamp
	v_cndmask_b32_e32 v6, 56, v89, vcc
	v_min_u32_e32 v138, v4, v6
	v_min_u32_e32 v67, 32, v5
	v_or_b32_e32 v4, v70, v85
	v_add_u32_e32 v4, v4, v67
	v_mov_b32_e32 v5, v71
	v_lshlrev_b32_e32 v82, 6, v138
	v_mov_b32_e32 v83, v71
	v_lshlrev_b32_e32 v0, 6, v136
	v_lshl_add_u64 v[6:7], v[82:83], 0, v[4:5]
	v_ashrrev_i32_e32 v1, 31, v0
	v_lshlrev_b64 v[6:7], 11, v[6:7]
	v_lshl_add_u64 v[80:81], v[70:71], 0, v[0:1]
	v_lshl_add_u64 v[60:61], v[74:75], 0, v[6:7]
	v_or_b32_e32 v0, v80, v137
	global_load_dwordx4 v[6:9], v[60:61], off
	v_add_u32_e32 v14, 64, v82
	v_mov_b32_e32 v15, v71
	v_or_b32_e32 v80, v0, v64
	v_lshl_add_u64 v[14:15], v[14:15], 0, v[4:5]
	v_lshlrev_b64 v[0:1], 11, v[80:81]
	v_add_co_u32_e32 v62, vcc, s43, v60
	v_lshlrev_b64 v[14:15], 11, v[14:15]
	v_mov_b32_e32 v19, v71
	v_add_u32_e32 v18, 0x80, v82
	v_lshl_add_u64 v[58:59], v[72:73], 0, v[0:1]
	v_addc_co_u32_e32 v63, vcc, 0, v61, vcc
	v_lshl_add_u64 v[90:91], v[74:75], 0, v[14:15]
	v_lshl_add_u64 v[18:19], v[18:19], 0, v[4:5]
	global_load_dwordx4 v[0:3], v[58:59], off
	v_lshlrev_b64 v[18:19], 11, v[18:19]
	v_add_co_u32_e32 v98, vcc, s43, v90
	v_lshl_add_u64 v[96:97], v[74:75], 0, v[18:19]
	s_nop 0
	v_addc_co_u32_e32 v99, vcc, 0, v91, vcc
	v_add_co_u32_e32 v100, vcc, s43, v96
	global_load_dwordx4 v[10:13], v[62:63], off
	s_nop 0
	v_addc_co_u32_e32 v101, vcc, 0, v97, vcc
	global_load_dwordx4 v[14:17], v[90:91], off
	global_load_dwordx4 v[18:21], v[96:97], off
	global_load_dwordx4 v[22:25], v[98:99], off
	global_load_dwordx4 v[26:29], v[100:101], off
	global_load_dwordx4 v[30:33], v[60:61], off offset:128
	global_load_dwordx4 v[92:95], v[58:59], off offset:128
	global_load_dwordx4 v[34:37], v[62:63], off offset:128
	global_load_dwordx4 v[38:41], v[90:91], off offset:128
	global_load_dwordx4 v[42:45], v[96:97], off offset:128
	global_load_dwordx4 v[46:49], v[98:99], off offset:128
	global_load_dwordx4 v[50:53], v[100:101], off offset:128
	global_load_dwordx4 v[54:57], v[60:61], off offset:2048
	global_load_dwordx4 v[104:107], v[58:59], off offset:2048
	s_waitcnt vmcnt(14)
	v_mfma_f32_16x16x32_bf16 v[6:9], v[6:9], v[0:3], 0
	s_waitcnt vmcnt(7)
	v_mfma_f32_16x16x32_bf16 v[6:9], v[30:33], v[92:95], v[6:9]
	global_load_dwordx4 v[30:33], v[62:63], off offset:2048
	v_mfma_f32_16x16x32_bf16 v[10:13], v[10:13], v[0:3], 0
	s_waitcnt vmcnt(7)
	v_mfma_f32_16x16x32_bf16 v[10:13], v[34:37], v[92:95], v[10:13]
	global_load_dwordx4 v[34:37], v[90:91], off offset:2048
	v_mfma_f32_16x16x32_bf16 v[14:17], v[14:17], v[0:3], 0
	v_mfma_f32_16x16x32_bf16 v[18:21], v[18:21], v[0:3], 0
	v_mfma_f32_16x16x32_bf16 v[22:25], v[22:25], v[0:3], 0
	v_mfma_f32_16x16x32_bf16 v[26:29], v[26:29], v[0:3], 0
	s_waitcnt vmcnt(7)
	v_mfma_f32_16x16x32_bf16 v[14:17], v[38:41], v[92:95], v[14:17]
	global_load_dwordx4 v[38:41], v[96:97], off offset:2048
	s_waitcnt vmcnt(7)
	v_mfma_f32_16x16x32_bf16 v[18:21], v[42:45], v[92:95], v[18:21]
	global_load_dwordx4 v[42:45], v[98:99], off offset:2048
	s_waitcnt vmcnt(7)
	v_mfma_f32_16x16x32_bf16 v[22:25], v[46:49], v[92:95], v[22:25]
	global_load_dwordx4 v[46:49], v[100:101], off offset:2048
	s_waitcnt vmcnt(7)
	v_mfma_f32_16x16x32_bf16 v[26:29], v[50:53], v[92:95], v[26:29]
	global_load_dwordx4 v[50:53], v[60:61], off offset:2176
	global_load_dwordx4 v[108:111], v[58:59], off offset:2176
	s_waitcnt vmcnt(7)
	v_mfma_f32_16x16x32_bf16 v[6:9], v[54:57], v[104:107], v[6:9]
	global_load_dwordx4 v[54:57], v[62:63], off offset:2176
	s_waitcnt vmcnt(7)
	v_mfma_f32_16x16x32_bf16 v[10:13], v[30:33], v[104:107], v[10:13]
	global_load_dwordx4 v[30:33], v[90:91], off offset:2176
	s_waitcnt vmcnt(7)
	v_mfma_f32_16x16x32_bf16 v[14:17], v[34:37], v[104:107], v[14:17]
	global_load_dwordx4 v[34:37], v[96:97], off offset:2176
	s_waitcnt vmcnt(3)
	v_mfma_f32_16x16x32_bf16 v[60:63], v[50:53], v[108:111], v[6:9]
	s_nop 2
	v_mov_b32_e32 v7, v71
	v_add_u32_e32 v6, 0xc0, v82
	v_lshl_add_u64 v[6:7], v[6:7], 0, v[4:5]
	v_lshlrev_b64 v[6:7], 11, v[6:7]
	s_waitcnt vmcnt(2)
	v_mfma_f32_16x16x32_bf16 v[56:59], v[54:57], v[108:111], v[10:13]
	s_waitcnt vmcnt(1)
	v_mfma_f32_16x16x32_bf16 v[52:55], v[30:33], v[108:111], v[14:17]
	v_lshl_add_u64 v[30:31], v[74:75], 0, v[6:7]
	global_load_dwordx4 v[6:9], v[30:31], off
	global_load_dwordx4 v[10:13], v[30:31], off offset:128
	v_mfma_f32_16x16x32_bf16 v[18:21], v[38:41], v[104:107], v[18:21]
	global_load_dwordx4 v[38:41], v[98:99], off offset:2176
	global_load_dwordx4 v[14:17], v[30:31], off offset:2048
	v_mfma_f32_16x16x32_bf16 v[22:25], v[42:45], v[104:107], v[22:25]
	global_load_dwordx4 v[96:99], v[100:101], off offset:2176
	v_mfma_f32_16x16x32_bf16 v[26:29], v[46:49], v[104:107], v[26:29]
	s_waitcnt vmcnt(5)
	v_mfma_f32_16x16x32_bf16 v[44:47], v[34:37], v[108:111], v[18:21]
	s_nop 2
	global_load_dwordx4 v[18:21], v[30:31], off offset:2176
	s_waitcnt vmcnt(3)
	v_mfma_f32_16x16x32_bf16 v[48:51], v[38:41], v[108:111], v[22:25]
	s_nop 2
	v_add_co_u32_e32 v22, vcc, s43, v30
	v_mfma_f32_16x16x32_bf16 v[6:9], v[6:9], v[0:3], 0
	s_nop 0
	v_addc_co_u32_e32 v23, vcc, 0, v31, vcc
	v_mfma_f32_16x16x32_bf16 v[6:9], v[10:13], v[92:95], v[6:9]
	global_load_dwordx4 v[10:13], v[22:23], off
	s_waitcnt vmcnt(3)
	v_mfma_f32_16x16x32_bf16 v[6:9], v[14:17], v[104:107], v[6:9]
	global_load_dwordx4 v[14:17], v[22:23], off offset:128
	s_waitcnt vmcnt(2)
; __device__ __forceinline__ f32x4 mfma16(bf16x8 a, bf16x8 b, f32x4 c) { return __builtin_amdgcn_mfma_f32_16x16x32_bf16(a, b, c, 0, 0, 0); }
; __device__ void phase_na(const Params& P, unsigned char* smem) {
;     ...
;                 const size_t ktok = (size_t)tokbase + (rs + i) * 64 + k0 + (l15 >> 2) * 8 + a * 4 + (l15 & 3);
;                 const bf16_t* kptr = Kp + ktok * 1024 + h * 128 + l4 * 8;
;                 f32x4 c = {0.f, 0.f, 0.f, 0.f};
; #pragma unroll
;                 for (int ks = 0; ks < 4; ++ks) c = mfma16(*(const bf16x8*)(kptr + ks * 32), qf[ks], c);
;                 st[i][a] = c;
;             }
;         const int qc = q0 + l15, cs = min(max(qc - 8, 0), 48);
;         float mx = -1e30f;
; #pragma unroll
;         for (int i = 0; i < 8; ++i) {
;             const float* brow = rpb_s + (h * 15 + (rs + i - r + 7)) * 31;
; #pragma unroll
;             for (int a = 0; a < 2; ++a)
; #pragma unroll
;                 for (int jj = 0; jj < 4; ++jj) {
;                     const int kc = k0 + l4 * 8 + a * 4 + jj;
;                     const bool valid = (kc >= cs) && (kc < cs + 16);
;                     const int dc = min(max(kc - qc, -15), 15) + 15;
;                     const float s = valid ? st[i][a][jj] * scale + brow[dc] : -1e30f;
	v_mfma_f32_16x16x32_bf16 v[36:39], v[18:21], v[108:111], v[6:9]
	global_load_dwordx4 v[18:21], v[22:23], off offset:2176
	s_nop 3
	global_load_dwordx4 v[6:9], v[22:23], off offset:2048
	v_mfma_f32_16x16x32_bf16 v[40:43], v[96:99], v[108:111], v[26:29]
	s_waitcnt vmcnt(3)
	v_mfma_f32_16x16x32_bf16 v[10:13], v[10:13], v[0:3], 0
	s_waitcnt vmcnt(2)
	v_mfma_f32_16x16x32_bf16 v[10:13], v[14:17], v[92:95], v[10:13]
	v_add_u32_e32 v14, 0x100, v82
	v_mov_b32_e32 v15, v71
	v_lshl_add_u64 v[14:15], v[14:15], 0, v[4:5]
	v_lshlrev_b64 v[14:15], 11, v[14:15]
	v_lshl_add_u64 v[22:23], v[74:75], 0, v[14:15]
	global_load_dwordx4 v[14:17], v[22:23], off
	s_waitcnt vmcnt(1)
	v_mfma_f32_16x16x32_bf16 v[6:9], v[6:9], v[104:107], v[10:13]
	s_nop 2
	global_load_dwordx4 v[10:13], v[22:23], off offset:128
	v_mfma_f32_16x16x32_bf16 v[32:35], v[18:21], v[108:111], v[6:9]
	global_load_dwordx4 v[18:21], v[22:23], off offset:2176
	s_nop 1
	global_load_dwordx4 v[6:9], v[22:23], off offset:2048
	v_add_co_u32_e32 v22, vcc, s43, v22
	s_waitcnt vmcnt(3)
	v_mfma_f32_16x16x32_bf16 v[14:17], v[14:17], v[0:3], 0
	v_addc_co_u32_e32 v23, vcc, 0, v23, vcc
	s_waitcnt vmcnt(2)
	v_mfma_f32_16x16x32_bf16 v[10:13], v[10:13], v[92:95], v[14:17]
	s_nop 4
	global_load_dwordx4 v[14:17], v[22:23], off
	s_waitcnt vmcnt(1)
	v_mfma_f32_16x16x32_bf16 v[6:9], v[6:9], v[104:107], v[10:13]
	s_nop 2
	global_load_dwordx4 v[10:13], v[22:23], off offset:128
	v_mfma_f32_16x16x32_bf16 v[28:31], v[18:21], v[108:111], v[6:9]
	global_load_dwordx4 v[18:21], v[22:23], off offset:2176
	s_nop 1
	global_load_dwordx4 v[6:9], v[22:23], off offset:2048
	s_waitcnt vmcnt(3)
	v_mfma_f32_16x16x32_bf16 v[14:17], v[14:17], v[0:3], 0
	s_waitcnt vmcnt(2)
	v_mfma_f32_16x16x32_bf16 v[10:13], v[10:13], v[92:95], v[14:17]
	s_nop 5
	v_add_u32_e32 v14, 0x140, v82
	v_mov_b32_e32 v15, v71
	v_lshl_add_u64 v[14:15], v[14:15], 0, v[4:5]
	v_lshlrev_b64 v[14:15], 11, v[14:15]
	v_lshl_add_u64 v[22:23], v[74:75], 0, v[14:15]
	global_load_dwordx4 v[14:17], v[22:23], off
	s_waitcnt vmcnt(1)
	v_mfma_f32_16x16x32_bf16 v[6:9], v[6:9], v[104:107], v[10:13]
	v_add_co_u32_e32 v90, vcc, s43, v22
	s_nop 1
	global_load_dwordx4 v[10:13], v[22:23], off offset:128
	v_mfma_f32_16x16x32_bf16 v[24:27], v[18:21], v[108:111], v[6:9]
	global_load_dwordx4 v[18:21], v[22:23], off offset:2176
	v_addc_co_u32_e32 v91, vcc, 0, v23, vcc
	s_nop 0
	global_load_dwordx4 v[6:9], v[22:23], off offset:2048
	s_waitcnt vmcnt(3)
	v_mfma_f32_16x16x32_bf16 v[14:17], v[14:17], v[0:3], 0
	global_load_dwordx4 v[96:99], v[90:91], off offset:2176
	s_waitcnt vmcnt(3)
	v_mfma_f32_16x16x32_bf16 v[10:13], v[10:13], v[92:95], v[14:17]
	s_nop 4
	global_load_dwordx4 v[14:17], v[90:91], off
	s_waitcnt vmcnt(2)
	v_mfma_f32_16x16x32_bf16 v[6:9], v[6:9], v[104:107], v[10:13]
	s_nop 2
	global_load_dwordx4 v[10:13], v[90:91], off offset:128
	v_mfma_f32_16x16x32_bf16 v[20:23], v[18:21], v[108:111], v[6:9]
	s_nop 2
	global_load_dwordx4 v[6:9], v[90:91], off offset:2048
	s_waitcnt vmcnt(2)
	v_mfma_f32_16x16x32_bf16 v[14:17], v[14:17], v[0:3], 0
	s_waitcnt vmcnt(1)
	v_mfma_f32_16x16x32_bf16 v[10:13], v[10:13], v[92:95], v[14:17]
	s_nop 5
	v_add_u32_e32 v14, 0x180, v82
	v_mov_b32_e32 v15, v71
	v_lshl_add_u64 v[14:15], v[14:15], 0, v[4:5]
	v_lshlrev_b64 v[14:15], 11, v[14:15]
	v_lshl_add_u64 v[14:15], v[74:75], 0, v[14:15]
	global_load_dwordx4 v[100:103], v[14:15], off
	s_waitcnt vmcnt(1)
	v_mfma_f32_16x16x32_bf16 v[6:9], v[6:9], v[104:107], v[10:13]
	v_add_co_u32_e32 v90, vcc, s43, v14
	s_nop 1
	global_load_dwordx4 v[10:13], v[14:15], off offset:128
	v_mfma_f32_16x16x32_bf16 v[16:19], v[96:99], v[108:111], v[6:9]
	v_addc_co_u32_e32 v91, vcc, 0, v15, vcc
	global_load_dwordx4 v[112:115], v[90:91], off offset:128
	s_nop 0
	global_load_dwordx4 v[6:9], v[14:15], off offset:2048
	s_waitcnt vmcnt(3)
	v_mfma_f32_16x16x32_bf16 v[96:99], v[100:103], v[0:3], 0
	global_load_dwordx4 v[100:103], v[14:15], off offset:2176
	s_waitcnt vmcnt(3)
	v_mfma_f32_16x16x32_bf16 v[10:13], v[10:13], v[92:95], v[96:99]
	s_nop 4
	global_load_dwordx4 v[96:99], v[90:91], off
	s_waitcnt vmcnt(2)
	v_mfma_f32_16x16x32_bf16 v[6:9], v[6:9], v[104:107], v[10:13]
	s_nop 2
	v_add_u32_e32 v10, 0x1c0, v82
	v_mov_b32_e32 v11, v71
	v_lshl_add_u64 v[4:5], v[10:11], 0, v[4:5]
	v_lshlrev_b64 v[4:5], 11, v[4:5]
	v_lshl_add_u64 v[10:11], v[74:75], 0, v[4:5]
	s_waitcnt vmcnt(1)
	v_mfma_f32_16x16x32_bf16 v[12:15], v[100:103], v[108:111], v[6:9]
	s_nop 2
	global_load_dwordx4 v[6:9], v[90:91], off offset:2048
	global_load_dwordx4 v[100:103], v[90:91], off offset:2176
	global_load_dwordx4 v[116:119], v[10:11], off
	v_add_co_u32_e32 v90, vcc, s43, v10
	s_waitcnt vmcnt(3)
	v_mfma_f32_16x16x32_bf16 v[96:99], v[96:99], v[0:3], 0
	v_addc_co_u32_e32 v91, vcc, 0, v11, vcc
	v_mfma_f32_16x16x32_bf16 v[96:99], v[112:115], v[92:95], v[96:99]
	global_load_dwordx4 v[112:115], v[10:11], off offset:128
	global_load_dwordx4 v[120:123], v[10:11], off offset:2048
	global_load_dwordx4 v[124:127], v[10:11], off offset:2176
	global_load_dwordx4 v[128:131], v[90:91], off
	s_waitcnt vmcnt(6)
	v_mfma_f32_16x16x32_bf16 v[4:7], v[6:9], v[104:107], v[96:99]
	global_load_dwordx4 v[132:135], v[90:91], off offset:128
	s_nop 1
	v_or_b32_e32 v99, v137, v64
	v_max_i32_e32 v83, 8, v99
	s_waitcnt vmcnt(6)
	v_mfma_f32_16x16x32_bf16 v[8:11], v[100:103], v[108:111], v[4:7]
	v_add_u32_e32 v83, -8, v83
	v_min_u32_e32 v100, 48, v83
	v_sub_u32_e32 v83, s25, v136
	s_waitcnt vmcnt(5)
	v_mfma_f32_16x16x32_bf16 v[4:7], v[116:119], v[0:3], 0
	global_load_dwordx4 v[116:119], v[90:91], off offset:2048
	v_add_u32_e32 v83, v83, v138
	v_add_u32_e32 v101, v67, v68
	s_waitcnt vmcnt(5)
	v_mfma_f32_16x16x32_bf16 v[4:7], v[112:115], v[92:95], v[4:7]
	global_load_dwordx4 v[112:115], v[90:91], off offset:2176
	v_add_u32_e32 v102, 16, v100
	v_mul_lo_u32 v83, v83, s44
	s_waitcnt vmcnt(3)
	v_mfma_f32_16x16x32_bf16 v[0:3], v[128:131], v[0:3], 0
	v_cmp_ge_u32_e32 vcc, v101, v100
	v_cmp_lt_u32_e64 s[0:1], v101, v102
	v_sub_u32_e32 v90, v101, v99
	s_waitcnt vmcnt(2)
	v_mfma_f32_16x16x32_bf16 v[0:3], v[132:135], v[92:95], v[0:3]
	v_add_u32_e32 v91, 0, v83
	s_and_b64 s[8:9], vcc, s[0:1]
	v_mov_b32_e32 v83, 0xf149f2ca
	v_mfma_f32_16x16x32_bf16 v[4:7], v[120:123], v[104:107], v[4:7]
	v_med3_i32 v92, v90, -15, 15
	v_mov_b32_e32 v90, 0xf149f2ca
	s_waitcnt vmcnt(1)
	v_mfma_f32_16x16x32_bf16 v[0:3], v[116:119], v[104:107], v[0:3]
	v_mfma_f32_16x16x32_bf16 v[4:7], v[124:127], v[108:111], v[4:7]
	s_waitcnt vmcnt(0)
	v_mfma_f32_16x16x32_bf16 v[0:3], v[112:115], v[108:111], v[0:3]
	s_and_saveexec_b64 s[0:1], s[8:9]
	s_cbranch_execz .LBB0_212
	v_lshl_add_u32 v90, v92, 2, v91
	ds_read_b32 v90, v90 offset:60
	s_waitcnt lgkmcnt(0)
	v_fmac_f32_e32 v90, 0x3db504f3, v60

; #define PG8_STAGE(bufoff, gbase, voff) do { _Pragma("unroll") for (int _i = 0; _i < 2; ++_i) \
;         __builtin_amdgcn_global_load_lds((const unsigned*)((const char*)(gbase) + (voff)[_i]), (PG8_LAS unsigned*)(lds + (bufoff) + ldsw + _i * 8192), 16, 0, 0); } while (0)
; #define PG8_LDA(dst, b, h) do { _Pragma("unroll") for (int m = 0; m < 4; ++m) _Pragma("unroll") for (int k = 0; k < 2; ++k) dst[m][k] = *(const PG8_LAS bf16x8*)(lds + PG8_SA(b, h) + aoff + m * 2048 + k * 1024); } while (0)
; #define PG8_LDB(dst, b, h) do { _Pragma("unroll") for (int n = 0; n < 2; ++n) _Pragma("unroll") for (int k = 0; k < 2; ++k) dst[n][k] = *(const PG8_LAS bf16x8*)(lds + PG8_SB(b, h) + boff + n * 2048 + k * 1024); } while (0)
; #define PG8_WAIT_V(n) asm volatile("s_waitcnt vmcnt(" #n ")" ::: "memory")
; #define PG8_WAIT_L(n) asm volatile("s_waitcnt lgkmcnt(" #n ")" ::: "memory")
; #define PG8_BAR __builtin_amdgcn_s_barrier()
; #define PG8_SCHED __builtin_amdgcn_sched_barrier(0)
; template <class Epi, class Sched>
; __device__ __forceinline__ void gemm_phase(PG8_LAS unsigned char* lds, const Gemm g, const Sched& S, const Epi& E) {
;     ...
;             PG8_LDB(B0, 0, 0); PG8_SCHED; PG8_LDA(At, 0, 0); PG8_STAGE(PG8_SA(1, 1), a1 + hstep, voffA);
;             PG8_WAIT_L(8); PG8_BAR; PG8_WAIT_L(0); PG8_MMA(0, 0, At, B0); PG8_BAR; PG8_SCHED;
;             PG8_LDB(B1, 0, 1); PG8_STAGE(PG8_SB(0, 0), b2, voffB);
;             PG8_BAR; PG8_WAIT_L(0); PG8_MMA(0, 1, At, B1); PG8_BAR;
;             PG8_LDA(At, 0, 1); PG8_STAGE(PG8_SA(0, 0), a2, voffA);
;             PG8_BAR; PG8_WAIT_L(0); PG8_MMA(1, 0, At, B0); PG8_BAR; PG8_SCHED;
;             PG8_STAGE(PG8_SB(0, 1), b2 + hstep, voffB);
;             PG8_WAIT_V(6); PG8_BAR; PG8_MMA(1, 1, At, B1); PG8_BAR;
;             PG8_LDB(B0, 1, 0); PG8_SCHED; PG8_LDA(At, 1, 0); PG8_STAGE(PG8_SA(0, 1), a2 + hstep, voffA);
;             PG8_WAIT_L(8); PG8_BAR; PG8_WAIT_L(0); PG8_MMA(0, 0, At, B0); PG8_BAR; PG8_SCHED;
;             PG8_LDB(B1, 1, 1); PG8_STAGE(PG8_SB(1, 0), b3, voffB);
;             PG8_BAR; PG8_WAIT_L(0); PG8_MMA(0, 1, At, B1); PG8_BAR;
;             PG8_LDA(At, 1, 1); PG8_STAGE(PG8_SA(1, 0), a3, voffA);
;             PG8_BAR; PG8_WAIT_L(0); PG8_MMA(1, 0, At, B0); PG8_BAR; PG8_SCHED;
;             PG8_STAGE(PG8_SB(1, 1), b3 + hstep, voffB);
;             PG8_WAIT_V(6); PG8_BAR; PG8_MMA(1, 1, At, B1); PG8_BAR;
.LBB0_892:
	s_add_u32 s25, s18, s24
	s_addc_u32 s30, s19, 0
	s_add_u32 s28, s25, 0x100
	s_addc_u32 s29, s30, 0
	s_and_b64 s[26:27], s[22:23], exec
	s_cselect_b32 s29, s9, s29
	s_cselect_b32 s28, s63, s28
	s_add_u32 s24, s16, s24
	s_addc_u32 s26, s17, 0
	s_add_u32 s24, s24, 0x100
	s_addc_u32 s26, s26, 0
	s_and_b64 s[22:23], s[22:23], exec
	s_cselect_b32 s43, s7, s26
	s_cselect_b32 s42, s64, s24
	s_add_u32 s44, s25, 0x10080
	s_addc_u32 s45, s30, 0
	s_add_i32 s31, s60, s51
	s_add_i32 m0, s15, 0xc000
	s_add_i32 s30, s15, 0xe000
	s_add_i32 s73, s31, 0x2000
	s_add_u32 s26, s42, 0x10000
	s_addc_u32 s27, s43, 0
	s_add_i32 s70, s61, s51
	ds_read_b128 v[140:143], v149
	ds_read_b128 v[152:155], v149 offset:1024
	ds_read_b128 v[156:159], v149 offset:2048
	ds_read_b128 v[160:163], v149 offset:3072
	s_add_i32 s69, s70, 0x2000
	s_add_i32 s68, 0, 0x18000
	s_add_u32 s24, s28, 0x10000
	s_addc_u32 s25, s29, 0
	s_add_i32 s67, s68, s51
	s_add_i32 s66, 0, 0x1c000
	s_add_i32 s65, s67, 0x2000
	s_add_u32 s22, s42, 0x10080
	s_addc_u32 s23, s43, 0
	s_add_i32 s72, s66, s51
	s_add_i32 s71, s72, 0x2000
	v_lshl_add_u64 v[196:197], s[44:45], 0, v[128:129]
	ds_read_b128 v[164:167], v150
	ds_read_b128 v[168:171], v150 offset:1024
	ds_read_b128 v[172:175], v150 offset:2048
	ds_read_b128 v[176:179], v150 offset:3072
	ds_read_b128 v[180:183], v150 offset:4096
	ds_read_b128 v[184:187], v150 offset:5120
	ds_read_b128 v[188:191], v150 offset:6144
	ds_read_b128 v[192:195], v150 offset:7168
	global_load_lds_dwordx4 v[196:197], off
	v_lshl_add_u64 v[196:197], s[44:45], 0, v[132:133]
	s_mov_b32 m0, s30
	s_nop 0
	global_load_lds_dwordx4 v[196:197], off
	s_waitcnt lgkmcnt(8)
	s_barrier
	s_waitcnt lgkmcnt(0)
	s_waitcnt lgkmcnt(0)
	v_mfma_f32_16x16x32_bf16 v[124:127], v[140:143], v[164:167], v[124:127]
	v_mfma_f32_16x16x32_bf16 v[120:123], v[156:159], v[164:167], v[120:123]
	v_mfma_f32_16x16x32_bf16 v[116:119], v[140:143], v[172:175], v[116:119]
	v_mfma_f32_16x16x32_bf16 v[108:111], v[156:159], v[172:175], v[108:111]
	v_mfma_f32_16x16x32_bf16 v[100:103], v[140:143], v[180:183], v[100:103]
	v_mfma_f32_16x16x32_bf16 v[92:95], v[156:159], v[180:183], v[92:95]
	v_mfma_f32_16x16x32_bf16 v[84:87], v[140:143], v[188:191], v[84:87]
	v_mfma_f32_16x16x32_bf16 v[76:79], v[156:159], v[188:191], v[76:79]
	v_mfma_f32_16x16x32_bf16 v[124:127], v[152:155], v[168:171], v[124:127]
	v_mfma_f32_16x16x32_bf16 v[120:123], v[160:163], v[168:171], v[120:123]
	v_mfma_f32_16x16x32_bf16 v[116:119], v[152:155], v[176:179], v[116:119]
	v_mfma_f32_16x16x32_bf16 v[108:111], v[160:163], v[176:179], v[108:111]
	v_mfma_f32_16x16x32_bf16 v[100:103], v[152:155], v[184:187], v[100:103]
	v_mfma_f32_16x16x32_bf16 v[92:95], v[160:163], v[184:187], v[92:95]
	v_mfma_f32_16x16x32_bf16 v[84:87], v[152:155], v[192:195], v[84:87]
	v_mfma_f32_16x16x32_bf16 v[76:79], v[160:163], v[192:195], v[76:79]
	s_barrier
	s_mov_b32 m0, s31
	v_lshl_add_u64 v[212:213], s[42:43], 0, v[130:131]
	ds_read_b128 v[196:199], v151
	ds_read_b128 v[200:203], v151 offset:1024
	ds_read_b128 v[204:207], v151 offset:2048
	ds_read_b128 v[208:211], v151 offset:3072
	global_load_lds_dwordx4 v[212:213], off
	v_lshl_add_u64 v[214:215], s[42:43], 0, v[134:135]
	s_mov_b32 m0, s73
	s_nop 0
	global_load_lds_dwordx4 v[214:215], off
	s_barrier
	s_waitcnt lgkmcnt(0)
	s_waitcnt lgkmcnt(0)
	v_mfma_f32_16x16x32_bf16 v[112:115], v[196:199], v[164:167], v[112:115]
	v_mfma_f32_16x16x32_bf16 v[104:107], v[204:207], v[164:167], v[104:107]
	v_mfma_f32_16x16x32_bf16 v[96:99], v[196:199], v[172:175], v[96:99]
	v_mfma_f32_16x16x32_bf16 v[88:91], v[204:207], v[172:175], v[88:91]
	v_mfma_f32_16x16x32_bf16 v[80:83], v[196:199], v[180:183], v[80:83]
	v_mfma_f32_16x16x32_bf16 v[72:75], v[204:207], v[180:183], v[72:75]
	v_mfma_f32_16x16x32_bf16 v[68:71], v[196:199], v[188:191], v[68:71]
	v_mfma_f32_16x16x32_bf16 v[64:67], v[204:207], v[188:191], v[64:67]
	v_mfma_f32_16x16x32_bf16 v[112:115], v[200:203], v[168:171], v[112:115]
	v_mfma_f32_16x16x32_bf16 v[104:107], v[208:211], v[168:171], v[104:107]
	v_mfma_f32_16x16x32_bf16 v[96:99], v[200:203], v[176:179], v[96:99]
	v_mfma_f32_16x16x32_bf16 v[88:91], v[208:211], v[176:179], v[88:91]
	v_mfma_f32_16x16x32_bf16 v[80:83], v[200:203], v[184:187], v[80:83]
	v_mfma_f32_16x16x32_bf16 v[72:75], v[208:211], v[184:187], v[72:75]
	v_mfma_f32_16x16x32_bf16 v[68:71], v[200:203], v[192:195], v[68:71]
	v_mfma_f32_16x16x32_bf16 v[64:67], v[208:211], v[192:195], v[64:67]
	s_mov_b32 m0, s15
	v_lshl_add_u64 v[216:217], s[28:29], 0, v[128:129]
	s_barrier
	ds_read_b128 v[164:167], v150 offset:16384
	ds_read_b128 v[168:171], v150 offset:17408
	ds_read_b128 v[172:175], v150 offset:18432
	ds_read_b128 v[176:179], v150 offset:19456
	ds_read_b128 v[180:183], v150 offset:20480
	ds_read_b128 v[184:187], v150 offset:21504
	ds_read_b128 v[188:191], v150 offset:22528
	ds_read_b128 v[192:195], v150 offset:23552
	global_load_lds_dwordx4 v[216:217], off
	v_lshl_add_u64 v[218:219], s[28:29], 0, v[132:133]
	s_mov_b32 m0, s52
	s_nop 0
	global_load_lds_dwordx4 v[218:219], off
	s_barrier
	s_waitcnt lgkmcnt(0)
	s_waitcnt lgkmcnt(0)
	v_mfma_f32_16x16x32_bf16 v[60:63], v[140:143], v[164:167], v[60:63]
	v_mfma_f32_16x16x32_bf16 v[56:59], v[156:159], v[164:167], v[56:59]
	v_mfma_f32_16x16x32_bf16 v[52:55], v[140:143], v[172:175], v[52:55]
	v_mfma_f32_16x16x32_bf16 v[44:47], v[156:159], v[172:175], v[44:47]
	v_mfma_f32_16x16x32_bf16 v[36:39], v[140:143], v[180:183], v[36:39]
	v_mfma_f32_16x16x32_bf16 v[28:31], v[156:159], v[180:183], v[28:31]
	v_mfma_f32_16x16x32_bf16 v[20:23], v[140:143], v[188:191], v[20:23]
	v_mfma_f32_16x16x32_bf16 v[12:15], v[156:159], v[188:191], v[12:15]
	v_mfma_f32_16x16x32_bf16 v[60:63], v[152:155], v[168:171], v[60:63]
	v_mfma_f32_16x16x32_bf16 v[56:59], v[160:163], v[168:171], v[56:59]
	v_mfma_f32_16x16x32_bf16 v[52:55], v[152:155], v[176:179], v[52:55]
	v_mfma_f32_16x16x32_bf16 v[44:47], v[160:163], v[176:179], v[44:47]
	v_mfma_f32_16x16x32_bf16 v[36:39], v[152:155], v[184:187], v[36:39]
	v_mfma_f32_16x16x32_bf16 v[28:31], v[160:163], v[184:187], v[28:31]
	v_mfma_f32_16x16x32_bf16 v[20:23], v[152:155], v[192:195], v[20:23]
	v_mfma_f32_16x16x32_bf16 v[12:15], v[160:163], v[192:195], v[12:15]
	s_barrier
; #define PG8_STAGE(bufoff, gbase, voff) do { _Pragma("unroll") for (int _i = 0; _i < 2; ++_i) \
;         __builtin_amdgcn_global_load_lds((const unsigned*)((const char*)(gbase) + (voff)[_i]), (PG8_LAS unsigned*)(lds + (bufoff) + ldsw + _i * 8192), 16, 0, 0); } while (0)
; #define PG8_LDA(dst, b, h) do { _Pragma("unroll") for (int m = 0; m < 4; ++m) _Pragma("unroll") for (int k = 0; k < 2; ++k) dst[m][k] = *(const PG8_LAS bf16x8*)(lds + PG8_SA(b, h) + aoff + m * 2048 + k * 1024); } while (0)
; #define PG8_LDB(dst, b, h) do { _Pragma("unroll") for (int n = 0; n < 2; ++n) _Pragma("unroll") for (int k = 0; k < 2; ++k) dst[n][k] = *(const PG8_LAS bf16x8*)(lds + PG8_SB(b, h) + boff + n * 2048 + k * 1024); } while (0)
; #define PG8_WAIT_V(n) asm volatile("s_waitcnt vmcnt(" #n ")" ::: "memory")
; #define PG8_WAIT_L(n) asm volatile("s_waitcnt lgkmcnt(" #n ")" ::: "memory")
; #define PG8_BAR __builtin_amdgcn_s_barrier()
; #define PG8_SCHED __builtin_amdgcn_sched_barrier(0)
; template <class Epi, class Sched>
; __device__ __forceinline__ void gemm_phase(PG8_LAS unsigned char* lds, const Gemm g, const Sched& S, const Epi& E) {
;     ...
;             PG8_LDB(B0, 0, 0); PG8_SCHED; PG8_LDA(At, 0, 0); PG8_STAGE(PG8_SA(1, 1), a1 + hstep, voffA);
;             PG8_WAIT_L(8); PG8_BAR; PG8_WAIT_L(0); PG8_MMA(0, 0, At, B0); PG8_BAR; PG8_SCHED;
;             PG8_LDB(B1, 0, 1); PG8_STAGE(PG8_SB(0, 0), b2, voffB);
;             PG8_BAR; PG8_WAIT_L(0); PG8_MMA(0, 1, At, B1); PG8_BAR;
;             PG8_LDA(At, 0, 1); PG8_STAGE(PG8_SA(0, 0), a2, voffA);
;             PG8_BAR; PG8_WAIT_L(0); PG8_MMA(1, 0, At, B0); PG8_BAR; PG8_SCHED;
;             PG8_STAGE(PG8_SB(0, 1), b2 + hstep, voffB);
;             PG8_WAIT_V(6); PG8_BAR; PG8_MMA(1, 1, At, B1); PG8_BAR;
;             PG8_LDB(B0, 1, 0); PG8_SCHED; PG8_LDA(At, 1, 0); PG8_STAGE(PG8_SA(0, 1), a2 + hstep, voffA);
;             PG8_WAIT_L(8); PG8_BAR; PG8_WAIT_L(0); PG8_MMA(0, 0, At, B0); PG8_BAR; PG8_SCHED;
;             PG8_LDB(B1, 1, 1); PG8_STAGE(PG8_SB(1, 0), b3, voffB);
;             PG8_BAR; PG8_WAIT_L(0); PG8_MMA(0, 1, At, B1); PG8_BAR;
;             PG8_LDA(At, 1, 1); PG8_STAGE(PG8_SA(1, 0), a3, voffA);
;             PG8_BAR; PG8_WAIT_L(0); PG8_MMA(1, 0, At, B0); PG8_BAR; PG8_SCHED;
;             PG8_STAGE(PG8_SB(1, 1), b3 + hstep, voffB);
;             PG8_WAIT_V(6); PG8_BAR; PG8_MMA(1, 1, At, B1); PG8_BAR;
	s_mov_b32 m0, s70
	v_lshl_add_u64 v[140:141], s[26:27], 0, v[130:131]
	global_load_lds_dwordx4 v[140:141], off
	v_lshl_add_u64 v[140:141], s[26:27], 0, v[134:135]
	s_mov_b32 m0, s69
	s_nop 0
	global_load_lds_dwordx4 v[140:141], off
	s_waitcnt vmcnt(6)
	s_barrier
	v_mfma_f32_16x16x32_bf16 v[48:51], v[196:199], v[164:167], v[48:51]
	v_mfma_f32_16x16x32_bf16 v[40:43], v[204:207], v[164:167], v[40:43]
	v_mfma_f32_16x16x32_bf16 v[32:35], v[196:199], v[172:175], v[32:35]
	v_mfma_f32_16x16x32_bf16 v[24:27], v[204:207], v[172:175], v[24:27]
	v_mfma_f32_16x16x32_bf16 v[16:19], v[196:199], v[180:183], v[16:19]
	v_mfma_f32_16x16x32_bf16 v[8:11], v[204:207], v[180:183], v[8:11]
	v_mfma_f32_16x16x32_bf16 v[4:7], v[196:199], v[188:191], v[4:7]
	v_mfma_f32_16x16x32_bf16 v[0:3], v[204:207], v[188:191], v[0:3]
	v_mfma_f32_16x16x32_bf16 v[48:51], v[200:203], v[168:171], v[48:51]
	v_mfma_f32_16x16x32_bf16 v[40:43], v[208:211], v[168:171], v[40:43]
	v_mfma_f32_16x16x32_bf16 v[32:35], v[200:203], v[176:179], v[32:35]
	v_mfma_f32_16x16x32_bf16 v[24:27], v[208:211], v[176:179], v[24:27]
	v_mfma_f32_16x16x32_bf16 v[16:19], v[200:203], v[184:187], v[16:19]
	v_mfma_f32_16x16x32_bf16 v[8:11], v[208:211], v[184:187], v[8:11]
	v_mfma_f32_16x16x32_bf16 v[4:7], v[200:203], v[192:195], v[4:7]
	v_mfma_f32_16x16x32_bf16 v[0:3], v[208:211], v[192:195], v[0:3]
	v_add_u32_e32 v160, s68, v145
	s_barrier
	ds_read_b128 v[140:143], v160
	ds_read_b128 v[152:155], v160 offset:1024
	ds_read_b128 v[156:159], v160 offset:2048
	ds_read_b128 v[160:163], v160 offset:3072
	s_mov_b32 m0, s53
	v_lshl_add_u64 v[196:197], s[24:25], 0, v[128:129]
	ds_read_b128 v[164:167], v150 offset:32768
	ds_read_b128 v[168:171], v150 offset:33792
	ds_read_b128 v[172:175], v150 offset:34816
	ds_read_b128 v[176:179], v150 offset:35840
	ds_read_b128 v[180:183], v150 offset:36864
	ds_read_b128 v[184:187], v150 offset:37888
	ds_read_b128 v[188:191], v150 offset:38912
	ds_read_b128 v[192:195], v150 offset:39936
	global_load_lds_dwordx4 v[196:197], off
	v_lshl_add_u64 v[196:197], s[24:25], 0, v[132:133]
	s_mov_b32 m0, s54
	s_nop 0
	global_load_lds_dwordx4 v[196:197], off
	s_waitcnt lgkmcnt(8)
	s_barrier
	s_waitcnt lgkmcnt(0)
	s_waitcnt lgkmcnt(0)
	v_mfma_f32_16x16x32_bf16 v[124:127], v[140:143], v[164:167], v[124:127]
	v_mfma_f32_16x16x32_bf16 v[120:123], v[156:159], v[164:167], v[120:123]
	v_mfma_f32_16x16x32_bf16 v[116:119], v[140:143], v[172:175], v[116:119]
	v_mfma_f32_16x16x32_bf16 v[108:111], v[156:159], v[172:175], v[108:111]
	v_mfma_f32_16x16x32_bf16 v[100:103], v[140:143], v[180:183], v[100:103]
	v_mfma_f32_16x16x32_bf16 v[92:95], v[156:159], v[180:183], v[92:95]
	v_mfma_f32_16x16x32_bf16 v[84:87], v[140:143], v[188:191], v[84:87]
	v_mfma_f32_16x16x32_bf16 v[76:79], v[156:159], v[188:191], v[76:79]
	v_mfma_f32_16x16x32_bf16 v[124:127], v[152:155], v[168:171], v[124:127]
	v_mfma_f32_16x16x32_bf16 v[120:123], v[160:163], v[168:171], v[120:123]
	v_mfma_f32_16x16x32_bf16 v[116:119], v[152:155], v[176:179], v[116:119]
	v_mfma_f32_16x16x32_bf16 v[108:111], v[160:163], v[176:179], v[108:111]
	v_mfma_f32_16x16x32_bf16 v[100:103], v[152:155], v[184:187], v[100:103]
	v_mfma_f32_16x16x32_bf16 v[92:95], v[160:163], v[184:187], v[92:95]
	v_mfma_f32_16x16x32_bf16 v[84:87], v[152:155], v[192:195], v[84:87]
	v_mfma_f32_16x16x32_bf16 v[76:79], v[160:163], v[192:195], v[76:79]
	s_barrier
	s_mov_b32 m0, s67
	v_add_u32_e32 v208, s66, v145
	v_lshl_add_u64 v[212:213], v[212:213], 0, s[0:1]
	ds_read_b128 v[196:199], v208
	ds_read_b128 v[200:203], v208 offset:1024
	ds_read_b128 v[204:207], v208 offset:2048
	ds_read_b128 v[208:211], v208 offset:3072
	global_load_lds_dwordx4 v[212:213], off
	v_lshl_add_u64 v[212:213], v[214:215], 0, s[0:1]
	s_mov_b32 m0, s65
	s_nop 0
	global_load_lds_dwordx4 v[212:213], off
	s_barrier
	s_waitcnt lgkmcnt(0)
	s_waitcnt lgkmcnt(0)
	v_mfma_f32_16x16x32_bf16 v[112:115], v[196:199], v[164:167], v[112:115]
	v_mfma_f32_16x16x32_bf16 v[104:107], v[204:207], v[164:167], v[104:107]
	v_mfma_f32_16x16x32_bf16 v[96:99], v[196:199], v[172:175], v[96:99]
	v_mfma_f32_16x16x32_bf16 v[88:91], v[204:207], v[172:175], v[88:91]
	v_mfma_f32_16x16x32_bf16 v[80:83], v[196:199], v[180:183], v[80:83]
	v_mfma_f32_16x16x32_bf16 v[72:75], v[204:207], v[180:183], v[72:75]
	v_mfma_f32_16x16x32_bf16 v[68:71], v[196:199], v[188:191], v[68:71]
	v_mfma_f32_16x16x32_bf16 v[64:67], v[204:207], v[188:191], v[64:67]
	v_mfma_f32_16x16x32_bf16 v[112:115], v[200:203], v[168:171], v[112:115]
	v_mfma_f32_16x16x32_bf16 v[104:107], v[208:211], v[168:171], v[104:107]
	v_mfma_f32_16x16x32_bf16 v[96:99], v[200:203], v[176:179], v[96:99]
	v_mfma_f32_16x16x32_bf16 v[88:91], v[208:211], v[176:179], v[88:91]
	v_mfma_f32_16x16x32_bf16 v[80:83], v[200:203], v[184:187], v[80:83]
	v_mfma_f32_16x16x32_bf16 v[72:75], v[208:211], v[184:187], v[72:75]
	v_mfma_f32_16x16x32_bf16 v[68:71], v[200:203], v[192:195], v[68:71]
	v_mfma_f32_16x16x32_bf16 v[64:67], v[208:211], v[192:195], v[64:67]
	s_mov_b32 m0, s56
	v_lshl_add_u64 v[212:213], v[216:217], 0, s[0:1]
	s_barrier
	ds_read_b128 v[164:167], v150 offset:49152
	ds_read_b128 v[168:171], v150 offset:50176
	ds_read_b128 v[172:175], v150 offset:51200
	ds_read_b128 v[176:179], v150 offset:52224
	ds_read_b128 v[180:183], v150 offset:53248
	ds_read_b128 v[184:187], v150 offset:54272
	ds_read_b128 v[188:191], v150 offset:55296
	ds_read_b128 v[192:195], v150 offset:56320
	global_load_lds_dwordx4 v[212:213], off
	v_lshl_add_u64 v[212:213], v[218:219], 0, s[0:1]
	s_mov_b32 m0, s57
	s_nop 0
	global_load_lds_dwordx4 v[212:213], off
	s_barrier
; #define PG8_STAGE(bufoff, gbase, voff) do { _Pragma("unroll") for (int _i = 0; _i < 2; ++_i) \
;         __builtin_amdgcn_global_load_lds((const unsigned*)((const char*)(gbase) + (voff)[_i]), (PG8_LAS unsigned*)(lds + (bufoff) + ldsw + _i * 8192), 16, 0, 0); } while (0)
; #define PG8_LDA(dst, b, h) do { _Pragma("unroll") for (int m = 0; m < 4; ++m) _Pragma("unroll") for (int k = 0; k < 2; ++k) dst[m][k] = *(const PG8_LAS bf16x8*)(lds + PG8_SA(b, h) + aoff + m * 2048 + k * 1024); } while (0)
; #define PG8_LDB(dst, b, h) do { _Pragma("unroll") for (int n = 0; n < 2; ++n) _Pragma("unroll") for (int k = 0; k < 2; ++k) dst[n][k] = *(const PG8_LAS bf16x8*)(lds + PG8_SB(b, h) + boff + n * 2048 + k * 1024); } while (0)
; #define PG8_WAIT_V(n) asm volatile("s_waitcnt vmcnt(" #n ")" ::: "memory")
; #define PG8_WAIT_L(n) asm volatile("s_waitcnt lgkmcnt(" #n ")" ::: "memory")
; #define PG8_BAR __builtin_amdgcn_s_barrier()
; #define PG8_SCHED __builtin_amdgcn_sched_barrier(0)
; template <class Epi, class Sched>
; __device__ __forceinline__ void gemm_phase(PG8_LAS unsigned char* lds, const Gemm g, const Sched& S, const Epi& E) {
;     ...
;             PG8_LDB(B0, 0, 0); PG8_SCHED; PG8_LDA(At, 0, 0); PG8_STAGE(PG8_SA(1, 1), a1 + hstep, voffA);
;             PG8_WAIT_L(8); PG8_BAR; PG8_WAIT_L(0); PG8_MMA(0, 0, At, B0); PG8_BAR; PG8_SCHED;
;             PG8_LDB(B1, 0, 1); PG8_STAGE(PG8_SB(0, 0), b2, voffB);
;             PG8_BAR; PG8_WAIT_L(0); PG8_MMA(0, 1, At, B1); PG8_BAR;
;             PG8_LDA(At, 0, 1); PG8_STAGE(PG8_SA(0, 0), a2, voffA);
;             PG8_BAR; PG8_WAIT_L(0); PG8_MMA(1, 0, At, B0); PG8_BAR; PG8_SCHED;
;             PG8_STAGE(PG8_SB(0, 1), b2 + hstep, voffB);
;             PG8_WAIT_V(6); PG8_BAR; PG8_MMA(1, 1, At, B1); PG8_BAR;
;             PG8_LDB(B0, 1, 0); PG8_SCHED; PG8_LDA(At, 1, 0); PG8_STAGE(PG8_SA(0, 1), a2 + hstep, voffA);
;             PG8_WAIT_L(8); PG8_BAR; PG8_WAIT_L(0); PG8_MMA(0, 0, At, B0); PG8_BAR; PG8_SCHED;
;             PG8_LDB(B1, 1, 1); PG8_STAGE(PG8_SB(1, 0), b3, voffB);
;             PG8_BAR; PG8_WAIT_L(0); PG8_MMA(0, 1, At, B1); PG8_BAR;
;             PG8_LDA(At, 1, 1); PG8_STAGE(PG8_SA(1, 0), a3, voffA);
;             PG8_BAR; PG8_WAIT_L(0); PG8_MMA(1, 0, At, B0); PG8_BAR; PG8_SCHED;
;             PG8_STAGE(PG8_SB(1, 1), b3 + hstep, voffB);
;             PG8_WAIT_V(6); PG8_BAR; PG8_MMA(1, 1, At, B1); PG8_BAR;
	s_waitcnt lgkmcnt(0)
	s_waitcnt lgkmcnt(0)
	v_mfma_f32_16x16x32_bf16 v[60:63], v[140:143], v[164:167], v[60:63]
	v_mfma_f32_16x16x32_bf16 v[56:59], v[156:159], v[164:167], v[56:59]
	v_mfma_f32_16x16x32_bf16 v[52:55], v[140:143], v[172:175], v[52:55]
	v_mfma_f32_16x16x32_bf16 v[44:47], v[156:159], v[172:175], v[44:47]
	v_mfma_f32_16x16x32_bf16 v[36:39], v[140:143], v[180:183], v[36:39]
	v_mfma_f32_16x16x32_bf16 v[28:31], v[156:159], v[180:183], v[28:31]
	v_mfma_f32_16x16x32_bf16 v[20:23], v[140:143], v[188:191], v[20:23]
	v_mfma_f32_16x16x32_bf16 v[12:15], v[156:159], v[188:191], v[12:15]
	v_mfma_f32_16x16x32_bf16 v[60:63], v[152:155], v[168:171], v[60:63]
	v_mfma_f32_16x16x32_bf16 v[56:59], v[160:163], v[168:171], v[56:59]
	v_mfma_f32_16x16x32_bf16 v[52:55], v[152:155], v[176:179], v[52:55]
	v_mfma_f32_16x16x32_bf16 v[44:47], v[160:163], v[176:179], v[44:47]
	v_mfma_f32_16x16x32_bf16 v[36:39], v[152:155], v[184:187], v[36:39]
	v_mfma_f32_16x16x32_bf16 v[28:31], v[160:163], v[184:187], v[28:31]
	v_mfma_f32_16x16x32_bf16 v[20:23], v[152:155], v[192:195], v[20:23]
	v_mfma_f32_16x16x32_bf16 v[12:15], v[160:163], v[192:195], v[12:15]
	s_barrier
	s_mov_b32 m0, s72
	v_lshl_add_u64 v[140:141], s[22:23], 0, v[130:131]
	global_load_lds_dwordx4 v[140:141], off
	v_lshl_add_u64 v[140:141], s[22:23], 0, v[134:135]
	s_mov_b32 m0, s71
	s_nop 0
	global_load_lds_dwordx4 v[140:141], off
	s_waitcnt vmcnt(6)
	s_barrier
	v_mfma_f32_16x16x32_bf16 v[48:51], v[196:199], v[164:167], v[48:51]
	v_mfma_f32_16x16x32_bf16 v[40:43], v[204:207], v[164:167], v[40:43]
	v_mfma_f32_16x16x32_bf16 v[32:35], v[196:199], v[172:175], v[32:35]
	v_mfma_f32_16x16x32_bf16 v[24:27], v[204:207], v[172:175], v[24:27]
	v_mfma_f32_16x16x32_bf16 v[16:19], v[196:199], v[180:183], v[16:19]
	v_mfma_f32_16x16x32_bf16 v[8:11], v[204:207], v[180:183], v[8:11]
	v_mfma_f32_16x16x32_bf16 v[4:7], v[196:199], v[188:191], v[4:7]
	v_mfma_f32_16x16x32_bf16 v[0:3], v[204:207], v[188:191], v[0:3]
	v_mfma_f32_16x16x32_bf16 v[48:51], v[200:203], v[168:171], v[48:51]
	v_mfma_f32_16x16x32_bf16 v[40:43], v[208:211], v[168:171], v[40:43]
	v_mfma_f32_16x16x32_bf16 v[32:35], v[200:203], v[176:179], v[32:35]
	v_mfma_f32_16x16x32_bf16 v[24:27], v[208:211], v[176:179], v[24:27]
	v_mfma_f32_16x16x32_bf16 v[16:19], v[200:203], v[184:187], v[16:19]
	v_mfma_f32_16x16x32_bf16 v[8:11], v[208:211], v[184:187], v[8:11]
	v_mfma_f32_16x16x32_bf16 v[4:7], v[200:203], v[192:195], v[4:7]
	v_mfma_f32_16x16x32_bf16 v[0:3], v[208:211], v[192:195], v[0:3]
	s_movk_i32 s24, 0x100
	s_andn2_b64 vcc, exec, s[20:21]
	s_mov_b64 s[22:23], -1
	s_mov_b64 s[20:21], 0
	s_barrier
	s_cbranch_vccz .LBB0_892
; __device__ __forceinline__ uint4 pk8(f32x4 a, f32x4 b) { return make_uint4(cvt_pk_bf16(a[0], a[1]), cvt_pk_bf16(a[2], a[3]), cvt_pk_bf16(b[0], b[1]), cvt_pk_bf16(b[2], b[3])); }
;     __device__ __forceinline__ void operator()(AccRef acc, const Unit& u, int wr, int wc, int fr, int fq) const {
;         const int pi = u.pn / tpp; bf16_t* base = pi == 0 ? pl[0] : (pi == 1 ? pl[1] : (pi == 2 ? pl[2] : pl[3]));
;         const int cbase = (u.pn - pi * tpp) * 256 + wc * 32 + 8 * fq;
; #pragma unroll
;         for (int ai = 0; ai < 2; ++ai)
; #pragma unroll
;             for (int m = 0; m < 4; ++m) {
;                 const int r = u.pm * 256 + ai * 128 + wr * 64 + m * 16 + fr;
;                 float s = 1.f;
;                 if (SCALE == 1) s = rs[r];
;                 if (SCALE == 2) s = rsqrtf(rs[r] * (1.f / D) + EPS);
;                 bf16_t* rowp = base + (size_t)r * ldc + cbase;
; #pragma unroll
;                 for (int bj = 0; bj < 2; ++bj) *(uint4*)(rowp + bj * 128) = pk8(acc[ai][bj][m][0] * s, acc[ai][bj][m][1] * s);
;             }
	s_mul_hi_i32 s7, s62, 0x10624dd3
	s_lshr_b32 s9, s7, 31
	s_lshr_b32 s7, s7, 6
	s_add_i32 s7, s7, s9
	s_mulk_i32 s7, 0x3e8
	s_sub_i32 s7, s62, s7
	v_lshl_or_b32 v140, s7, 8, v147
	v_lshl_add_u32 v142, s14, 8, v148
	v_ashrrev_i32_e32 v141, 31, v140
	v_ashrrev_i32_e32 v143, 31, v142
	v_lshl_add_u64 v[140:141], v[140:141], 1, s[36:37]
	v_bfe_i32 v250, v144, 0, 1
	v_and_b32_e32 v250, 0xfffff040, v250
	v_bfe_u32 v251, v146, 1, 1
	v_mul_u32_u24_e32 v251, 0xf80, v251
	v_add_u32_e32 v250, v250, v251
	v_and_b32_e32 v251, 1, v146
	v_lshl_add_u32 v250, v251, 6, v250
	v_ashrrev_i32_e32 v251, 31, v250
	v_lshl_add_u64 v[140:141], v[250:251], 0, v[140:141]
	v_lshlrev_b64 v[152:153], 12, v[142:143]
	v_lshl_add_u64 v[152:153], v[140:141], 0, v[152:153]
	v_cvt_pk_bf16_f32 v124, v124, v125
	v_cvt_pk_bf16_f32 v125, v126, v127
	v_cvt_pk_bf16_f32 v126, v120, v121
	v_cvt_pk_bf16_f32 v127, v122, v123
	global_store_dwordx4 v[152:153], v[124:127], off
	v_cvt_pk_bf16_f32 v112, v112, v113
	v_cvt_pk_bf16_f32 v113, v114, v115
	v_cvt_pk_bf16_f32 v114, v104, v105
	v_or_b32_e32 v104, 16, v142
	v_ashrrev_i32_e32 v105, 31, v104
	v_lshlrev_b64 v[104:105], 12, v[104:105]
	v_cvt_pk_bf16_f32 v115, v106, v107
	global_store_dwordx4 v[152:153], v[112:115], off offset:256
	s_and_b64 vcc, exec, s[4:5]
	s_mov_b32 s62, s6
	v_lshl_add_u64 v[112:113], v[140:141], 0, v[104:105]
	v_cvt_pk_bf16_f32 v104, v116, v117
	v_cvt_pk_bf16_f32 v105, v118, v119
	v_cvt_pk_bf16_f32 v106, v108, v109
	v_cvt_pk_bf16_f32 v107, v110, v111
	global_store_dwordx4 v[112:113], v[104:107], off
	v_cvt_pk_bf16_f32 v96, v96, v97
	v_cvt_pk_bf16_f32 v97, v98, v99
	v_cvt_pk_bf16_f32 v98, v88, v89
	v_or_b32_e32 v88, 32, v142
	v_ashrrev_i32_e32 v89, 31, v88
	v_lshlrev_b64 v[88:89], 12, v[88:89]
	v_cvt_pk_bf16_f32 v99, v90, v91
	global_store_dwordx4 v[112:113], v[96:99], off offset:256
	s_mov_b32 s14, s8
	s_mov_b64 s[16:17], s[12:13]
	v_lshl_add_u64 v[96:97], v[140:141], 0, v[88:89]
	v_cvt_pk_bf16_f32 v88, v100, v101
	v_cvt_pk_bf16_f32 v89, v102, v103
	v_cvt_pk_bf16_f32 v90, v92, v93
	v_cvt_pk_bf16_f32 v91, v94, v95
	global_store_dwordx4 v[96:97], v[88:91], off
	v_cvt_pk_bf16_f32 v80, v80, v81
	v_cvt_pk_bf16_f32 v81, v82, v83
	v_cvt_pk_bf16_f32 v82, v72, v73
	v_or_b32_e32 v72, 48, v142
	v_ashrrev_i32_e32 v73, 31, v72
	v_lshlrev_b64 v[72:73], 12, v[72:73]
	v_cvt_pk_bf16_f32 v83, v74, v75
	global_store_dwordx4 v[96:97], v[80:83], off offset:256
	s_mov_b64 s[18:19], s[10:11]
	s_nop 0
	v_lshl_add_u64 v[80:81], v[140:141], 0, v[72:73]
	v_cvt_pk_bf16_f32 v72, v84, v85
	v_cvt_pk_bf16_f32 v73, v86, v87
	v_cvt_pk_bf16_f32 v74, v76, v77
	v_cvt_pk_bf16_f32 v75, v78, v79
	global_store_dwordx4 v[80:81], v[72:75], off
	v_cvt_pk_bf16_f32 v68, v68, v69
	v_cvt_pk_bf16_f32 v69, v70, v71
	v_cvt_pk_bf16_f32 v70, v64, v65
	v_add_u32_e32 v64, 0x80, v142
	v_ashrrev_i32_e32 v65, 31, v64
	v_lshlrev_b64 v[64:65], 12, v[64:65]
	v_lshl_add_u64 v[64:65], v[140:141], 0, v[64:65]
	v_cvt_pk_bf16_f32 v71, v66, v67
	global_store_dwordx4 v[80:81], v[68:71], off offset:256
	v_cvt_pk_bf16_f32 v60, v60, v61
	v_cvt_pk_bf16_f32 v61, v62, v63
	v_cvt_pk_bf16_f32 v62, v56, v57
	v_cvt_pk_bf16_f32 v63, v58, v59
	global_store_dwordx4 v[64:65], v[60:63], off
	v_cvt_pk_bf16_f32 v48, v48, v49
	v_cvt_pk_bf16_f32 v49, v50, v51
	v_cvt_pk_bf16_f32 v50, v40, v41
	v_add_u32_e32 v40, 0x90, v142
	v_ashrrev_i32_e32 v41, 31, v40
	v_lshlrev_b64 v[40:41], 12, v[40:41]
	v_cvt_pk_bf16_f32 v51, v42, v43
	global_store_dwordx4 v[64:65], v[48:51], off offset:256
	s_nop 1
	v_lshl_add_u64 v[48:49], v[140:141], 0, v[40:41]
	v_cvt_pk_bf16_f32 v40, v52, v53
	v_cvt_pk_bf16_f32 v41, v54, v55
	v_cvt_pk_bf16_f32 v42, v44, v45
	v_cvt_pk_bf16_f32 v43, v46, v47
	global_store_dwordx4 v[48:49], v[40:43], off
	v_cvt_pk_bf16_f32 v32, v32, v33
	v_cvt_pk_bf16_f32 v33, v34, v35
	v_cvt_pk_bf16_f32 v34, v24, v25
	v_add_u32_e32 v24, 0xa0, v142
	v_ashrrev_i32_e32 v25, 31, v24
	v_lshlrev_b64 v[24:25], 12, v[24:25]
	v_cvt_pk_bf16_f32 v35, v26, v27
	global_store_dwordx4 v[48:49], v[32:35], off offset:256
	s_nop 1
	v_lshl_add_u64 v[32:33], v[140:141], 0, v[24:25]
	v_cvt_pk_bf16_f32 v24, v36, v37
	v_cvt_pk_bf16_f32 v25, v38, v39
	v_cvt_pk_bf16_f32 v26, v28, v29
	v_cvt_pk_bf16_f32 v27, v30, v31
	global_store_dwordx4 v[32:33], v[24:27], off
	v_cvt_pk_bf16_f32 v16, v16, v17
	v_cvt_pk_bf16_f32 v17, v18, v19
	v_cvt_pk_bf16_f32 v18, v8, v9
	v_add_u32_e32 v8, 0xb0, v142
	v_ashrrev_i32_e32 v9, 31, v8
	v_lshlrev_b64 v[8:9], 12, v[8:9]
	v_cvt_pk_bf16_f32 v19, v10, v11
	global_store_dwordx4 v[32:33], v[16:19], off offset:256
	s_nop 1
	v_lshl_add_u64 v[16:17], v[140:141], 0, v[8:9]
	v_cvt_pk_bf16_f32 v8, v20, v21
	v_cvt_pk_bf16_f32 v9, v22, v23
	v_cvt_pk_bf16_f32 v10, v12, v13
	v_cvt_pk_bf16_f32 v11, v14, v15
	global_store_dwordx4 v[16:17], v[8:11], off
	v_cvt_pk_bf16_f32 v4, v4, v5
	v_cvt_pk_bf16_f32 v5, v6, v7
	v_cvt_pk_bf16_f32 v6, v0, v1
	v_cvt_pk_bf16_f32 v7, v2, v3
	global_store_dwordx4 v[16:17], v[4:7], off offset:256
	s_cbranch_vccz .LBB0_885
	s_waitcnt vmcnt(0)
	s_cmpk_gt_u32 s3, 0xff
	s_cbranch_scc1 .LBB0_896
	s_barrier

; #define PG8_STAGE(bufoff, gbase, voff) do { _Pragma("unroll") for (int _i = 0; _i < 2; ++_i) \
;         __builtin_amdgcn_global_load_lds((const unsigned*)((const char*)(gbase) + (voff)[_i]), (PG8_LAS unsigned*)(lds + (bufoff) + ldsw + _i * 8192), 16, 0, 0); } while (0)
; #define PG8_LDA(dst, b, h) do { _Pragma("unroll") for (int m = 0; m < 4; ++m) _Pragma("unroll") for (int k = 0; k < 2; ++k) dst[m][k] = *(const PG8_LAS bf16x8*)(lds + PG8_SA(b, h) + aoff + m * 2048 + k * 1024); } while (0)
; #define PG8_LDB(dst, b, h) do { _Pragma("unroll") for (int n = 0; n < 2; ++n) _Pragma("unroll") for (int k = 0; k < 2; ++k) dst[n][k] = *(const PG8_LAS bf16x8*)(lds + PG8_SB(b, h) + boff + n * 2048 + k * 1024); } while (0)
; #define PG8_WAIT_V(n) asm volatile("s_waitcnt vmcnt(" #n ")" ::: "memory")
; #define PG8_WAIT_L(n) asm volatile("s_waitcnt lgkmcnt(" #n ")" ::: "memory")
; #define PG8_BAR __builtin_amdgcn_s_barrier()
; #define PG8_SCHED __builtin_amdgcn_sched_barrier(0)
; template <class Epi, class Sched>
; __device__ __forceinline__ void gemm_phase(PG8_LAS unsigned char* lds, const Gemm g, const Sched& S, const Epi& E) {
;     ...
;             PG8_LDB(B0, 0, 0); PG8_SCHED; PG8_LDA(At, 0, 0); PG8_STAGE(PG8_SA(1, 1), a1 + hstep, voffA);
;             PG8_WAIT_L(8); PG8_BAR; PG8_WAIT_L(0); PG8_MMA(0, 0, At, B0); PG8_BAR; PG8_SCHED;
;             PG8_LDB(B1, 0, 1); PG8_STAGE(PG8_SB(0, 0), b2, voffB);
;             PG8_BAR; PG8_WAIT_L(0); PG8_MMA(0, 1, At, B1); PG8_BAR;
;             PG8_LDA(At, 0, 1); PG8_STAGE(PG8_SA(0, 0), a2, voffA);
;             PG8_BAR; PG8_WAIT_L(0); PG8_MMA(1, 0, At, B0); PG8_BAR; PG8_SCHED;
;             PG8_STAGE(PG8_SB(0, 1), b2 + hstep, voffB);
;             PG8_WAIT_V(6); PG8_BAR; PG8_MMA(1, 1, At, B1); PG8_BAR;
;             PG8_LDB(B0, 1, 0); PG8_SCHED; PG8_LDA(At, 1, 0); PG8_STAGE(PG8_SA(0, 1), a2 + hstep, voffA);
;             PG8_WAIT_L(8); PG8_BAR; PG8_WAIT_L(0); PG8_MMA(0, 0, At, B0); PG8_BAR; PG8_SCHED;
;             PG8_LDB(B1, 1, 1); PG8_STAGE(PG8_SB(1, 0), b3, voffB);
;             PG8_BAR; PG8_WAIT_L(0); PG8_MMA(0, 1, At, B1); PG8_BAR;
;             PG8_LDA(At, 1, 1); PG8_STAGE(PG8_SA(1, 0), a3, voffA);
;             PG8_BAR; PG8_WAIT_L(0); PG8_MMA(1, 0, At, B0); PG8_BAR; PG8_SCHED;
;             PG8_STAGE(PG8_SB(1, 1), b3 + hstep, voffB);
;             PG8_WAIT_V(6); PG8_BAR; PG8_MMA(1, 1, At, B1); PG8_BAR;
.LBB0_1059:
	ds_read_b128 v[148:151], v153
	ds_read_b128 v[156:159], v153 offset:1024
	ds_read_b128 v[160:163], v153 offset:2048
	ds_read_b128 v[164:167], v153 offset:3072
	s_add_u32 s18, s16, 0xfff80080
	s_addc_u32 s19, s17, -1
	s_cmp_eq_u32 s53, 28
	s_cselect_b32 s21, s9, s19
	s_cselect_b32 s20, s49, s18
	s_cselect_b32 s19, s7, s52
	s_cselect_b32 s18, s50, s51
	v_lshl_add_u64 v[200:201], s[16:17], 0, v[136:137]
	s_add_i32 m0, s15, 0xc000
	ds_read_b128 v[168:171], v154
	ds_read_b128 v[172:175], v154 offset:1024
	ds_read_b128 v[176:179], v154 offset:2048
	ds_read_b128 v[180:183], v154 offset:3072
	ds_read_b128 v[184:187], v154 offset:4096
	ds_read_b128 v[188:191], v154 offset:5120
	ds_read_b128 v[192:195], v154 offset:6144
	ds_read_b128 v[196:199], v154 offset:7168
	global_load_lds_dwordx4 v[200:201], off
	v_lshl_add_u64 v[200:201], s[16:17], 0, v[138:139]
	s_add_i32 m0, s15, 0xe000
	s_nop 0
	global_load_lds_dwordx4 v[200:201], off
	s_waitcnt lgkmcnt(8)
	s_barrier
	s_waitcnt lgkmcnt(0)
	s_waitcnt lgkmcnt(0)
	v_mfma_f32_16x16x32_bf16 v[124:127], v[148:151], v[168:171], v[124:127]
	v_mfma_f32_16x16x32_bf16 v[120:123], v[160:163], v[168:171], v[120:123]
	v_mfma_f32_16x16x32_bf16 v[108:111], v[148:151], v[176:179], v[108:111]
	v_mfma_f32_16x16x32_bf16 v[104:107], v[160:163], v[176:179], v[104:107]
	v_mfma_f32_16x16x32_bf16 v[92:95], v[148:151], v[184:187], v[92:95]
	v_mfma_f32_16x16x32_bf16 v[88:91], v[160:163], v[184:187], v[88:91]
	v_mfma_f32_16x16x32_bf16 v[76:79], v[148:151], v[192:195], v[76:79]
	v_mfma_f32_16x16x32_bf16 v[72:75], v[160:163], v[192:195], v[72:75]
	v_mfma_f32_16x16x32_bf16 v[124:127], v[156:159], v[172:175], v[124:127]
	v_mfma_f32_16x16x32_bf16 v[120:123], v[164:167], v[172:175], v[120:123]
	v_mfma_f32_16x16x32_bf16 v[108:111], v[156:159], v[180:183], v[108:111]
	v_mfma_f32_16x16x32_bf16 v[104:107], v[164:167], v[180:183], v[104:107]
	v_mfma_f32_16x16x32_bf16 v[92:95], v[156:159], v[188:191], v[92:95]
	v_mfma_f32_16x16x32_bf16 v[88:91], v[164:167], v[188:191], v[88:91]
	v_mfma_f32_16x16x32_bf16 v[76:79], v[156:159], v[196:199], v[76:79]
	v_mfma_f32_16x16x32_bf16 v[72:75], v[164:167], v[196:199], v[72:75]
	s_barrier
	s_add_i32 s30, s46, s25
	v_lshl_add_u64 v[216:217], s[18:19], 0, v[130:131]
	s_mov_b32 m0, s30
	ds_read_b128 v[200:203], v155
	ds_read_b128 v[204:207], v155 offset:1024
	ds_read_b128 v[208:211], v155 offset:2048
	ds_read_b128 v[212:215], v155 offset:3072
	global_load_lds_dwordx4 v[216:217], off
	v_lshl_add_u64 v[218:219], s[18:19], 0, v[134:135]
	s_add_i32 m0, s30, 0x2000
	s_nop 0
	global_load_lds_dwordx4 v[218:219], off
	s_barrier
	s_waitcnt lgkmcnt(0)
	s_waitcnt lgkmcnt(0)
	v_mfma_f32_16x16x32_bf16 v[116:119], v[200:203], v[168:171], v[116:119]
	v_mfma_f32_16x16x32_bf16 v[112:115], v[208:211], v[168:171], v[112:115]
	v_mfma_f32_16x16x32_bf16 v[100:103], v[200:203], v[176:179], v[100:103]
	v_mfma_f32_16x16x32_bf16 v[96:99], v[208:211], v[176:179], v[96:99]
	v_mfma_f32_16x16x32_bf16 v[84:87], v[200:203], v[184:187], v[84:87]
	v_mfma_f32_16x16x32_bf16 v[80:83], v[208:211], v[184:187], v[80:83]
	v_mfma_f32_16x16x32_bf16 v[68:71], v[200:203], v[192:195], v[68:71]
	v_mfma_f32_16x16x32_bf16 v[64:67], v[208:211], v[192:195], v[64:67]
	v_mfma_f32_16x16x32_bf16 v[116:119], v[204:207], v[172:175], v[116:119]
	v_mfma_f32_16x16x32_bf16 v[112:115], v[212:215], v[172:175], v[112:115]
	v_mfma_f32_16x16x32_bf16 v[100:103], v[204:207], v[180:183], v[100:103]
	v_mfma_f32_16x16x32_bf16 v[96:99], v[212:215], v[180:183], v[96:99]
	v_mfma_f32_16x16x32_bf16 v[84:87], v[204:207], v[188:191], v[84:87]
	v_mfma_f32_16x16x32_bf16 v[80:83], v[212:215], v[188:191], v[80:83]
	v_mfma_f32_16x16x32_bf16 v[68:71], v[204:207], v[196:199], v[68:71]
	v_mfma_f32_16x16x32_bf16 v[64:67], v[212:215], v[196:199], v[64:67]
	s_mov_b32 m0, s15
	v_lshl_add_u64 v[220:221], s[20:21], 0, v[128:129]
	s_barrier
	ds_read_b128 v[168:171], v154 offset:16384
	ds_read_b128 v[172:175], v154 offset:17408
	ds_read_b128 v[176:179], v154 offset:18432
	ds_read_b128 v[180:183], v154 offset:19456
	ds_read_b128 v[184:187], v154 offset:20480
	ds_read_b128 v[188:191], v154 offset:21504
	ds_read_b128 v[192:195], v154 offset:22528
	ds_read_b128 v[196:199], v154 offset:23552
	global_load_lds_dwordx4 v[220:221], off
	v_lshl_add_u64 v[222:223], s[20:21], 0, v[132:133]
	s_mov_b32 m0, s28
	s_nop 0
	global_load_lds_dwordx4 v[222:223], off
	s_barrier
	s_waitcnt lgkmcnt(0)
	s_waitcnt lgkmcnt(0)
	v_mfma_f32_16x16x32_bf16 v[60:63], v[148:151], v[168:171], v[60:63]
	v_mfma_f32_16x16x32_bf16 v[56:59], v[160:163], v[168:171], v[56:59]
	v_mfma_f32_16x16x32_bf16 v[44:47], v[148:151], v[176:179], v[44:47]
	v_mfma_f32_16x16x32_bf16 v[40:43], v[160:163], v[176:179], v[40:43]
	v_mfma_f32_16x16x32_bf16 v[28:31], v[148:151], v[184:187], v[28:31]
	v_mfma_f32_16x16x32_bf16 v[24:27], v[160:163], v[184:187], v[24:27]
	v_mfma_f32_16x16x32_bf16 v[12:15], v[148:151], v[192:195], v[12:15]
	v_mfma_f32_16x16x32_bf16 v[8:11], v[160:163], v[192:195], v[8:11]
	v_mfma_f32_16x16x32_bf16 v[60:63], v[156:159], v[172:175], v[60:63]
	v_mfma_f32_16x16x32_bf16 v[56:59], v[164:167], v[172:175], v[56:59]
	v_mfma_f32_16x16x32_bf16 v[44:47], v[156:159], v[180:183], v[44:47]
	v_mfma_f32_16x16x32_bf16 v[40:43], v[164:167], v[180:183], v[40:43]
	v_mfma_f32_16x16x32_bf16 v[28:31], v[156:159], v[188:191], v[28:31]
	v_mfma_f32_16x16x32_bf16 v[24:27], v[164:167], v[188:191], v[24:27]
	v_mfma_f32_16x16x32_bf16 v[12:15], v[156:159], v[196:199], v[12:15]
	v_mfma_f32_16x16x32_bf16 v[8:11], v[164:167], v[196:199], v[8:11]
	s_barrier
; #define PG8_STAGE(bufoff, gbase, voff) do { _Pragma("unroll") for (int _i = 0; _i < 2; ++_i) \
;         __builtin_amdgcn_global_load_lds((const unsigned*)((const char*)(gbase) + (voff)[_i]), (PG8_LAS unsigned*)(lds + (bufoff) + ldsw + _i * 8192), 16, 0, 0); } while (0)
; #define PG8_LDA(dst, b, h) do { _Pragma("unroll") for (int m = 0; m < 4; ++m) _Pragma("unroll") for (int k = 0; k < 2; ++k) dst[m][k] = *(const PG8_LAS bf16x8*)(lds + PG8_SA(b, h) + aoff + m * 2048 + k * 1024); } while (0)
; #define PG8_LDB(dst, b, h) do { _Pragma("unroll") for (int n = 0; n < 2; ++n) _Pragma("unroll") for (int k = 0; k < 2; ++k) dst[n][k] = *(const PG8_LAS bf16x8*)(lds + PG8_SB(b, h) + boff + n * 2048 + k * 1024); } while (0)
; #define PG8_WAIT_V(n) asm volatile("s_waitcnt vmcnt(" #n ")" ::: "memory")
; #define PG8_WAIT_L(n) asm volatile("s_waitcnt lgkmcnt(" #n ")" ::: "memory")
; #define PG8_BAR __builtin_amdgcn_s_barrier()
; #define PG8_SCHED __builtin_amdgcn_sched_barrier(0)
; template <class Epi, class Sched>
; __device__ __forceinline__ void gemm_phase(PG8_LAS unsigned char* lds, const Gemm g, const Sched& S, const Epi& E) {
;     ...
;             PG8_LDB(B0, 0, 0); PG8_SCHED; PG8_LDA(At, 0, 0); PG8_STAGE(PG8_SA(1, 1), a1 + hstep, voffA);
;             PG8_WAIT_L(8); PG8_BAR; PG8_WAIT_L(0); PG8_MMA(0, 0, At, B0); PG8_BAR; PG8_SCHED;
;             PG8_LDB(B1, 0, 1); PG8_STAGE(PG8_SB(0, 0), b2, voffB);
;             PG8_BAR; PG8_WAIT_L(0); PG8_MMA(0, 1, At, B1); PG8_BAR;
;             PG8_LDA(At, 0, 1); PG8_STAGE(PG8_SA(0, 0), a2, voffA);
;             PG8_BAR; PG8_WAIT_L(0); PG8_MMA(1, 0, At, B0); PG8_BAR; PG8_SCHED;
;             PG8_STAGE(PG8_SB(0, 1), b2 + hstep, voffB);
;             PG8_WAIT_V(6); PG8_BAR; PG8_MMA(1, 1, At, B1); PG8_BAR;
;             PG8_LDB(B0, 1, 0); PG8_SCHED; PG8_LDA(At, 1, 0); PG8_STAGE(PG8_SA(0, 1), a2 + hstep, voffA);
;             PG8_WAIT_L(8); PG8_BAR; PG8_WAIT_L(0); PG8_MMA(0, 0, At, B0); PG8_BAR; PG8_SCHED;
;             PG8_LDB(B1, 1, 1); PG8_STAGE(PG8_SB(1, 0), b3, voffB);
;             PG8_BAR; PG8_WAIT_L(0); PG8_MMA(0, 1, At, B1); PG8_BAR;
;             PG8_LDA(At, 1, 1); PG8_STAGE(PG8_SA(1, 0), a3, voffA);
;             PG8_BAR; PG8_WAIT_L(0); PG8_MMA(1, 0, At, B0); PG8_BAR; PG8_SCHED;
;             PG8_STAGE(PG8_SB(1, 1), b3 + hstep, voffB);
;             PG8_WAIT_V(6); PG8_BAR; PG8_MMA(1, 1, At, B1); PG8_BAR;
	s_add_u32 s30, s18, 0x80000
	s_addc_u32 s31, s19, 0
	s_add_i32 s54, s47, s25
	v_lshl_add_u64 v[148:149], s[30:31], 0, v[130:131]
	s_mov_b32 m0, s54
	s_nop 0
	global_load_lds_dwordx4 v[148:149], off
	v_lshl_add_u64 v[148:149], s[30:31], 0, v[134:135]
	s_add_i32 m0, s54, 0x2000
	s_nop 0
	global_load_lds_dwordx4 v[148:149], off
	s_waitcnt vmcnt(6)
	s_barrier
	v_mfma_f32_16x16x32_bf16 v[52:55], v[200:203], v[168:171], v[52:55]
	v_mfma_f32_16x16x32_bf16 v[48:51], v[208:211], v[168:171], v[48:51]
	v_mfma_f32_16x16x32_bf16 v[36:39], v[200:203], v[176:179], v[36:39]
	v_mfma_f32_16x16x32_bf16 v[32:35], v[208:211], v[176:179], v[32:35]
	v_mfma_f32_16x16x32_bf16 v[20:23], v[200:203], v[184:187], v[20:23]
	v_mfma_f32_16x16x32_bf16 v[16:19], v[208:211], v[184:187], v[16:19]
	v_mfma_f32_16x16x32_bf16 v[4:7], v[200:203], v[192:195], v[4:7]
	v_mfma_f32_16x16x32_bf16 v[0:3], v[208:211], v[192:195], v[0:3]
	v_mfma_f32_16x16x32_bf16 v[52:55], v[204:207], v[172:175], v[52:55]
	v_mfma_f32_16x16x32_bf16 v[48:51], v[212:215], v[172:175], v[48:51]
	v_mfma_f32_16x16x32_bf16 v[36:39], v[204:207], v[180:183], v[36:39]
	v_mfma_f32_16x16x32_bf16 v[32:35], v[212:215], v[180:183], v[32:35]
	v_mfma_f32_16x16x32_bf16 v[20:23], v[204:207], v[188:191], v[20:23]
	v_mfma_f32_16x16x32_bf16 v[16:19], v[212:215], v[188:191], v[16:19]
	v_mfma_f32_16x16x32_bf16 v[4:7], v[204:207], v[196:199], v[4:7]
	v_mfma_f32_16x16x32_bf16 v[0:3], v[212:215], v[196:199], v[0:3]
	s_add_i32 s30, 0, 0x18000
	v_add_u32_e32 v164, s30, v147
	s_barrier
	ds_read_b128 v[148:151], v164
	ds_read_b128 v[156:159], v164 offset:1024
	ds_read_b128 v[160:163], v164 offset:2048
	ds_read_b128 v[164:167], v164 offset:3072
	s_add_u32 s20, s20, 0x80000
	s_addc_u32 s21, s21, 0
	s_mov_b32 m0, s29
	v_lshl_add_u64 v[200:201], s[20:21], 0, v[128:129]
	ds_read_b128 v[168:171], v154 offset:32768
	ds_read_b128 v[172:175], v154 offset:33792
	ds_read_b128 v[176:179], v154 offset:34816
	ds_read_b128 v[180:183], v154 offset:35840
	ds_read_b128 v[184:187], v154 offset:36864
	ds_read_b128 v[188:191], v154 offset:37888
	ds_read_b128 v[192:195], v154 offset:38912
	ds_read_b128 v[196:199], v154 offset:39936
	global_load_lds_dwordx4 v[200:201], off
	v_lshl_add_u64 v[200:201], s[20:21], 0, v[132:133]
	s_mov_b32 m0, s38
	s_nop 0
	global_load_lds_dwordx4 v[200:201], off
	s_waitcnt lgkmcnt(8)
	s_barrier
	s_waitcnt lgkmcnt(0)
	s_waitcnt lgkmcnt(0)
	v_mfma_f32_16x16x32_bf16 v[124:127], v[148:151], v[168:171], v[124:127]
	v_mfma_f32_16x16x32_bf16 v[120:123], v[160:163], v[168:171], v[120:123]
	v_mfma_f32_16x16x32_bf16 v[108:111], v[148:151], v[176:179], v[108:111]
	v_mfma_f32_16x16x32_bf16 v[104:107], v[160:163], v[176:179], v[104:107]
	v_mfma_f32_16x16x32_bf16 v[92:95], v[148:151], v[184:187], v[92:95]
	v_mfma_f32_16x16x32_bf16 v[88:91], v[160:163], v[184:187], v[88:91]
	v_mfma_f32_16x16x32_bf16 v[76:79], v[148:151], v[192:195], v[76:79]
	v_mfma_f32_16x16x32_bf16 v[72:75], v[160:163], v[192:195], v[72:75]
	v_mfma_f32_16x16x32_bf16 v[124:127], v[156:159], v[172:175], v[124:127]
	v_mfma_f32_16x16x32_bf16 v[120:123], v[164:167], v[172:175], v[120:123]
	v_mfma_f32_16x16x32_bf16 v[108:111], v[156:159], v[180:183], v[108:111]
	v_mfma_f32_16x16x32_bf16 v[104:107], v[164:167], v[180:183], v[104:107]
	v_mfma_f32_16x16x32_bf16 v[92:95], v[156:159], v[188:191], v[92:95]
	v_mfma_f32_16x16x32_bf16 v[88:91], v[164:167], v[188:191], v[88:91]
	v_mfma_f32_16x16x32_bf16 v[76:79], v[156:159], v[196:199], v[76:79]
	v_mfma_f32_16x16x32_bf16 v[72:75], v[164:167], v[196:199], v[72:75]
	s_barrier
	s_add_i32 s20, 0, 0x1c000
	s_add_i32 s21, s30, s25
	v_add_u32_e32 v212, s20, v147
	v_lshl_add_u64 v[216:217], v[216:217], 0, s[0:1]
	s_mov_b32 m0, s21
	ds_read_b128 v[200:203], v212
	ds_read_b128 v[204:207], v212 offset:1024
	ds_read_b128 v[208:211], v212 offset:2048
	ds_read_b128 v[212:215], v212 offset:3072
	global_load_lds_dwordx4 v[216:217], off
	v_lshl_add_u64 v[216:217], v[218:219], 0, s[0:1]
	s_add_i32 m0, s21, 0x2000
	s_nop 0
	global_load_lds_dwordx4 v[216:217], off
	s_barrier
	s_waitcnt lgkmcnt(0)
	s_waitcnt lgkmcnt(0)
	v_mfma_f32_16x16x32_bf16 v[116:119], v[200:203], v[168:171], v[116:119]
	v_mfma_f32_16x16x32_bf16 v[112:115], v[208:211], v[168:171], v[112:115]
	v_mfma_f32_16x16x32_bf16 v[100:103], v[200:203], v[176:179], v[100:103]
	v_mfma_f32_16x16x32_bf16 v[96:99], v[208:211], v[176:179], v[96:99]
	v_mfma_f32_16x16x32_bf16 v[84:87], v[200:203], v[184:187], v[84:87]
	v_mfma_f32_16x16x32_bf16 v[80:83], v[208:211], v[184:187], v[80:83]
	v_mfma_f32_16x16x32_bf16 v[68:71], v[200:203], v[192:195], v[68:71]
	v_mfma_f32_16x16x32_bf16 v[64:67], v[208:211], v[192:195], v[64:67]
	v_mfma_f32_16x16x32_bf16 v[116:119], v[204:207], v[172:175], v[116:119]
	v_mfma_f32_16x16x32_bf16 v[112:115], v[212:215], v[172:175], v[112:115]
	v_mfma_f32_16x16x32_bf16 v[100:103], v[204:207], v[180:183], v[100:103]
	v_mfma_f32_16x16x32_bf16 v[96:99], v[212:215], v[180:183], v[96:99]
	v_mfma_f32_16x16x32_bf16 v[84:87], v[204:207], v[188:191], v[84:87]
	v_mfma_f32_16x16x32_bf16 v[80:83], v[212:215], v[188:191], v[80:83]
	v_mfma_f32_16x16x32_bf16 v[68:71], v[204:207], v[196:199], v[68:71]
	v_mfma_f32_16x16x32_bf16 v[64:67], v[212:215], v[196:199], v[64:67]
	s_mov_b32 m0, s42
	v_lshl_add_u64 v[216:217], v[220:221], 0, s[0:1]
	s_barrier
	ds_read_b128 v[168:171], v154 offset:49152
	ds_read_b128 v[172:175], v154 offset:50176
	ds_read_b128 v[176:179], v154 offset:51200
	ds_read_b128 v[180:183], v154 offset:52224
	ds_read_b128 v[184:187], v154 offset:53248
	ds_read_b128 v[188:191], v154 offset:54272
	ds_read_b128 v[192:195], v154 offset:55296
	ds_read_b128 v[196:199], v154 offset:56320
	global_load_lds_dwordx4 v[216:217], off
	v_lshl_add_u64 v[216:217], v[222:223], 0, s[0:1]
	s_mov_b32 m0, s43
	s_nop 0
	global_load_lds_dwordx4 v[216:217], off
	s_barrier
; #define PG8_STAGE(bufoff, gbase, voff) do { _Pragma("unroll") for (int _i = 0; _i < 2; ++_i) \
;         __builtin_amdgcn_global_load_lds((const unsigned*)((const char*)(gbase) + (voff)[_i]), (PG8_LAS unsigned*)(lds + (bufoff) + ldsw + _i * 8192), 16, 0, 0); } while (0)
; #define PG8_LDA(dst, b, h) do { _Pragma("unroll") for (int m = 0; m < 4; ++m) _Pragma("unroll") for (int k = 0; k < 2; ++k) dst[m][k] = *(const PG8_LAS bf16x8*)(lds + PG8_SA(b, h) + aoff + m * 2048 + k * 1024); } while (0)
; #define PG8_MMA(ai, bj, At, Bt) do { __builtin_amdgcn_s_setprio(1); _Pragma("unroll") for (int m = 0; m < 4; ++m) _Pragma("unroll") for (int n = 0; n < 2; ++n) _Pragma("unroll") for (int k = 0; k < 2; ++k) \
;         acc[ai][bj][m][n] = __builtin_amdgcn_mfma_f32_16x16x32_bf16(Bt[n][k], At[m][k], acc[ai][bj][m][n], 0, 0, 0); __builtin_amdgcn_s_setprio(0); } while (0)
; #define PG8_WAIT_V(n) asm volatile("s_waitcnt vmcnt(" #n ")" ::: "memory")
; #define PG8_WAIT_L(n) asm volatile("s_waitcnt lgkmcnt(" #n ")" ::: "memory")
; #define PG8_BAR __builtin_amdgcn_s_barrier()
; #define PG8_SCHED __builtin_amdgcn_sched_barrier(0)
; template <class Epi, class Sched>
; __device__ __forceinline__ void gemm_phase(PG8_LAS unsigned char* lds, const Gemm g, const Sched& S, const Epi& E) {
;     ...
;             PG8_LDA(At, 1, 1); PG8_STAGE(PG8_SA(1, 0), a3, voffA);
;             PG8_BAR; PG8_WAIT_L(0); PG8_MMA(1, 0, At, B0); PG8_BAR; PG8_SCHED;
;             PG8_STAGE(PG8_SB(1, 1), b3 + hstep, voffB);
;             PG8_WAIT_V(6); PG8_BAR; PG8_MMA(1, 1, At, B1); PG8_BAR;
;         }
;     __device__ __forceinline__ void operator()(AccRef acc, const Unit& u, int wr, int wc, int fr, int fq) const {
;         const int c0 = u.pn * 256 + wc * 32 + 8 * fq;
; #pragma unroll
;         for (int ai = 0; ai < 2; ++ai)
; #pragma unroll
;             for (int m = 0; m < 4; ++m) {
;                 const int r = u.pm * 256 + ai * 128 + wr * 64 + m * 16 + fr;
;                 const float s = rinv[r];
;                 float ss = 0.f;
; #pragma unroll
;                 for (int bj = 0; bj < 2; ++bj) {
;                     const size_t o = (size_t)r * D + c0 + bj * 128;
;                     const uint4 h8 = *(const uint4*)(H2 + o);
;                     f32x4 v0 = unpk4(make_uint2(h8.x, h8.y)), v1 = unpk4(make_uint2(h8.z, h8.w));
;                     const uint4 pp8 = *(const uint4*)(PPb + o);
	s_waitcnt lgkmcnt(0)
	s_waitcnt lgkmcnt(0)
	v_mfma_f32_16x16x32_bf16 v[60:63], v[148:151], v[168:171], v[60:63]
	v_mfma_f32_16x16x32_bf16 v[56:59], v[160:163], v[168:171], v[56:59]
	v_mfma_f32_16x16x32_bf16 v[44:47], v[148:151], v[176:179], v[44:47]
	v_mfma_f32_16x16x32_bf16 v[40:43], v[160:163], v[176:179], v[40:43]
	v_mfma_f32_16x16x32_bf16 v[28:31], v[148:151], v[184:187], v[28:31]
	v_mfma_f32_16x16x32_bf16 v[24:27], v[160:163], v[184:187], v[24:27]
	v_mfma_f32_16x16x32_bf16 v[12:15], v[148:151], v[192:195], v[12:15]
	v_mfma_f32_16x16x32_bf16 v[8:11], v[160:163], v[192:195], v[8:11]
	v_mfma_f32_16x16x32_bf16 v[60:63], v[156:159], v[172:175], v[60:63]
	v_mfma_f32_16x16x32_bf16 v[56:59], v[164:167], v[172:175], v[56:59]
	v_mfma_f32_16x16x32_bf16 v[44:47], v[156:159], v[180:183], v[44:47]
	v_mfma_f32_16x16x32_bf16 v[40:43], v[164:167], v[180:183], v[40:43]
	v_mfma_f32_16x16x32_bf16 v[28:31], v[156:159], v[188:191], v[28:31]
	v_mfma_f32_16x16x32_bf16 v[24:27], v[164:167], v[188:191], v[24:27]
	v_mfma_f32_16x16x32_bf16 v[12:15], v[156:159], v[196:199], v[12:15]
	v_mfma_f32_16x16x32_bf16 v[8:11], v[164:167], v[196:199], v[8:11]
	s_barrier
	s_add_u32 s18, s18, 0x80080
	s_addc_u32 s19, s19, 0
	s_add_i32 s20, s20, s25
	v_lshl_add_u64 v[148:149], s[18:19], 0, v[130:131]
	s_mov_b32 m0, s20
	s_nop 0
	global_load_lds_dwordx4 v[148:149], off
	v_lshl_add_u64 v[148:149], s[18:19], 0, v[134:135]
	s_add_i32 m0, s20, 0x2000
	s_nop 0
	global_load_lds_dwordx4 v[148:149], off
	s_waitcnt vmcnt(6)
	s_barrier
	v_mfma_f32_16x16x32_bf16 v[52:55], v[200:203], v[168:171], v[52:55]
	v_mfma_f32_16x16x32_bf16 v[48:51], v[208:211], v[168:171], v[48:51]
	v_mfma_f32_16x16x32_bf16 v[36:39], v[200:203], v[176:179], v[36:39]
	v_mfma_f32_16x16x32_bf16 v[32:35], v[208:211], v[176:179], v[32:35]
	v_mfma_f32_16x16x32_bf16 v[20:23], v[200:203], v[184:187], v[20:23]
	v_mfma_f32_16x16x32_bf16 v[16:19], v[208:211], v[184:187], v[16:19]
	v_mfma_f32_16x16x32_bf16 v[4:7], v[200:203], v[192:195], v[4:7]
	v_mfma_f32_16x16x32_bf16 v[0:3], v[208:211], v[192:195], v[0:3]
	v_mfma_f32_16x16x32_bf16 v[52:55], v[204:207], v[172:175], v[52:55]
	v_mfma_f32_16x16x32_bf16 v[48:51], v[212:215], v[172:175], v[48:51]
	v_mfma_f32_16x16x32_bf16 v[36:39], v[204:207], v[180:183], v[36:39]
	v_mfma_f32_16x16x32_bf16 v[32:35], v[212:215], v[180:183], v[32:35]
	v_mfma_f32_16x16x32_bf16 v[20:23], v[204:207], v[188:191], v[20:23]
	v_mfma_f32_16x16x32_bf16 v[16:19], v[212:215], v[188:191], v[16:19]
	v_mfma_f32_16x16x32_bf16 v[4:7], v[204:207], v[196:199], v[4:7]
	v_mfma_f32_16x16x32_bf16 v[0:3], v[212:215], v[196:199], v[0:3]
	s_add_i32 s53, s53, 2
	s_add_u32 s16, s16, 0x100
	s_addc_u32 s17, s17, 0
	s_add_u32 s51, s51, 0x100
	s_addc_u32 s52, s52, 0
	s_cmp_gt_u32 s53, 29
	s_barrier
	s_cbranch_scc0 .LBB0_1059
	v_bfe_i32 v254, v144, 0, 1
	v_and_b32_e32 v254, 0xfffff040, v254
	v_bfe_u32 v255, v146, 1, 1
	v_mul_u32_u24_e32 v255, 0xf80, v255
	v_add_u32_e32 v254, v254, v255
	v_and_b32_e32 v255, 1, v146
	v_lshl_add_u32 v254, v255, 6, v254
	v_ashrrev_i32_e32 v255, 31, v254
	v_lshl_add_u64 v[250:251], s[36:37], 0, v[254:255]
	v_lshl_add_u32 v148, s14, 8, v145
	v_ashrrev_i32_e32 v149, 31, v148
	v_lshl_add_u64 v[150:151], v[148:149], 2, s[26:27]
	global_load_dword v170, v[150:151], off
	v_lshl_or_b32 v150, s48, 8, v152
	v_ashrrev_i32_e32 v151, 31, v150
	v_lshlrev_b64 v[156:157], 11, v[148:149]
	v_lshl_add_u64 v[156:157], v[156:157], 0, v[150:151]
	v_lshlrev_b64 v[164:165], 1, v[156:157]
	v_lshl_add_u64 v[156:157], s[34:35], 0, v[164:165]
	v_lshl_add_u64 v[160:161], v[250:251], 0, v[164:165]
	global_load_dwordx4 v[156:159], v[156:157], off
	v_lshl_add_u64 v[166:167], s[40:41], 0, v[164:165]
	global_load_dwordx4 v[160:163], v[160:161], off
	v_or_b32_e32 v164, 0x100, v164
	v_lshl_add_u64 v[168:169], s[34:35], 0, v[164:165]
	s_and_b64 vcc, exec, s[4:5]
	s_mov_b32 s48, s6
	s_mov_b32 s14, s8
	s_mov_b64 s[18:19], s[12:13]
	s_mov_b64 s[16:17], s[10:11]
	global_load_dwordx4 v[178:181], v[168:169], off
	v_lshl_add_u64 v[236:237], v[250:251], 0, v[164:165]
	global_load_dwordx4 v[182:185], v[236:237], off
	v_or_b32_e32 v240, 16, v148
	v_ashrrev_i32_e32 v241, 31, v240
	v_lshlrev_b64 v[238:239], 11, v[240:241]
	v_lshl_add_u64 v[238:239], v[238:239], 0, v[150:151]
	v_lshlrev_b64 v[238:239], 1, v[238:239]
	v_lshl_add_u64 v[236:237], v[250:251], 0, v[238:239]
	global_load_dwordx4 v[186:189], v[236:237], off
	v_or_b32_e32 v238, 16, v148
	v_ashrrev_i32_e32 v239, 31, v238
	v_lshl_add_u64 v[236:237], v[238:239], 2, s[26:27]
	global_load_dword v190, v[236:237], off
	v_or_b32_e32 v238, 16, v148
	v_ashrrev_i32_e32 v239, 31, v238
	v_lshlrev_b64 v[236:237], 11, v[238:239]
	v_lshl_add_u64 v[236:237], v[236:237], 0, v[150:151]
	v_lshlrev_b64 v[236:237], 1, v[236:237]
	v_lshl_add_u64 v[240:241], s[34:35], 0, v[236:237]
	global_load_dwordx4 v[192:195], v[240:241], off
	v_or_b32_e32 v240, 16, v148
	v_ashrrev_i32_e32 v241, 31, v240
	v_lshlrev_b64 v[236:237], 11, v[240:241]
	v_lshl_add_u64 v[236:237], v[236:237], 0, v[150:151]
	v_lshlrev_b64 v[236:237], 1, v[236:237]
	v_or_b32_e32 v236, 0x100, v236
	v_lshl_add_u64 v[238:239], s[34:35], 0, v[236:237]
	global_load_dwordx4 v[196:199], v[238:239], off
	v_or_b32_e32 v240, 16, v148
	v_ashrrev_i32_e32 v241, 31, v240
	v_lshlrev_b64 v[238:239], 11, v[240:241]
	v_lshl_add_u64 v[238:239], v[238:239], 0, v[150:151]
	v_lshlrev_b64 v[238:239], 1, v[238:239]
	v_or_b32_e32 v238, 0x100, v238
	v_lshl_add_u64 v[236:237], v[250:251], 0, v[238:239]
	global_load_dwordx4 v[200:203], v[236:237], off
	v_or_b32_e32 v240, 32, v148
	v_ashrrev_i32_e32 v241, 31, v240
	v_lshlrev_b64 v[238:239], 11, v[240:241]
	v_lshl_add_u64 v[238:239], v[238:239], 0, v[150:151]
	v_lshlrev_b64 v[238:239], 1, v[238:239]
	v_lshl_add_u64 v[236:237], v[250:251], 0, v[238:239]
	global_load_dwordx4 v[204:207], v[236:237], off
	v_or_b32_e32 v238, 32, v148
	v_ashrrev_i32_e32 v239, 31, v238
	v_lshl_add_u64 v[236:237], v[238:239], 2, s[26:27]
	global_load_dword v191, v[236:237], off
	v_or_b32_e32 v238, 32, v148
	v_ashrrev_i32_e32 v239, 31, v238
	v_lshlrev_b64 v[236:237], 11, v[238:239]
	v_lshl_add_u64 v[236:237], v[236:237], 0, v[150:151]
	v_lshlrev_b64 v[236:237], 1, v[236:237]
	v_lshl_add_u64 v[240:241], s[34:35], 0, v[236:237]
	global_load_dwordx4 v[208:211], v[240:241], off
	v_or_b32_e32 v240, 32, v148
	v_ashrrev_i32_e32 v241, 31, v240
	v_lshlrev_b64 v[236:237], 11, v[240:241]
	v_lshl_add_u64 v[236:237], v[236:237], 0, v[150:151]
	v_lshlrev_b64 v[236:237], 1, v[236:237]
	v_or_b32_e32 v236, 0x100, v236
	v_lshl_add_u64 v[238:239], s[34:35], 0, v[236:237]
	global_load_dwordx4 v[212:215], v[238:239], off
	v_or_b32_e32 v240, 32, v148
	v_ashrrev_i32_e32 v241, 31, v240
	v_lshlrev_b64 v[238:239], 11, v[240:241]
	v_lshl_add_u64 v[238:239], v[238:239], 0, v[150:151]
	v_lshlrev_b64 v[238:239], 1, v[238:239]
	v_or_b32_e32 v238, 0x100, v238
	v_lshl_add_u64 v[236:237], v[250:251], 0, v[238:239]
	global_load_dwordx4 v[216:219], v[236:237], off
	s_waitcnt vmcnt(12)
; __device__ __forceinline__ f32x4 unpk4(uint2 u) { f32x4 r; r[0] = __uint_as_float(u.x << 16); r[1] = __uint_as_float(u.x & 0xffff0000u); r[2] = __uint_as_float(u.y << 16); r[3] = __uint_as_float(u.y & 0xffff0000u); return r; }
; __device__ __forceinline__ float sigm(float x) { return __builtin_amdgcn_rcpf(1.f + __expf(-x)); }
; __device__ __forceinline__ uint4 pk8(f32x4 a, f32x4 b) { return make_uint4(cvt_pk_bf16(a[0], a[1]), cvt_pk_bf16(a[2], a[3]), cvt_pk_bf16(b[0], b[1]), cvt_pk_bf16(b[2], b[3])); }
;     __device__ __forceinline__ void operator()(AccRef acc, const Unit& u, int wr, int wc, int fr, int fq) const {
;         const int c0 = u.pn * 256 + wc * 32 + 8 * fq;
; #pragma unroll
;         for (int ai = 0; ai < 2; ++ai)
; #pragma unroll
;             for (int m = 0; m < 4; ++m) {
;                 const int r = u.pm * 256 + ai * 128 + wr * 64 + m * 16 + fr;
;                 const float s = rinv[r];
;                 float ss = 0.f;
; #pragma unroll
;                 for (int bj = 0; bj < 2; ++bj) {
;                     const size_t o = (size_t)r * D + c0 + bj * 128;
;                     const uint4 h8 = *(const uint4*)(H2 + o);
;                     f32x4 v0 = unpk4(make_uint2(h8.x, h8.y)), v1 = unpk4(make_uint2(h8.z, h8.w));
;                     const uint4 pp8 = *(const uint4*)(PPb + o);
;                     const f32x4 p0 = unpk4(make_uint2(pp8.x, pp8.y)), p1 = unpk4(make_uint2(pp8.z, pp8.w));
; #pragma unroll
;                     for (int e = 0; e < 4; ++e) { v0[e] += sigm(acc[ai][bj][m][0][e] * s) * p0[e]; v1[e] += sigm(acc[ai][bj][m][1][e] * s) * p1[e]; }
;                     ss += v0[0] * v0[0] + v0[1] * v0[1] + v0[2] * v0[2] + v0[3] * v0[3] + v1[0] * v1[0] + v1[1] * v1[1] + v1[2] * v1[2] + v1[3] * v1[3];
;                     *(uint4*)(H3 + o) = pk8(v0, v1);
;                 }
;                 (void)ss;
;             }
	v_mul_f32_e32 v120, v120, v170
	v_mul_f32_e32 v125, v125, v170
	v_mul_f32_e32 v121, v121, v170
	v_mul_f32_e32 v127, v127, v170
	v_mul_f32_e32 v123, v123, v170
	v_mul_f32_e32 v124, v124, v170
	v_mul_f32_e32 v126, v126, v170
	v_mul_f32_e32 v122, v122, v170
	v_mul_f32_e32 v120, 0xbfb8aa3b, v120
	v_mul_f32_e32 v125, 0xbfb8aa3b, v125
	v_mul_f32_e32 v121, 0xbfb8aa3b, v121
	v_mul_f32_e32 v127, 0xbfb8aa3b, v127
	v_mul_f32_e32 v123, 0xbfb8aa3b, v123
	v_mul_f32_e32 v124, 0xbfb8aa3b, v124
	v_mul_f32_e32 v126, 0xbfb8aa3b, v126
	v_mul_f32_e32 v122, 0xbfb8aa3b, v122
	v_exp_f32_e32 v120, v120
	v_exp_f32_e32 v125, v125
	v_exp_f32_e32 v121, v121
	v_exp_f32_e32 v127, v127
	v_exp_f32_e32 v123, v123
	v_exp_f32_e32 v124, v124
	v_exp_f32_e32 v126, v126
	v_exp_f32_e32 v122, v122
	v_add_f32_e32 v120, 1.0, v120
	v_add_f32_e32 v125, 1.0, v125
	v_add_f32_e32 v121, 1.0, v121
	v_add_f32_e32 v127, 1.0, v127
	v_add_f32_e32 v123, 1.0, v123
	v_add_f32_e32 v124, 1.0, v124
	v_add_f32_e32 v126, 1.0, v126
	v_add_f32_e32 v122, 1.0, v122
	v_rcp_f32_e32 v120, v120
	v_rcp_f32_e32 v125, v125
	v_rcp_f32_e32 v121, v121
	v_rcp_f32_e32 v127, v127
	v_rcp_f32_e32 v123, v123
	v_rcp_f32_e32 v124, v124
	v_rcp_f32_e32 v126, v126
	v_rcp_f32_e32 v122, v122
	v_lshlrev_b32_e32 v149, 16, v156
	v_and_b32_e32 v156, 0xffff0000, v156
	v_lshlrev_b32_e32 v171, 16, v157
	v_and_b32_e32 v157, 0xffff0000, v157
	v_lshlrev_b32_e32 v172, 16, v158
	v_and_b32_e32 v158, 0xffff0000, v158
	v_lshlrev_b32_e32 v173, 16, v159
	v_and_b32_e32 v159, 0xffff0000, v159
	v_lshlrev_b32_e32 v174, 16, v160
	v_and_b32_e32 v160, 0xffff0000, v160
	v_lshlrev_b32_e32 v175, 16, v161
	v_and_b32_e32 v161, 0xffff0000, v161
	v_lshlrev_b32_e32 v176, 16, v162
	v_and_b32_e32 v162, 0xffff0000, v162
	v_lshlrev_b32_e32 v177, 16, v163
	v_and_b32_e32 v163, 0xffff0000, v163
	v_fmac_f32_e32 v172, v120, v176
	v_fmac_f32_e32 v156, v125, v160
	v_fmac_f32_e32 v158, v121, v162
	v_fmac_f32_e32 v157, v127, v161
	v_fmac_f32_e32 v159, v123, v163
	v_lshl_add_u64 v[120:121], v[250:251], 0, v[164:165]
	v_fmac_f32_e32 v149, v124, v174
	v_fmac_f32_e32 v171, v126, v175
	v_fmac_f32_e32 v173, v122, v177
	v_cvt_pk_bf16_f32 v122, v149, v156
	v_cvt_pk_bf16_f32 v123, v171, v157
	v_cvt_pk_bf16_f32 v124, v172, v158
	v_cvt_pk_bf16_f32 v125, v173, v159
	v_mul_f32_e32 v116, v116, v170
	v_mul_f32_e32 v117, v117, v170
	v_mul_f32_e32 v112, v112, v170
	v_mul_f32_e32 v113, v113, v170
	v_mul_f32_e32 v118, v118, v170
	v_mul_f32_e32 v114, v114, v170
	v_mul_f32_e32 v119, v119, v170
	v_mul_f32_e32 v115, v115, v170
	v_mul_f32_e32 v116, 0xbfb8aa3b, v116
	v_mul_f32_e32 v117, 0xbfb8aa3b, v117
	v_mul_f32_e32 v112, 0xbfb8aa3b, v112
	v_mul_f32_e32 v113, 0xbfb8aa3b, v113
	v_mul_f32_e32 v118, 0xbfb8aa3b, v118
	v_mul_f32_e32 v114, 0xbfb8aa3b, v114
	v_mul_f32_e32 v119, 0xbfb8aa3b, v119
	v_mul_f32_e32 v115, 0xbfb8aa3b, v115
	v_exp_f32_e32 v116, v116
	v_exp_f32_e32 v117, v117
	v_exp_f32_e32 v112, v112
	v_exp_f32_e32 v113, v113
	v_exp_f32_e32 v118, v118
	v_exp_f32_e32 v114, v114
	v_exp_f32_e32 v119, v119
	v_exp_f32_e32 v115, v115
	v_add_f32_e32 v116, 1.0, v116
	v_add_f32_e32 v117, 1.0, v117
	v_or_b32_e32 v126, 16, v148
	v_add_f32_e32 v112, 1.0, v112
	v_add_f32_e32 v113, 1.0, v113
	v_add_f32_e32 v118, 1.0, v118
	v_add_f32_e32 v114, 1.0, v114
	v_add_f32_e32 v119, 1.0, v119
	v_add_f32_e32 v115, 1.0, v115
	v_rcp_f32_e32 v116, v116
	v_rcp_f32_e32 v117, v117
	v_ashrrev_i32_e32 v127, 31, v126
	v_rcp_f32_e32 v112, v112
	v_rcp_f32_e32 v113, v113
	v_rcp_f32_e32 v118, v118
	v_rcp_f32_e32 v114, v114
	v_rcp_f32_e32 v119, v119
	v_rcp_f32_e32 v115, v115
	v_lshlrev_b64 v[120:121], 11, v[126:127]
	v_lshl_add_u64 v[120:121], v[120:121], 0, v[150:151]
	global_store_dwordx4 v[166:167], v[122:125], off
	v_lshlrev_b64 v[120:121], 1, v[120:121]
	v_lshl_add_u64 v[164:165], s[40:41], 0, v[164:165]
	v_lshl_add_u64 v[168:169], s[34:35], 0, v[120:121]
	v_or_b32_e32 v240, 48, v148
	v_ashrrev_i32_e32 v241, 31, v240
	v_lshlrev_b64 v[238:239], 11, v[240:241]
	v_lshl_add_u64 v[238:239], v[238:239], 0, v[150:151]
	v_lshlrev_b64 v[238:239], 1, v[238:239]
	v_lshl_add_u64 v[236:237], v[250:251], 0, v[238:239]
	global_load_dwordx4 v[220:223], v[236:237], off
	v_or_b32_e32 v238, 48, v148
	v_ashrrev_i32_e32 v239, 31, v238
	v_lshl_add_u64 v[236:237], v[238:239], 2, s[26:27]
	global_load_dword v224, v[236:237], off
	v_or_b32_e32 v238, 48, v148
	v_ashrrev_i32_e32 v239, 31, v238
	v_lshlrev_b64 v[236:237], 11, v[238:239]
	v_lshl_add_u64 v[236:237], v[236:237], 0, v[150:151]
	v_lshlrev_b64 v[236:237], 1, v[236:237]
	v_lshl_add_u64 v[240:241], s[34:35], 0, v[236:237]
	global_load_dwordx4 v[226:229], v[240:241], off
	s_waitcnt vmcnt(14)
	v_lshlrev_b32_e32 v122, 16, v178
	v_and_b32_e32 v123, 0xffff0000, v178
	v_lshlrev_b32_e32 v124, 16, v179
	v_and_b32_e32 v125, 0xffff0000, v179
	v_lshlrev_b32_e32 v149, 16, v180
	v_and_b32_e32 v156, 0xffff0000, v180
	v_lshlrev_b32_e32 v157, 16, v181
	v_and_b32_e32 v158, 0xffff0000, v181
	v_lshlrev_b32_e32 v159, 16, v182
	v_and_b32_e32 v160, 0xffff0000, v182
	v_lshlrev_b32_e32 v166, 16, v183
	v_and_b32_e32 v161, 0xffff0000, v183
	v_lshlrev_b32_e32 v167, 16, v184
	v_and_b32_e32 v162, 0xffff0000, v184
	v_lshlrev_b32_e32 v170, 16, v185
	v_and_b32_e32 v163, 0xffff0000, v185
	v_fmac_f32_e32 v122, v116, v159
	v_fmac_f32_e32 v123, v117, v160
	v_fmac_f32_e32 v149, v112, v167
	v_fmac_f32_e32 v156, v113, v162
	v_fmac_f32_e32 v124, v118, v166
	v_fmac_f32_e32 v157, v114, v170
	v_fmac_f32_e32 v125, v119, v161
	v_fmac_f32_e32 v158, v115, v163
	v_cvt_pk_bf16_f32 v112, v122, v123
	v_cvt_pk_bf16_f32 v113, v124, v125
	v_cvt_pk_bf16_f32 v114, v149, v156
	v_cvt_pk_bf16_f32 v115, v157, v158
	global_store_dwordx4 v[164:165], v[112:115], off
	v_lshl_add_u64 v[116:117], v[250:251], 0, v[120:121]
	v_lshl_add_u64 v[122:123], v[126:127], 2, s[26:27]
	s_nop 0
	v_lshl_add_u64 v[122:123], s[40:41], 0, v[120:121]
	v_or_b32_e32 v120, 0x100, v120
	v_lshl_add_u64 v[124:125], s[34:35], 0, v[120:121]
	v_or_b32_e32 v240, 48, v148
	v_ashrrev_i32_e32 v241, 31, v240
	v_lshlrev_b64 v[236:237], 11, v[240:241]
	v_lshl_add_u64 v[236:237], v[236:237], 0, v[150:151]
	v_lshlrev_b64 v[236:237], 1, v[236:237]
	v_or_b32_e32 v236, 0x100, v236
	v_lshl_add_u64 v[238:239], s[34:35], 0, v[236:237]
	global_load_dwordx4 v[178:181], v[238:239], off
	v_or_b32_e32 v240, 48, v148
	v_ashrrev_i32_e32 v241, 31, v240
	v_lshlrev_b64 v[238:239], 11, v[240:241]
	v_lshl_add_u64 v[238:239], v[238:239], 0, v[150:151]
	v_lshlrev_b64 v[238:239], 1, v[238:239]
	v_or_b32_e32 v238, 0x100, v238
	v_lshl_add_u64 v[236:237], v[250:251], 0, v[238:239]
	global_load_dwordx4 v[182:185], v[236:237], off
	s_waitcnt vmcnt(14)
; __device__ __forceinline__ f32x4 unpk4(uint2 u) { f32x4 r; r[0] = __uint_as_float(u.x << 16); r[1] = __uint_as_float(u.x & 0xffff0000u); r[2] = __uint_as_float(u.y << 16); r[3] = __uint_as_float(u.y & 0xffff0000u); return r; }
; __device__ __forceinline__ float sigm(float x) { return __builtin_amdgcn_rcpf(1.f + __expf(-x)); }
; __device__ __forceinline__ uint4 pk8(f32x4 a, f32x4 b) { return make_uint4(cvt_pk_bf16(a[0], a[1]), cvt_pk_bf16(a[2], a[3]), cvt_pk_bf16(b[0], b[1]), cvt_pk_bf16(b[2], b[3])); }
;     __device__ __forceinline__ void operator()(AccRef acc, const Unit& u, int wr, int wc, int fr, int fq) const {
;         const int c0 = u.pn * 256 + wc * 32 + 8 * fq;
; #pragma unroll
;         for (int ai = 0; ai < 2; ++ai)
; #pragma unroll
;             for (int m = 0; m < 4; ++m) {
;                 const int r = u.pm * 256 + ai * 128 + wr * 64 + m * 16 + fr;
;                 const float s = rinv[r];
;                 float ss = 0.f;
; #pragma unroll
;                 for (int bj = 0; bj < 2; ++bj) {
;                     const size_t o = (size_t)r * D + c0 + bj * 128;
;                     const uint4 h8 = *(const uint4*)(H2 + o);
;                     f32x4 v0 = unpk4(make_uint2(h8.x, h8.y)), v1 = unpk4(make_uint2(h8.z, h8.w));
;                     const uint4 pp8 = *(const uint4*)(PPb + o);
;                     const f32x4 p0 = unpk4(make_uint2(pp8.x, pp8.y)), p1 = unpk4(make_uint2(pp8.z, pp8.w));
; #pragma unroll
;                     for (int e = 0; e < 4; ++e) { v0[e] += sigm(acc[ai][bj][m][0][e] * s) * p0[e]; v1[e] += sigm(acc[ai][bj][m][1][e] * s) * p1[e]; }
;                     ss += v0[0] * v0[0] + v0[1] * v0[1] + v0[2] * v0[2] + v0[3] * v0[3] + v1[0] * v1[0] + v1[1] * v1[1] + v1[2] * v1[2] + v1[3] * v1[3];
;                     *(uint4*)(H3 + o) = pk8(v0, v1);
;                 }
;                 (void)ss;
;             }
	v_lshlrev_b32_e32 v158, 16, v186
	v_and_b32_e32 v116, 0xffff0000, v186
	v_mul_f32_e32 v104, v104, v190
	v_mul_f32_e32 v109, v109, v190
	v_mul_f32_e32 v105, v105, v190
	v_mul_f32_e32 v111, v111, v190
	v_mul_f32_e32 v107, v107, v190
	v_mul_f32_e32 v108, v108, v190
	v_mul_f32_e32 v110, v110, v190
	v_mul_f32_e32 v106, v106, v190
	v_mul_f32_e32 v104, 0xbfb8aa3b, v104
	v_mul_f32_e32 v109, 0xbfb8aa3b, v109
	v_mul_f32_e32 v105, 0xbfb8aa3b, v105
	v_mul_f32_e32 v111, 0xbfb8aa3b, v111
	v_mul_f32_e32 v107, 0xbfb8aa3b, v107
	v_mul_f32_e32 v108, 0xbfb8aa3b, v108
	v_mul_f32_e32 v110, 0xbfb8aa3b, v110
	v_mul_f32_e32 v106, 0xbfb8aa3b, v106
	v_exp_f32_e32 v104, v104
	v_exp_f32_e32 v109, v109
	v_exp_f32_e32 v105, v105
	v_exp_f32_e32 v111, v111
	v_exp_f32_e32 v107, v107
	v_exp_f32_e32 v108, v108
	v_exp_f32_e32 v110, v110
	v_exp_f32_e32 v106, v106
	v_add_f32_e32 v104, 1.0, v104
	v_add_f32_e32 v109, 1.0, v109
	v_add_f32_e32 v105, 1.0, v105
	v_add_f32_e32 v111, 1.0, v111
	v_add_f32_e32 v107, 1.0, v107
	v_add_f32_e32 v108, 1.0, v108
	v_add_f32_e32 v110, 1.0, v110
	v_add_f32_e32 v106, 1.0, v106
	v_rcp_f32_e32 v104, v104
	v_rcp_f32_e32 v109, v109
	v_rcp_f32_e32 v105, v105
	v_rcp_f32_e32 v111, v111
	v_rcp_f32_e32 v107, v107
	v_rcp_f32_e32 v108, v108
	v_rcp_f32_e32 v110, v110
	v_rcp_f32_e32 v106, v106
	v_lshlrev_b32_e32 v127, 16, v192
	v_and_b32_e32 v112, 0xffff0000, v192
	v_lshlrev_b32_e32 v149, 16, v193
	v_and_b32_e32 v113, 0xffff0000, v193
	v_lshlrev_b32_e32 v156, 16, v194
	v_and_b32_e32 v114, 0xffff0000, v194
	v_lshlrev_b32_e32 v157, 16, v195
	v_and_b32_e32 v115, 0xffff0000, v195
	v_lshlrev_b32_e32 v159, 16, v187
	v_and_b32_e32 v117, 0xffff0000, v187
	v_lshlrev_b32_e32 v160, 16, v188
	v_and_b32_e32 v118, 0xffff0000, v188
	v_lshlrev_b32_e32 v161, 16, v189
	v_and_b32_e32 v119, 0xffff0000, v189
	v_fmac_f32_e32 v156, v104, v160
	v_fmac_f32_e32 v112, v109, v116
	v_fmac_f32_e32 v114, v105, v118
	v_fmac_f32_e32 v113, v111, v117
	v_fmac_f32_e32 v115, v107, v119
	v_lshl_add_u64 v[104:105], v[250:251], 0, v[120:121]
	v_fmac_f32_e32 v127, v108, v158
	v_fmac_f32_e32 v149, v110, v159
	v_fmac_f32_e32 v157, v106, v161
	v_cvt_pk_bf16_f32 v106, v127, v112
	v_cvt_pk_bf16_f32 v107, v149, v113
	v_cvt_pk_bf16_f32 v108, v156, v114
	v_cvt_pk_bf16_f32 v109, v157, v115
	v_mul_f32_e32 v100, v100, v190
	v_mul_f32_e32 v101, v101, v190
	v_mul_f32_e32 v96, v96, v190
	v_mul_f32_e32 v97, v97, v190
	v_mul_f32_e32 v102, v102, v190
	v_mul_f32_e32 v98, v98, v190
	v_mul_f32_e32 v103, v103, v190
	v_mul_f32_e32 v99, v99, v190
	v_mul_f32_e32 v100, 0xbfb8aa3b, v100
	v_mul_f32_e32 v101, 0xbfb8aa3b, v101
	v_mul_f32_e32 v96, 0xbfb8aa3b, v96
	v_mul_f32_e32 v97, 0xbfb8aa3b, v97
	v_mul_f32_e32 v102, 0xbfb8aa3b, v102
	v_mul_f32_e32 v98, 0xbfb8aa3b, v98
	v_mul_f32_e32 v103, 0xbfb8aa3b, v103
	v_mul_f32_e32 v99, 0xbfb8aa3b, v99
	v_exp_f32_e32 v100, v100
	v_exp_f32_e32 v101, v101
	v_exp_f32_e32 v96, v96
	v_exp_f32_e32 v97, v97
	v_exp_f32_e32 v102, v102
	v_exp_f32_e32 v98, v98
	v_exp_f32_e32 v103, v103
	v_exp_f32_e32 v99, v99
	v_add_f32_e32 v100, 1.0, v100
	v_add_f32_e32 v101, 1.0, v101
	v_or_b32_e32 v118, 32, v148
	v_add_f32_e32 v96, 1.0, v96
	v_add_f32_e32 v97, 1.0, v97
	v_add_f32_e32 v102, 1.0, v102
	v_add_f32_e32 v98, 1.0, v98
	v_add_f32_e32 v103, 1.0, v103
	v_add_f32_e32 v99, 1.0, v99
	v_rcp_f32_e32 v100, v100
	v_rcp_f32_e32 v101, v101
	v_ashrrev_i32_e32 v119, 31, v118
	v_rcp_f32_e32 v96, v96
	v_rcp_f32_e32 v97, v97
	v_rcp_f32_e32 v102, v102
	v_rcp_f32_e32 v98, v98
	v_rcp_f32_e32 v103, v103
	v_rcp_f32_e32 v99, v99
	v_lshlrev_b64 v[104:105], 11, v[118:119]
	v_lshl_add_u64 v[104:105], v[104:105], 0, v[150:151]
	global_store_dwordx4 v[122:123], v[106:109], off
	v_lshlrev_b64 v[104:105], 1, v[104:105]
	v_lshl_add_u64 v[120:121], s[40:41], 0, v[120:121]
	v_lshl_add_u64 v[124:125], s[34:35], 0, v[104:105]
	v_add_u32_e32 v240, 0x80, v148
	v_ashrrev_i32_e32 v241, 31, v240
	v_lshlrev_b64 v[238:239], 11, v[240:241]
	v_lshl_add_u64 v[238:239], v[238:239], 0, v[150:151]
	v_lshlrev_b64 v[238:239], 1, v[238:239]
	v_lshl_add_u64 v[236:237], v[250:251], 0, v[238:239]
	global_load_dwordx4 v[186:189], v[236:237], off
	v_add_u32_e32 v238, 0x80, v148
	v_ashrrev_i32_e32 v239, 31, v238
	v_lshl_add_u64 v[236:237], v[238:239], 2, s[26:27]
	global_load_dword v190, v[236:237], off
	v_add_u32_e32 v238, 0x80, v148
	v_ashrrev_i32_e32 v239, 31, v238
	v_lshlrev_b64 v[236:237], 11, v[238:239]
	v_lshl_add_u64 v[236:237], v[236:237], 0, v[150:151]
	v_lshlrev_b64 v[236:237], 1, v[236:237]
	v_lshl_add_u64 v[240:241], s[34:35], 0, v[236:237]
	global_load_dwordx4 v[192:195], v[240:241], off
	s_waitcnt vmcnt(16)
	v_lshlrev_b32_e32 v106, 16, v196
	v_and_b32_e32 v107, 0xffff0000, v196
	v_lshlrev_b32_e32 v122, 16, v200
	v_and_b32_e32 v114, 0xffff0000, v200
	v_lshlrev_b32_e32 v108, 16, v197
	v_and_b32_e32 v109, 0xffff0000, v197
	v_lshlrev_b32_e32 v110, 16, v198
	v_and_b32_e32 v111, 0xffff0000, v198
	v_lshlrev_b32_e32 v112, 16, v199
	v_and_b32_e32 v113, 0xffff0000, v199
	v_lshlrev_b32_e32 v123, 16, v201
	v_and_b32_e32 v115, 0xffff0000, v201
	v_lshlrev_b32_e32 v126, 16, v202
	v_and_b32_e32 v116, 0xffff0000, v202
	v_lshlrev_b32_e32 v127, 16, v203
	v_and_b32_e32 v117, 0xffff0000, v203
	v_fmac_f32_e32 v106, v100, v122
	v_fmac_f32_e32 v107, v101, v114
	v_fmac_f32_e32 v110, v96, v126
	v_fmac_f32_e32 v111, v97, v116
	v_fmac_f32_e32 v108, v102, v123
	v_fmac_f32_e32 v112, v98, v127
	v_fmac_f32_e32 v109, v103, v115
	v_fmac_f32_e32 v113, v99, v117
	v_cvt_pk_bf16_f32 v96, v106, v107
	v_cvt_pk_bf16_f32 v97, v108, v109
	v_cvt_pk_bf16_f32 v98, v110, v111
	v_cvt_pk_bf16_f32 v99, v112, v113
	global_store_dwordx4 v[120:121], v[96:99], off
	v_lshl_add_u64 v[100:101], v[250:251], 0, v[104:105]
	v_lshl_add_u64 v[106:107], v[118:119], 2, s[26:27]
	s_nop 0
	v_lshl_add_u64 v[106:107], s[40:41], 0, v[104:105]
	v_or_b32_e32 v104, 0x100, v104
	v_lshl_add_u64 v[108:109], s[34:35], 0, v[104:105]
	v_add_u32_e32 v240, 0x80, v148
	v_ashrrev_i32_e32 v241, 31, v240
	v_lshlrev_b64 v[236:237], 11, v[240:241]
	v_lshl_add_u64 v[236:237], v[236:237], 0, v[150:151]
	v_lshlrev_b64 v[236:237], 1, v[236:237]
	v_or_b32_e32 v236, 0x100, v236
	v_lshl_add_u64 v[238:239], s[34:35], 0, v[236:237]
	global_load_dwordx4 v[196:199], v[238:239], off
	v_add_u32_e32 v240, 0x80, v148
	v_ashrrev_i32_e32 v241, 31, v240
	v_lshlrev_b64 v[238:239], 11, v[240:241]
	v_lshl_add_u64 v[238:239], v[238:239], 0, v[150:151]
	v_lshlrev_b64 v[238:239], 1, v[238:239]
	v_or_b32_e32 v238, 0x100, v238
	v_lshl_add_u64 v[236:237], v[250:251], 0, v[238:239]
	global_load_dwordx4 v[200:203], v[236:237], off
	s_waitcnt vmcnt(16)
; __device__ __forceinline__ f32x4 unpk4(uint2 u) { f32x4 r; r[0] = __uint_as_float(u.x << 16); r[1] = __uint_as_float(u.x & 0xffff0000u); r[2] = __uint_as_float(u.y << 16); r[3] = __uint_as_float(u.y & 0xffff0000u); return r; }
; __device__ __forceinline__ float sigm(float x) { return __builtin_amdgcn_rcpf(1.f + __expf(-x)); }
; __device__ __forceinline__ uint4 pk8(f32x4 a, f32x4 b) { return make_uint4(cvt_pk_bf16(a[0], a[1]), cvt_pk_bf16(a[2], a[3]), cvt_pk_bf16(b[0], b[1]), cvt_pk_bf16(b[2], b[3])); }
;     __device__ __forceinline__ void operator()(AccRef acc, const Unit& u, int wr, int wc, int fr, int fq) const {
;         const int c0 = u.pn * 256 + wc * 32 + 8 * fq;
; #pragma unroll
;         for (int ai = 0; ai < 2; ++ai)
; #pragma unroll
;             for (int m = 0; m < 4; ++m) {
;                 const int r = u.pm * 256 + ai * 128 + wr * 64 + m * 16 + fr;
;                 const float s = rinv[r];
;                 float ss = 0.f;
; #pragma unroll
;                 for (int bj = 0; bj < 2; ++bj) {
;                     const size_t o = (size_t)r * D + c0 + bj * 128;
;                     const uint4 h8 = *(const uint4*)(H2 + o);
;                     f32x4 v0 = unpk4(make_uint2(h8.x, h8.y)), v1 = unpk4(make_uint2(h8.z, h8.w));
;                     const uint4 pp8 = *(const uint4*)(PPb + o);
;                     const f32x4 p0 = unpk4(make_uint2(pp8.x, pp8.y)), p1 = unpk4(make_uint2(pp8.z, pp8.w));
; #pragma unroll
;                     for (int e = 0; e < 4; ++e) { v0[e] += sigm(acc[ai][bj][m][0][e] * s) * p0[e]; v1[e] += sigm(acc[ai][bj][m][1][e] * s) * p1[e]; }
;                     ss += v0[0] * v0[0] + v0[1] * v0[1] + v0[2] * v0[2] + v0[3] * v0[3] + v1[0] * v1[0] + v1[1] * v1[1] + v1[2] * v1[2] + v1[3] * v1[3];
;                     *(uint4*)(H3 + o) = pk8(v0, v1);
;                 }
;                 (void)ss;
;             }
	v_lshlrev_b32_e32 v115, 16, v204
	v_and_b32_e32 v100, 0xffff0000, v204
	v_mul_f32_e32 v88, v88, v191
	v_mul_f32_e32 v93, v93, v191
	v_mul_f32_e32 v89, v89, v191
	v_mul_f32_e32 v95, v95, v191
	v_mul_f32_e32 v91, v91, v191
	v_mul_f32_e32 v92, v92, v191
	v_mul_f32_e32 v94, v94, v191
	v_mul_f32_e32 v90, v90, v191
	v_mul_f32_e32 v88, 0xbfb8aa3b, v88
	v_mul_f32_e32 v93, 0xbfb8aa3b, v93
	v_mul_f32_e32 v89, 0xbfb8aa3b, v89
	v_mul_f32_e32 v95, 0xbfb8aa3b, v95
	v_mul_f32_e32 v91, 0xbfb8aa3b, v91
	v_mul_f32_e32 v92, 0xbfb8aa3b, v92
	v_mul_f32_e32 v94, 0xbfb8aa3b, v94
	v_mul_f32_e32 v90, 0xbfb8aa3b, v90
	v_exp_f32_e32 v88, v88
	v_exp_f32_e32 v93, v93
	v_exp_f32_e32 v89, v89
	v_exp_f32_e32 v95, v95
	v_exp_f32_e32 v91, v91
	v_exp_f32_e32 v92, v92
	v_exp_f32_e32 v94, v94
	v_exp_f32_e32 v90, v90
	v_add_f32_e32 v88, 1.0, v88
	v_add_f32_e32 v93, 1.0, v93
	v_add_f32_e32 v89, 1.0, v89
	v_add_f32_e32 v95, 1.0, v95
	v_add_f32_e32 v91, 1.0, v91
	v_add_f32_e32 v92, 1.0, v92
	v_add_f32_e32 v94, 1.0, v94
	v_add_f32_e32 v90, 1.0, v90
	v_rcp_f32_e32 v88, v88
	v_rcp_f32_e32 v93, v93
	v_rcp_f32_e32 v89, v89
	v_rcp_f32_e32 v95, v95
	v_rcp_f32_e32 v91, v91
	v_rcp_f32_e32 v92, v92
	v_rcp_f32_e32 v94, v94
	v_rcp_f32_e32 v90, v90
	v_lshlrev_b32_e32 v111, 16, v208
	v_and_b32_e32 v96, 0xffff0000, v208
	v_lshlrev_b32_e32 v112, 16, v209
	v_and_b32_e32 v97, 0xffff0000, v209
	v_lshlrev_b32_e32 v113, 16, v210
	v_and_b32_e32 v98, 0xffff0000, v210
	v_lshlrev_b32_e32 v114, 16, v211
	v_and_b32_e32 v99, 0xffff0000, v211
	v_lshlrev_b32_e32 v116, 16, v205
	v_and_b32_e32 v101, 0xffff0000, v205
	v_lshlrev_b32_e32 v117, 16, v206
	v_and_b32_e32 v102, 0xffff0000, v206
	v_lshlrev_b32_e32 v118, 16, v207
	v_and_b32_e32 v103, 0xffff0000, v207
	v_fmac_f32_e32 v113, v88, v117
	v_fmac_f32_e32 v96, v93, v100
	v_fmac_f32_e32 v98, v89, v102
	v_fmac_f32_e32 v97, v95, v101
	v_fmac_f32_e32 v99, v91, v103
	v_lshl_add_u64 v[88:89], v[250:251], 0, v[104:105]
	v_fmac_f32_e32 v111, v92, v115
	v_fmac_f32_e32 v112, v94, v116
	v_fmac_f32_e32 v114, v90, v118
	v_cvt_pk_bf16_f32 v90, v111, v96
	v_cvt_pk_bf16_f32 v91, v112, v97
	v_cvt_pk_bf16_f32 v92, v113, v98
	v_cvt_pk_bf16_f32 v93, v114, v99
	v_mul_f32_e32 v84, v84, v191
	v_mul_f32_e32 v85, v85, v191
	v_mul_f32_e32 v80, v80, v191
	v_mul_f32_e32 v81, v81, v191
	v_mul_f32_e32 v86, v86, v191
	v_mul_f32_e32 v82, v82, v191
	v_mul_f32_e32 v87, v87, v191
	v_mul_f32_e32 v83, v83, v191
	v_mul_f32_e32 v84, 0xbfb8aa3b, v84
	v_mul_f32_e32 v85, 0xbfb8aa3b, v85
	v_mul_f32_e32 v80, 0xbfb8aa3b, v80
	v_mul_f32_e32 v81, 0xbfb8aa3b, v81
	v_mul_f32_e32 v86, 0xbfb8aa3b, v86
	v_mul_f32_e32 v82, 0xbfb8aa3b, v82
	v_mul_f32_e32 v87, 0xbfb8aa3b, v87
	v_mul_f32_e32 v83, 0xbfb8aa3b, v83
	v_exp_f32_e32 v84, v84
	v_exp_f32_e32 v85, v85
	v_exp_f32_e32 v80, v80
	v_exp_f32_e32 v81, v81
	v_exp_f32_e32 v86, v86
	v_exp_f32_e32 v82, v82
	v_exp_f32_e32 v87, v87
	v_exp_f32_e32 v83, v83
	v_add_f32_e32 v84, 1.0, v84
	v_add_f32_e32 v85, 1.0, v85
	v_or_b32_e32 v102, 48, v148
	v_add_f32_e32 v80, 1.0, v80
	v_add_f32_e32 v81, 1.0, v81
	v_add_f32_e32 v86, 1.0, v86
	v_add_f32_e32 v82, 1.0, v82
	v_add_f32_e32 v87, 1.0, v87
	v_add_f32_e32 v83, 1.0, v83
	v_rcp_f32_e32 v84, v84
	v_rcp_f32_e32 v85, v85
	v_ashrrev_i32_e32 v103, 31, v102
	v_rcp_f32_e32 v80, v80
	v_rcp_f32_e32 v81, v81
	v_rcp_f32_e32 v86, v86
	v_rcp_f32_e32 v82, v82
	v_rcp_f32_e32 v87, v87
	v_rcp_f32_e32 v83, v83
	v_lshlrev_b64 v[88:89], 11, v[102:103]
	v_lshl_add_u64 v[88:89], v[88:89], 0, v[150:151]
	global_store_dwordx4 v[106:107], v[90:93], off
	v_lshlrev_b64 v[88:89], 1, v[88:89]
	v_lshl_add_u64 v[104:105], s[40:41], 0, v[104:105]
	v_lshl_add_u64 v[108:109], s[34:35], 0, v[88:89]
	v_add_u32_e32 v240, 0x90, v148
	v_ashrrev_i32_e32 v241, 31, v240
	v_lshlrev_b64 v[238:239], 11, v[240:241]
	v_lshl_add_u64 v[238:239], v[238:239], 0, v[150:151]
	v_lshlrev_b64 v[238:239], 1, v[238:239]
	v_lshl_add_u64 v[236:237], v[250:251], 0, v[238:239]
	global_load_dwordx4 v[204:207], v[236:237], off
	v_add_u32_e32 v238, 0x90, v148
	v_ashrrev_i32_e32 v239, 31, v238
	v_lshl_add_u64 v[236:237], v[238:239], 2, s[26:27]
	global_load_dword v191, v[236:237], off
	v_add_u32_e32 v238, 0x90, v148
	v_ashrrev_i32_e32 v239, 31, v238
	v_lshlrev_b64 v[236:237], 11, v[238:239]
	v_lshl_add_u64 v[236:237], v[236:237], 0, v[150:151]
	v_lshlrev_b64 v[236:237], 1, v[236:237]
	v_lshl_add_u64 v[240:241], s[34:35], 0, v[236:237]
	global_load_dwordx4 v[208:211], v[240:241], off
	s_waitcnt vmcnt(18)
	v_lshlrev_b32_e32 v90, 16, v212
	v_and_b32_e32 v91, 0xffff0000, v212
	v_lshlrev_b32_e32 v106, 16, v216
	v_and_b32_e32 v98, 0xffff0000, v216
	v_lshlrev_b32_e32 v92, 16, v213
	v_and_b32_e32 v93, 0xffff0000, v213
	v_lshlrev_b32_e32 v94, 16, v214
	v_and_b32_e32 v95, 0xffff0000, v214
	v_lshlrev_b32_e32 v96, 16, v215
	v_and_b32_e32 v97, 0xffff0000, v215
	v_lshlrev_b32_e32 v107, 16, v217
	v_and_b32_e32 v99, 0xffff0000, v217
	v_lshlrev_b32_e32 v110, 16, v218
	v_and_b32_e32 v100, 0xffff0000, v218
	v_lshlrev_b32_e32 v111, 16, v219
	v_and_b32_e32 v101, 0xffff0000, v219
	v_fmac_f32_e32 v90, v84, v106
	v_fmac_f32_e32 v91, v85, v98
	v_fmac_f32_e32 v94, v80, v110
	v_fmac_f32_e32 v95, v81, v100
	v_fmac_f32_e32 v92, v86, v107
	v_fmac_f32_e32 v96, v82, v111
	v_fmac_f32_e32 v93, v87, v99
	v_fmac_f32_e32 v97, v83, v101
	v_cvt_pk_bf16_f32 v80, v90, v91
	v_cvt_pk_bf16_f32 v81, v92, v93
	v_cvt_pk_bf16_f32 v82, v94, v95
	v_cvt_pk_bf16_f32 v83, v96, v97
	global_store_dwordx4 v[104:105], v[80:83], off
	v_lshl_add_u64 v[84:85], v[250:251], 0, v[88:89]
	v_lshl_add_u64 v[90:91], v[102:103], 2, s[26:27]
	s_nop 0
	v_lshl_add_u64 v[90:91], s[40:41], 0, v[88:89]
	v_or_b32_e32 v88, 0x100, v88
	v_lshl_add_u64 v[92:93], s[34:35], 0, v[88:89]
	v_add_u32_e32 v240, 0x90, v148
	v_ashrrev_i32_e32 v241, 31, v240
	v_lshlrev_b64 v[236:237], 11, v[240:241]
	v_lshl_add_u64 v[236:237], v[236:237], 0, v[150:151]
	v_lshlrev_b64 v[236:237], 1, v[236:237]
	v_or_b32_e32 v236, 0x100, v236
	v_lshl_add_u64 v[238:239], s[34:35], 0, v[236:237]
	global_load_dwordx4 v[212:215], v[238:239], off
	v_add_u32_e32 v240, 0x90, v148
	v_ashrrev_i32_e32 v241, 31, v240
	v_lshlrev_b64 v[238:239], 11, v[240:241]
	v_lshl_add_u64 v[238:239], v[238:239], 0, v[150:151]
	v_lshlrev_b64 v[238:239], 1, v[238:239]
	v_or_b32_e32 v238, 0x100, v238
	v_lshl_add_u64 v[236:237], v[250:251], 0, v[238:239]
	global_load_dwordx4 v[216:219], v[236:237], off
	s_waitcnt vmcnt(17)
; __device__ __forceinline__ f32x4 unpk4(uint2 u) { f32x4 r; r[0] = __uint_as_float(u.x << 16); r[1] = __uint_as_float(u.x & 0xffff0000u); r[2] = __uint_as_float(u.y << 16); r[3] = __uint_as_float(u.y & 0xffff0000u); return r; }
; __device__ __forceinline__ float sigm(float x) { return __builtin_amdgcn_rcpf(1.f + __expf(-x)); }
; __device__ __forceinline__ uint4 pk8(f32x4 a, f32x4 b) { return make_uint4(cvt_pk_bf16(a[0], a[1]), cvt_pk_bf16(a[2], a[3]), cvt_pk_bf16(b[0], b[1]), cvt_pk_bf16(b[2], b[3])); }
;     __device__ __forceinline__ void operator()(AccRef acc, const Unit& u, int wr, int wc, int fr, int fq) const {
;         const int c0 = u.pn * 256 + wc * 32 + 8 * fq;
; #pragma unroll
;         for (int ai = 0; ai < 2; ++ai)
; #pragma unroll
;             for (int m = 0; m < 4; ++m) {
;                 const int r = u.pm * 256 + ai * 128 + wr * 64 + m * 16 + fr;
;                 const float s = rinv[r];
;                 float ss = 0.f;
; #pragma unroll
;                 for (int bj = 0; bj < 2; ++bj) {
;                     const size_t o = (size_t)r * D + c0 + bj * 128;
;                     const uint4 h8 = *(const uint4*)(H2 + o);
;                     f32x4 v0 = unpk4(make_uint2(h8.x, h8.y)), v1 = unpk4(make_uint2(h8.z, h8.w));
;                     const uint4 pp8 = *(const uint4*)(PPb + o);
;                     const f32x4 p0 = unpk4(make_uint2(pp8.x, pp8.y)), p1 = unpk4(make_uint2(pp8.z, pp8.w));
; #pragma unroll
;                     for (int e = 0; e < 4; ++e) { v0[e] += sigm(acc[ai][bj][m][0][e] * s) * p0[e]; v1[e] += sigm(acc[ai][bj][m][1][e] * s) * p1[e]; }
;                     ss += v0[0] * v0[0] + v0[1] * v0[1] + v0[2] * v0[2] + v0[3] * v0[3] + v1[0] * v1[0] + v1[1] * v1[1] + v1[2] * v1[2] + v1[3] * v1[3];
;                     *(uint4*)(H3 + o) = pk8(v0, v1);
;                 }
;                 (void)ss;
;             }
	v_lshlrev_b32_e32 v99, 16, v220
	v_and_b32_e32 v84, 0xffff0000, v220
	v_mul_f32_e32 v72, v72, v224
	v_mul_f32_e32 v77, v77, v224
	v_mul_f32_e32 v73, v73, v224
	v_mul_f32_e32 v79, v79, v224
	v_mul_f32_e32 v75, v75, v224
	v_mul_f32_e32 v76, v76, v224
	v_mul_f32_e32 v78, v78, v224
	v_mul_f32_e32 v74, v74, v224
	v_mul_f32_e32 v72, 0xbfb8aa3b, v72
	v_mul_f32_e32 v77, 0xbfb8aa3b, v77
	v_mul_f32_e32 v73, 0xbfb8aa3b, v73
	v_mul_f32_e32 v79, 0xbfb8aa3b, v79
	v_mul_f32_e32 v75, 0xbfb8aa3b, v75
	v_mul_f32_e32 v76, 0xbfb8aa3b, v76
	v_mul_f32_e32 v78, 0xbfb8aa3b, v78
	v_mul_f32_e32 v74, 0xbfb8aa3b, v74
	v_exp_f32_e32 v72, v72
	v_exp_f32_e32 v77, v77
	v_exp_f32_e32 v73, v73
	v_exp_f32_e32 v79, v79
	v_exp_f32_e32 v75, v75
	v_exp_f32_e32 v76, v76
	v_exp_f32_e32 v78, v78
	v_exp_f32_e32 v74, v74
	v_add_f32_e32 v72, 1.0, v72
	v_add_f32_e32 v77, 1.0, v77
	v_add_f32_e32 v73, 1.0, v73
	v_add_f32_e32 v79, 1.0, v79
	v_add_f32_e32 v75, 1.0, v75
	v_add_f32_e32 v76, 1.0, v76
	v_add_f32_e32 v78, 1.0, v78
	v_add_f32_e32 v74, 1.0, v74
	v_rcp_f32_e32 v72, v72
	v_rcp_f32_e32 v77, v77
	v_rcp_f32_e32 v73, v73
	v_rcp_f32_e32 v79, v79
	v_rcp_f32_e32 v75, v75
	v_rcp_f32_e32 v76, v76
	v_rcp_f32_e32 v78, v78
	v_rcp_f32_e32 v74, v74
	v_lshlrev_b32_e32 v95, 16, v226
	v_and_b32_e32 v80, 0xffff0000, v226
	v_lshlrev_b32_e32 v96, 16, v227
	v_and_b32_e32 v81, 0xffff0000, v227
	v_lshlrev_b32_e32 v97, 16, v228
	v_and_b32_e32 v82, 0xffff0000, v228
	v_lshlrev_b32_e32 v98, 16, v229
	v_and_b32_e32 v83, 0xffff0000, v229
	v_lshlrev_b32_e32 v100, 16, v221
	v_and_b32_e32 v85, 0xffff0000, v221
	v_lshlrev_b32_e32 v101, 16, v222
	v_and_b32_e32 v86, 0xffff0000, v222
	v_lshlrev_b32_e32 v102, 16, v223
	v_and_b32_e32 v87, 0xffff0000, v223
	v_fmac_f32_e32 v97, v72, v101
	v_fmac_f32_e32 v80, v77, v84
	v_fmac_f32_e32 v82, v73, v86
	v_fmac_f32_e32 v81, v79, v85
	v_fmac_f32_e32 v83, v75, v87
	v_lshl_add_u64 v[72:73], v[250:251], 0, v[88:89]
	v_fmac_f32_e32 v95, v76, v99
	v_fmac_f32_e32 v96, v78, v100
	v_fmac_f32_e32 v98, v74, v102
	v_cvt_pk_bf16_f32 v74, v95, v80
	v_cvt_pk_bf16_f32 v75, v96, v81
	v_cvt_pk_bf16_f32 v76, v97, v82
	v_cvt_pk_bf16_f32 v77, v98, v83
	v_mul_f32_e32 v68, v68, v224
	v_mul_f32_e32 v69, v69, v224
	v_mul_f32_e32 v64, v64, v224
	v_mul_f32_e32 v65, v65, v224
	v_mul_f32_e32 v70, v70, v224
	v_mul_f32_e32 v66, v66, v224
	v_mul_f32_e32 v71, v71, v224
	v_mul_f32_e32 v67, v67, v224
	v_mul_f32_e32 v68, 0xbfb8aa3b, v68
	v_mul_f32_e32 v69, 0xbfb8aa3b, v69
	v_mul_f32_e32 v64, 0xbfb8aa3b, v64
	v_mul_f32_e32 v65, 0xbfb8aa3b, v65
	v_mul_f32_e32 v70, 0xbfb8aa3b, v70
	v_mul_f32_e32 v66, 0xbfb8aa3b, v66
	v_mul_f32_e32 v71, 0xbfb8aa3b, v71
	v_mul_f32_e32 v67, 0xbfb8aa3b, v67
	v_exp_f32_e32 v68, v68
	v_exp_f32_e32 v69, v69
	v_exp_f32_e32 v64, v64
	v_exp_f32_e32 v65, v65
	v_exp_f32_e32 v70, v70
	v_exp_f32_e32 v66, v66
	v_exp_f32_e32 v71, v71
	v_exp_f32_e32 v67, v67
	v_add_f32_e32 v68, 1.0, v68
	v_add_f32_e32 v69, 1.0, v69
	v_add_u32_e32 v86, 0x80, v148
	v_add_f32_e32 v64, 1.0, v64
	v_add_f32_e32 v65, 1.0, v65
	v_add_f32_e32 v70, 1.0, v70
	v_add_f32_e32 v66, 1.0, v66
	v_add_f32_e32 v71, 1.0, v71
	v_add_f32_e32 v67, 1.0, v67
	v_rcp_f32_e32 v68, v68
	v_rcp_f32_e32 v69, v69
	v_ashrrev_i32_e32 v87, 31, v86
	v_rcp_f32_e32 v64, v64
	v_rcp_f32_e32 v65, v65
	v_rcp_f32_e32 v70, v70
	v_rcp_f32_e32 v66, v66
	v_rcp_f32_e32 v71, v71
	v_rcp_f32_e32 v67, v67
	v_lshlrev_b64 v[72:73], 11, v[86:87]
	v_lshl_add_u64 v[72:73], v[72:73], 0, v[150:151]
	global_store_dwordx4 v[90:91], v[74:77], off
	v_lshlrev_b64 v[72:73], 1, v[72:73]
	v_lshl_add_u64 v[88:89], s[40:41], 0, v[88:89]
	v_lshl_add_u64 v[92:93], s[34:35], 0, v[72:73]
	v_add_u32_e32 v240, 0xa0, v148
	v_ashrrev_i32_e32 v241, 31, v240
	v_lshlrev_b64 v[238:239], 11, v[240:241]
	v_lshl_add_u64 v[238:239], v[238:239], 0, v[150:151]
	v_lshlrev_b64 v[238:239], 1, v[238:239]
	v_lshl_add_u64 v[236:237], v[250:251], 0, v[238:239]
	global_load_dwordx4 v[220:223], v[236:237], off
	v_add_u32_e32 v238, 0xa0, v148
	v_ashrrev_i32_e32 v239, 31, v238
	v_lshl_add_u64 v[236:237], v[238:239], 2, s[26:27]
	global_load_dword v224, v[236:237], off
	v_add_u32_e32 v238, 0xa0, v148
	v_ashrrev_i32_e32 v239, 31, v238
	v_lshlrev_b64 v[236:237], 11, v[238:239]
	v_lshl_add_u64 v[236:237], v[236:237], 0, v[150:151]
	v_lshlrev_b64 v[236:237], 1, v[236:237]
	v_lshl_add_u64 v[240:241], s[34:35], 0, v[236:237]
	global_load_dwordx4 v[226:229], v[240:241], off
	s_waitcnt vmcnt(18)
	v_lshlrev_b32_e32 v74, 16, v178
	v_and_b32_e32 v75, 0xffff0000, v178
	v_lshlrev_b32_e32 v90, 16, v182
	v_and_b32_e32 v82, 0xffff0000, v182
	v_lshlrev_b32_e32 v76, 16, v179
	v_and_b32_e32 v77, 0xffff0000, v179
	v_lshlrev_b32_e32 v78, 16, v180
	v_and_b32_e32 v79, 0xffff0000, v180
	v_lshlrev_b32_e32 v80, 16, v181
	v_and_b32_e32 v81, 0xffff0000, v181
	v_lshlrev_b32_e32 v91, 16, v183
	v_and_b32_e32 v83, 0xffff0000, v183
	v_lshlrev_b32_e32 v94, 16, v184
	v_and_b32_e32 v84, 0xffff0000, v184
	v_lshlrev_b32_e32 v95, 16, v185
	v_and_b32_e32 v85, 0xffff0000, v185
	v_fmac_f32_e32 v74, v68, v90
	v_fmac_f32_e32 v75, v69, v82
	v_fmac_f32_e32 v78, v64, v94
	v_fmac_f32_e32 v79, v65, v84
	v_fmac_f32_e32 v76, v70, v91
	v_fmac_f32_e32 v80, v66, v95
	v_fmac_f32_e32 v77, v71, v83
	v_fmac_f32_e32 v81, v67, v85
	v_cvt_pk_bf16_f32 v64, v74, v75
	v_cvt_pk_bf16_f32 v65, v76, v77
	v_cvt_pk_bf16_f32 v66, v78, v79
	v_cvt_pk_bf16_f32 v67, v80, v81
	global_store_dwordx4 v[88:89], v[64:67], off
	v_lshl_add_u64 v[68:69], v[250:251], 0, v[72:73]
	v_lshl_add_u64 v[74:75], v[86:87], 2, s[26:27]
	s_nop 0
	v_lshl_add_u64 v[74:75], s[40:41], 0, v[72:73]
	v_or_b32_e32 v72, 0x100, v72
	v_lshl_add_u64 v[76:77], s[34:35], 0, v[72:73]
	v_add_u32_e32 v240, 0xa0, v148
	v_ashrrev_i32_e32 v241, 31, v240
	v_lshlrev_b64 v[236:237], 11, v[240:241]
	v_lshl_add_u64 v[236:237], v[236:237], 0, v[150:151]
	v_lshlrev_b64 v[236:237], 1, v[236:237]
	v_or_b32_e32 v236, 0x100, v236
	v_lshl_add_u64 v[238:239], s[34:35], 0, v[236:237]
	global_load_dwordx4 v[178:181], v[238:239], off
	v_add_u32_e32 v240, 0xa0, v148
	v_ashrrev_i32_e32 v241, 31, v240
	v_lshlrev_b64 v[238:239], 11, v[240:241]
	v_lshl_add_u64 v[238:239], v[238:239], 0, v[150:151]
	v_lshlrev_b64 v[238:239], 1, v[238:239]
	v_or_b32_e32 v238, 0x100, v238
	v_lshl_add_u64 v[236:237], v[250:251], 0, v[238:239]
	global_load_dwordx4 v[182:185], v[236:237], off
	s_waitcnt vmcnt(17)
; __device__ __forceinline__ f32x4 unpk4(uint2 u) { f32x4 r; r[0] = __uint_as_float(u.x << 16); r[1] = __uint_as_float(u.x & 0xffff0000u); r[2] = __uint_as_float(u.y << 16); r[3] = __uint_as_float(u.y & 0xffff0000u); return r; }
; __device__ __forceinline__ float sigm(float x) { return __builtin_amdgcn_rcpf(1.f + __expf(-x)); }
; __device__ __forceinline__ uint4 pk8(f32x4 a, f32x4 b) { return make_uint4(cvt_pk_bf16(a[0], a[1]), cvt_pk_bf16(a[2], a[3]), cvt_pk_bf16(b[0], b[1]), cvt_pk_bf16(b[2], b[3])); }
;     __device__ __forceinline__ void operator()(AccRef acc, const Unit& u, int wr, int wc, int fr, int fq) const {
;         const int c0 = u.pn * 256 + wc * 32 + 8 * fq;
; #pragma unroll
;         for (int ai = 0; ai < 2; ++ai)
; #pragma unroll
;             for (int m = 0; m < 4; ++m) {
;                 const int r = u.pm * 256 + ai * 128 + wr * 64 + m * 16 + fr;
;                 const float s = rinv[r];
;                 float ss = 0.f;
; #pragma unroll
;                 for (int bj = 0; bj < 2; ++bj) {
;                     const size_t o = (size_t)r * D + c0 + bj * 128;
;                     const uint4 h8 = *(const uint4*)(H2 + o);
;                     f32x4 v0 = unpk4(make_uint2(h8.x, h8.y)), v1 = unpk4(make_uint2(h8.z, h8.w));
;                     const uint4 pp8 = *(const uint4*)(PPb + o);
;                     const f32x4 p0 = unpk4(make_uint2(pp8.x, pp8.y)), p1 = unpk4(make_uint2(pp8.z, pp8.w));
; #pragma unroll
;                     for (int e = 0; e < 4; ++e) { v0[e] += sigm(acc[ai][bj][m][0][e] * s) * p0[e]; v1[e] += sigm(acc[ai][bj][m][1][e] * s) * p1[e]; }
;                     ss += v0[0] * v0[0] + v0[1] * v0[1] + v0[2] * v0[2] + v0[3] * v0[3] + v1[0] * v1[0] + v1[1] * v1[1] + v1[2] * v1[2] + v1[3] * v1[3];
;                     *(uint4*)(H3 + o) = pk8(v0, v1);
;                 }
;                 (void)ss;
;             }
	v_lshlrev_b32_e32 v83, 16, v186
	v_and_b32_e32 v68, 0xffff0000, v186
	v_mul_f32_e32 v56, v56, v190
	v_mul_f32_e32 v61, v61, v190
	v_mul_f32_e32 v57, v57, v190
	v_mul_f32_e32 v63, v63, v190
	v_mul_f32_e32 v59, v59, v190
	v_mul_f32_e32 v60, v60, v190
	v_mul_f32_e32 v62, v62, v190
	v_mul_f32_e32 v58, v58, v190
	v_mul_f32_e32 v56, 0xbfb8aa3b, v56
	v_mul_f32_e32 v61, 0xbfb8aa3b, v61
	v_mul_f32_e32 v57, 0xbfb8aa3b, v57
	v_mul_f32_e32 v63, 0xbfb8aa3b, v63
	v_mul_f32_e32 v59, 0xbfb8aa3b, v59
	v_mul_f32_e32 v60, 0xbfb8aa3b, v60
	v_mul_f32_e32 v62, 0xbfb8aa3b, v62
	v_mul_f32_e32 v58, 0xbfb8aa3b, v58
	v_exp_f32_e32 v56, v56
	v_exp_f32_e32 v61, v61
	v_exp_f32_e32 v57, v57
	v_exp_f32_e32 v63, v63
	v_exp_f32_e32 v59, v59
	v_exp_f32_e32 v60, v60
	v_exp_f32_e32 v62, v62
	v_exp_f32_e32 v58, v58
	v_add_f32_e32 v56, 1.0, v56
	v_add_f32_e32 v61, 1.0, v61
	v_add_f32_e32 v57, 1.0, v57
	v_add_f32_e32 v63, 1.0, v63
	v_add_f32_e32 v59, 1.0, v59
	v_add_f32_e32 v60, 1.0, v60
	v_add_f32_e32 v62, 1.0, v62
	v_add_f32_e32 v58, 1.0, v58
	v_rcp_f32_e32 v56, v56
	v_rcp_f32_e32 v61, v61
	v_rcp_f32_e32 v57, v57
	v_rcp_f32_e32 v63, v63
	v_rcp_f32_e32 v59, v59
	v_rcp_f32_e32 v60, v60
	v_rcp_f32_e32 v62, v62
	v_rcp_f32_e32 v58, v58
	v_lshlrev_b32_e32 v79, 16, v192
	v_and_b32_e32 v64, 0xffff0000, v192
	v_lshlrev_b32_e32 v80, 16, v193
	v_and_b32_e32 v65, 0xffff0000, v193
	v_lshlrev_b32_e32 v81, 16, v194
	v_and_b32_e32 v66, 0xffff0000, v194
	v_lshlrev_b32_e32 v82, 16, v195
	v_and_b32_e32 v67, 0xffff0000, v195
	v_lshlrev_b32_e32 v84, 16, v187
	v_and_b32_e32 v69, 0xffff0000, v187
	v_lshlrev_b32_e32 v85, 16, v188
	v_and_b32_e32 v70, 0xffff0000, v188
	v_lshlrev_b32_e32 v86, 16, v189
	v_and_b32_e32 v71, 0xffff0000, v189
	v_fmac_f32_e32 v81, v56, v85
	v_fmac_f32_e32 v64, v61, v68
	v_fmac_f32_e32 v66, v57, v70
	v_fmac_f32_e32 v65, v63, v69
	v_fmac_f32_e32 v67, v59, v71
	v_lshl_add_u64 v[56:57], v[250:251], 0, v[72:73]
	v_fmac_f32_e32 v79, v60, v83
	v_fmac_f32_e32 v80, v62, v84
	v_fmac_f32_e32 v82, v58, v86
	v_cvt_pk_bf16_f32 v58, v79, v64
	v_cvt_pk_bf16_f32 v59, v80, v65
	v_cvt_pk_bf16_f32 v60, v81, v66
	v_cvt_pk_bf16_f32 v61, v82, v67
	v_mul_f32_e32 v52, v52, v190
	v_mul_f32_e32 v53, v53, v190
	v_mul_f32_e32 v48, v48, v190
	v_mul_f32_e32 v49, v49, v190
	v_mul_f32_e32 v54, v54, v190
	v_mul_f32_e32 v50, v50, v190
	v_mul_f32_e32 v55, v55, v190
	v_mul_f32_e32 v51, v51, v190
	v_mul_f32_e32 v52, 0xbfb8aa3b, v52
	v_mul_f32_e32 v53, 0xbfb8aa3b, v53
	v_mul_f32_e32 v48, 0xbfb8aa3b, v48
	v_mul_f32_e32 v49, 0xbfb8aa3b, v49
	v_mul_f32_e32 v54, 0xbfb8aa3b, v54
	v_mul_f32_e32 v50, 0xbfb8aa3b, v50
	v_mul_f32_e32 v55, 0xbfb8aa3b, v55
	v_mul_f32_e32 v51, 0xbfb8aa3b, v51
	v_exp_f32_e32 v52, v52
	v_exp_f32_e32 v53, v53
	v_exp_f32_e32 v48, v48
	v_exp_f32_e32 v49, v49
	v_exp_f32_e32 v54, v54
	v_exp_f32_e32 v50, v50
	v_exp_f32_e32 v55, v55
	v_exp_f32_e32 v51, v51
	v_add_f32_e32 v52, 1.0, v52
	v_add_f32_e32 v53, 1.0, v53
	v_add_u32_e32 v70, 0x90, v148
	v_add_f32_e32 v48, 1.0, v48
	v_add_f32_e32 v49, 1.0, v49
	v_add_f32_e32 v54, 1.0, v54
	v_add_f32_e32 v50, 1.0, v50
	v_add_f32_e32 v55, 1.0, v55
	v_add_f32_e32 v51, 1.0, v51
	v_rcp_f32_e32 v52, v52
	v_rcp_f32_e32 v53, v53
	v_ashrrev_i32_e32 v71, 31, v70
	v_rcp_f32_e32 v48, v48
	v_rcp_f32_e32 v49, v49
	v_rcp_f32_e32 v54, v54
	v_rcp_f32_e32 v50, v50
	v_rcp_f32_e32 v55, v55
	v_rcp_f32_e32 v51, v51
	v_lshlrev_b64 v[56:57], 11, v[70:71]
	v_lshl_add_u64 v[56:57], v[56:57], 0, v[150:151]
	global_store_dwordx4 v[74:75], v[58:61], off
	v_lshlrev_b64 v[56:57], 1, v[56:57]
	v_lshl_add_u64 v[72:73], s[40:41], 0, v[72:73]
	v_lshl_add_u64 v[76:77], s[34:35], 0, v[56:57]
	v_add_u32_e32 v240, 0xb0, v148
	v_ashrrev_i32_e32 v241, 31, v240
	v_lshlrev_b64 v[238:239], 11, v[240:241]
	v_lshl_add_u64 v[238:239], v[238:239], 0, v[150:151]
	v_lshlrev_b64 v[238:239], 1, v[238:239]
	v_lshl_add_u64 v[236:237], v[250:251], 0, v[238:239]
	global_load_dwordx4 v[186:189], v[236:237], off
	v_add_u32_e32 v238, 0xb0, v148
	v_ashrrev_i32_e32 v239, 31, v238
	v_lshl_add_u64 v[236:237], v[238:239], 2, s[26:27]
	global_load_dword v190, v[236:237], off
	v_add_u32_e32 v238, 0xb0, v148
	v_ashrrev_i32_e32 v239, 31, v238
	v_lshlrev_b64 v[236:237], 11, v[238:239]
	v_lshl_add_u64 v[236:237], v[236:237], 0, v[150:151]
	v_lshlrev_b64 v[236:237], 1, v[236:237]
	v_lshl_add_u64 v[240:241], s[34:35], 0, v[236:237]
	global_load_dwordx4 v[192:195], v[240:241], off
	s_waitcnt vmcnt(18)
	v_lshlrev_b32_e32 v58, 16, v196
	v_and_b32_e32 v59, 0xffff0000, v196
	v_lshlrev_b32_e32 v74, 16, v200
	v_and_b32_e32 v66, 0xffff0000, v200
	v_lshlrev_b32_e32 v60, 16, v197
	v_and_b32_e32 v61, 0xffff0000, v197
	v_lshlrev_b32_e32 v62, 16, v198
	v_and_b32_e32 v63, 0xffff0000, v198
	v_lshlrev_b32_e32 v64, 16, v199
	v_and_b32_e32 v65, 0xffff0000, v199
	v_lshlrev_b32_e32 v75, 16, v201
	v_and_b32_e32 v67, 0xffff0000, v201
	v_lshlrev_b32_e32 v78, 16, v202
	v_and_b32_e32 v68, 0xffff0000, v202
	v_lshlrev_b32_e32 v79, 16, v203
	v_and_b32_e32 v69, 0xffff0000, v203
	v_fmac_f32_e32 v58, v52, v74
	v_fmac_f32_e32 v59, v53, v66
	v_fmac_f32_e32 v62, v48, v78
	v_fmac_f32_e32 v63, v49, v68
	v_fmac_f32_e32 v60, v54, v75
	v_fmac_f32_e32 v64, v50, v79
	v_fmac_f32_e32 v61, v55, v67
	v_fmac_f32_e32 v65, v51, v69
	v_cvt_pk_bf16_f32 v48, v58, v59
	v_cvt_pk_bf16_f32 v49, v60, v61
	v_cvt_pk_bf16_f32 v50, v62, v63
	v_cvt_pk_bf16_f32 v51, v64, v65
	global_store_dwordx4 v[72:73], v[48:51], off
	v_lshl_add_u64 v[52:53], v[250:251], 0, v[56:57]
	v_lshl_add_u64 v[58:59], v[70:71], 2, s[26:27]
	s_nop 0
	v_lshl_add_u64 v[58:59], s[40:41], 0, v[56:57]
	v_or_b32_e32 v56, 0x100, v56
	v_lshl_add_u64 v[60:61], s[34:35], 0, v[56:57]
	v_add_u32_e32 v240, 0xb0, v148
	v_ashrrev_i32_e32 v241, 31, v240
	v_lshlrev_b64 v[236:237], 11, v[240:241]
	v_lshl_add_u64 v[236:237], v[236:237], 0, v[150:151]
	v_lshlrev_b64 v[236:237], 1, v[236:237]
	v_or_b32_e32 v236, 0x100, v236
	v_lshl_add_u64 v[238:239], s[34:35], 0, v[236:237]
	global_load_dwordx4 v[196:199], v[238:239], off
	v_add_u32_e32 v240, 0xb0, v148
	v_ashrrev_i32_e32 v241, 31, v240
	v_lshlrev_b64 v[238:239], 11, v[240:241]
	v_lshl_add_u64 v[238:239], v[238:239], 0, v[150:151]
	v_lshlrev_b64 v[238:239], 1, v[238:239]
	v_or_b32_e32 v238, 0x100, v238
	v_lshl_add_u64 v[236:237], v[250:251], 0, v[238:239]
	global_load_dwordx4 v[200:203], v[236:237], off
	s_waitcnt vmcnt(17)
; __device__ __forceinline__ f32x4 unpk4(uint2 u) { f32x4 r; r[0] = __uint_as_float(u.x << 16); r[1] = __uint_as_float(u.x & 0xffff0000u); r[2] = __uint_as_float(u.y << 16); r[3] = __uint_as_float(u.y & 0xffff0000u); return r; }
; __device__ __forceinline__ float sigm(float x) { return __builtin_amdgcn_rcpf(1.f + __expf(-x)); }
; __device__ __forceinline__ uint4 pk8(f32x4 a, f32x4 b) { return make_uint4(cvt_pk_bf16(a[0], a[1]), cvt_pk_bf16(a[2], a[3]), cvt_pk_bf16(b[0], b[1]), cvt_pk_bf16(b[2], b[3])); }
;     __device__ __forceinline__ void operator()(AccRef acc, const Unit& u, int wr, int wc, int fr, int fq) const {
;         const int c0 = u.pn * 256 + wc * 32 + 8 * fq;
; #pragma unroll
;         for (int ai = 0; ai < 2; ++ai)
; #pragma unroll
;             for (int m = 0; m < 4; ++m) {
;                 const int r = u.pm * 256 + ai * 128 + wr * 64 + m * 16 + fr;
;                 const float s = rinv[r];
;                 float ss = 0.f;
; #pragma unroll
;                 for (int bj = 0; bj < 2; ++bj) {
;                     const size_t o = (size_t)r * D + c0 + bj * 128;
;                     const uint4 h8 = *(const uint4*)(H2 + o);
;                     f32x4 v0 = unpk4(make_uint2(h8.x, h8.y)), v1 = unpk4(make_uint2(h8.z, h8.w));
;                     const uint4 pp8 = *(const uint4*)(PPb + o);
;                     const f32x4 p0 = unpk4(make_uint2(pp8.x, pp8.y)), p1 = unpk4(make_uint2(pp8.z, pp8.w));
; #pragma unroll
;                     for (int e = 0; e < 4; ++e) { v0[e] += sigm(acc[ai][bj][m][0][e] * s) * p0[e]; v1[e] += sigm(acc[ai][bj][m][1][e] * s) * p1[e]; }
;                     ss += v0[0] * v0[0] + v0[1] * v0[1] + v0[2] * v0[2] + v0[3] * v0[3] + v1[0] * v1[0] + v1[1] * v1[1] + v1[2] * v1[2] + v1[3] * v1[3];
;                     *(uint4*)(H3 + o) = pk8(v0, v1);
;                 }
;                 (void)ss;
;             }
	v_lshlrev_b32_e32 v67, 16, v204
	v_and_b32_e32 v52, 0xffff0000, v204
	v_mul_f32_e32 v40, v40, v191
	v_mul_f32_e32 v45, v45, v191
	v_mul_f32_e32 v41, v41, v191
	v_mul_f32_e32 v47, v47, v191
	v_mul_f32_e32 v43, v43, v191
	v_mul_f32_e32 v44, v44, v191
	v_mul_f32_e32 v46, v46, v191
	v_mul_f32_e32 v42, v42, v191
	v_mul_f32_e32 v40, 0xbfb8aa3b, v40
	v_mul_f32_e32 v45, 0xbfb8aa3b, v45
	v_mul_f32_e32 v41, 0xbfb8aa3b, v41
	v_mul_f32_e32 v47, 0xbfb8aa3b, v47
	v_mul_f32_e32 v43, 0xbfb8aa3b, v43
	v_mul_f32_e32 v44, 0xbfb8aa3b, v44
	v_mul_f32_e32 v46, 0xbfb8aa3b, v46
	v_mul_f32_e32 v42, 0xbfb8aa3b, v42
	v_exp_f32_e32 v40, v40
	v_exp_f32_e32 v45, v45
	v_exp_f32_e32 v41, v41
	v_exp_f32_e32 v47, v47
	v_exp_f32_e32 v43, v43
	v_exp_f32_e32 v44, v44
	v_exp_f32_e32 v46, v46
	v_exp_f32_e32 v42, v42
	v_add_f32_e32 v40, 1.0, v40
	v_add_f32_e32 v45, 1.0, v45
	v_add_f32_e32 v41, 1.0, v41
	v_add_f32_e32 v47, 1.0, v47
	v_add_f32_e32 v43, 1.0, v43
	v_add_f32_e32 v44, 1.0, v44
	v_add_f32_e32 v46, 1.0, v46
	v_add_f32_e32 v42, 1.0, v42
	v_rcp_f32_e32 v40, v40
	v_rcp_f32_e32 v45, v45
	v_rcp_f32_e32 v41, v41
	v_rcp_f32_e32 v47, v47
	v_rcp_f32_e32 v43, v43
	v_rcp_f32_e32 v44, v44
	v_rcp_f32_e32 v46, v46
	v_rcp_f32_e32 v42, v42
	v_lshlrev_b32_e32 v63, 16, v208
	v_and_b32_e32 v48, 0xffff0000, v208
	v_lshlrev_b32_e32 v64, 16, v209
	v_and_b32_e32 v49, 0xffff0000, v209
	v_lshlrev_b32_e32 v65, 16, v210
	v_and_b32_e32 v50, 0xffff0000, v210
	v_lshlrev_b32_e32 v66, 16, v211
	v_and_b32_e32 v51, 0xffff0000, v211
	v_lshlrev_b32_e32 v68, 16, v205
	v_and_b32_e32 v53, 0xffff0000, v205
	v_lshlrev_b32_e32 v69, 16, v206
	v_and_b32_e32 v54, 0xffff0000, v206
	v_lshlrev_b32_e32 v70, 16, v207
	v_and_b32_e32 v55, 0xffff0000, v207
	v_fmac_f32_e32 v65, v40, v69
	v_fmac_f32_e32 v48, v45, v52
	v_fmac_f32_e32 v50, v41, v54
	v_fmac_f32_e32 v49, v47, v53
	v_fmac_f32_e32 v51, v43, v55
	v_lshl_add_u64 v[40:41], v[250:251], 0, v[56:57]
	v_fmac_f32_e32 v63, v44, v67
	v_fmac_f32_e32 v64, v46, v68
	v_fmac_f32_e32 v66, v42, v70
	v_cvt_pk_bf16_f32 v42, v63, v48
	v_cvt_pk_bf16_f32 v43, v64, v49
	v_cvt_pk_bf16_f32 v44, v65, v50
	v_cvt_pk_bf16_f32 v45, v66, v51
	v_mul_f32_e32 v36, v36, v191
	v_mul_f32_e32 v37, v37, v191
	v_mul_f32_e32 v32, v32, v191
	v_mul_f32_e32 v33, v33, v191
	v_mul_f32_e32 v38, v38, v191
	v_mul_f32_e32 v34, v34, v191
	v_mul_f32_e32 v39, v39, v191
	v_mul_f32_e32 v35, v35, v191
	v_mul_f32_e32 v36, 0xbfb8aa3b, v36
	v_mul_f32_e32 v37, 0xbfb8aa3b, v37
	v_mul_f32_e32 v32, 0xbfb8aa3b, v32
	v_mul_f32_e32 v33, 0xbfb8aa3b, v33
	v_mul_f32_e32 v38, 0xbfb8aa3b, v38
	v_mul_f32_e32 v34, 0xbfb8aa3b, v34
	v_mul_f32_e32 v39, 0xbfb8aa3b, v39
	v_mul_f32_e32 v35, 0xbfb8aa3b, v35
	v_exp_f32_e32 v36, v36
	v_exp_f32_e32 v37, v37
	v_exp_f32_e32 v32, v32
	v_exp_f32_e32 v33, v33
	v_exp_f32_e32 v38, v38
	v_exp_f32_e32 v34, v34
	v_exp_f32_e32 v39, v39
	v_exp_f32_e32 v35, v35
	v_add_f32_e32 v36, 1.0, v36
	v_add_f32_e32 v37, 1.0, v37
	v_add_u32_e32 v54, 0xa0, v148
	v_add_f32_e32 v32, 1.0, v32
	v_add_f32_e32 v33, 1.0, v33
	v_add_f32_e32 v38, 1.0, v38
	v_add_f32_e32 v34, 1.0, v34
	v_add_f32_e32 v39, 1.0, v39
	v_add_f32_e32 v35, 1.0, v35
	v_rcp_f32_e32 v36, v36
	v_rcp_f32_e32 v37, v37
	v_ashrrev_i32_e32 v55, 31, v54
	v_rcp_f32_e32 v32, v32
	v_rcp_f32_e32 v33, v33
	v_rcp_f32_e32 v38, v38
	v_rcp_f32_e32 v34, v34
	v_rcp_f32_e32 v39, v39
	v_rcp_f32_e32 v35, v35
	v_lshlrev_b64 v[40:41], 11, v[54:55]
	v_lshl_add_u64 v[40:41], v[40:41], 0, v[150:151]
	global_store_dwordx4 v[58:59], v[42:45], off
	v_lshlrev_b64 v[40:41], 1, v[40:41]
	v_lshl_add_u64 v[56:57], s[40:41], 0, v[56:57]
	v_lshl_add_u64 v[60:61], s[34:35], 0, v[40:41]
	s_waitcnt vmcnt(15)
	v_lshlrev_b32_e32 v42, 16, v212
	v_and_b32_e32 v43, 0xffff0000, v212
	v_lshlrev_b32_e32 v58, 16, v216
	v_and_b32_e32 v50, 0xffff0000, v216
	v_lshlrev_b32_e32 v44, 16, v213
	v_and_b32_e32 v45, 0xffff0000, v213
	v_lshlrev_b32_e32 v46, 16, v214
	v_and_b32_e32 v47, 0xffff0000, v214
	v_lshlrev_b32_e32 v48, 16, v215
	v_and_b32_e32 v49, 0xffff0000, v215
	v_lshlrev_b32_e32 v59, 16, v217
	v_and_b32_e32 v51, 0xffff0000, v217
	v_lshlrev_b32_e32 v62, 16, v218
	v_and_b32_e32 v52, 0xffff0000, v218
	v_lshlrev_b32_e32 v63, 16, v219
	v_and_b32_e32 v53, 0xffff0000, v219
	v_fmac_f32_e32 v42, v36, v58
	v_fmac_f32_e32 v43, v37, v50
	v_fmac_f32_e32 v46, v32, v62
	v_fmac_f32_e32 v47, v33, v52
	v_fmac_f32_e32 v44, v38, v59
	v_fmac_f32_e32 v48, v34, v63
	v_fmac_f32_e32 v45, v39, v51
	v_fmac_f32_e32 v49, v35, v53
	v_cvt_pk_bf16_f32 v32, v42, v43
	v_cvt_pk_bf16_f32 v33, v44, v45
	v_cvt_pk_bf16_f32 v34, v46, v47
	v_cvt_pk_bf16_f32 v35, v48, v49
	global_store_dwordx4 v[56:57], v[32:35], off
	v_lshl_add_u64 v[36:37], v[250:251], 0, v[40:41]
	v_lshl_add_u64 v[42:43], v[54:55], 2, s[26:27]
	s_nop 0
	v_lshl_add_u64 v[42:43], s[40:41], 0, v[40:41]
	v_or_b32_e32 v40, 0x100, v40
	v_lshl_add_u64 v[44:45], s[34:35], 0, v[40:41]
	s_waitcnt vmcnt(12)
; __device__ __forceinline__ f32x4 unpk4(uint2 u) { f32x4 r; r[0] = __uint_as_float(u.x << 16); r[1] = __uint_as_float(u.x & 0xffff0000u); r[2] = __uint_as_float(u.y << 16); r[3] = __uint_as_float(u.y & 0xffff0000u); return r; }
; __device__ __forceinline__ float sigm(float x) { return __builtin_amdgcn_rcpf(1.f + __expf(-x)); }
; __device__ __forceinline__ uint4 pk8(f32x4 a, f32x4 b) { return make_uint4(cvt_pk_bf16(a[0], a[1]), cvt_pk_bf16(a[2], a[3]), cvt_pk_bf16(b[0], b[1]), cvt_pk_bf16(b[2], b[3])); }
;     __device__ __forceinline__ void operator()(AccRef acc, const Unit& u, int wr, int wc, int fr, int fq) const {
;         const int c0 = u.pn * 256 + wc * 32 + 8 * fq;
; #pragma unroll
;         for (int ai = 0; ai < 2; ++ai)
; #pragma unroll
;             for (int m = 0; m < 4; ++m) {
;                 const int r = u.pm * 256 + ai * 128 + wr * 64 + m * 16 + fr;
;                 const float s = rinv[r];
;                 float ss = 0.f;
; #pragma unroll
;                 for (int bj = 0; bj < 2; ++bj) {
;                     const size_t o = (size_t)r * D + c0 + bj * 128;
;                     const uint4 h8 = *(const uint4*)(H2 + o);
;                     f32x4 v0 = unpk4(make_uint2(h8.x, h8.y)), v1 = unpk4(make_uint2(h8.z, h8.w));
;                     const uint4 pp8 = *(const uint4*)(PPb + o);
;                     const f32x4 p0 = unpk4(make_uint2(pp8.x, pp8.y)), p1 = unpk4(make_uint2(pp8.z, pp8.w));
; #pragma unroll
;                     for (int e = 0; e < 4; ++e) { v0[e] += sigm(acc[ai][bj][m][0][e] * s) * p0[e]; v1[e] += sigm(acc[ai][bj][m][1][e] * s) * p1[e]; }
;                     ss += v0[0] * v0[0] + v0[1] * v0[1] + v0[2] * v0[2] + v0[3] * v0[3] + v1[0] * v1[0] + v1[1] * v1[1] + v1[2] * v1[2] + v1[3] * v1[3];
;                     *(uint4*)(H3 + o) = pk8(v0, v1);
;                 }
;                 (void)ss;
;             }
	v_lshlrev_b32_e32 v51, 16, v220
	v_and_b32_e32 v36, 0xffff0000, v220
	v_mul_f32_e32 v24, v24, v224
	v_mul_f32_e32 v29, v29, v224
	v_mul_f32_e32 v25, v25, v224
	v_mul_f32_e32 v31, v31, v224
	v_mul_f32_e32 v27, v27, v224
	v_mul_f32_e32 v28, v28, v224
	v_mul_f32_e32 v30, v30, v224
	v_mul_f32_e32 v26, v26, v224
	v_mul_f32_e32 v24, 0xbfb8aa3b, v24
	v_mul_f32_e32 v29, 0xbfb8aa3b, v29
	v_mul_f32_e32 v25, 0xbfb8aa3b, v25
	v_mul_f32_e32 v31, 0xbfb8aa3b, v31
	v_mul_f32_e32 v27, 0xbfb8aa3b, v27
	v_mul_f32_e32 v28, 0xbfb8aa3b, v28
	v_mul_f32_e32 v30, 0xbfb8aa3b, v30
	v_mul_f32_e32 v26, 0xbfb8aa3b, v26
	v_exp_f32_e32 v24, v24
	v_exp_f32_e32 v29, v29
	v_exp_f32_e32 v25, v25
	v_exp_f32_e32 v31, v31
	v_exp_f32_e32 v27, v27
	v_exp_f32_e32 v28, v28
	v_exp_f32_e32 v30, v30
	v_exp_f32_e32 v26, v26
	v_add_f32_e32 v24, 1.0, v24
	v_add_f32_e32 v29, 1.0, v29
	v_add_f32_e32 v25, 1.0, v25
	v_add_f32_e32 v31, 1.0, v31
	v_add_f32_e32 v27, 1.0, v27
	v_add_f32_e32 v28, 1.0, v28
	v_add_f32_e32 v30, 1.0, v30
	v_add_f32_e32 v26, 1.0, v26
	v_rcp_f32_e32 v24, v24
	v_rcp_f32_e32 v29, v29
	v_rcp_f32_e32 v25, v25
	v_rcp_f32_e32 v31, v31
	v_rcp_f32_e32 v27, v27
	v_rcp_f32_e32 v28, v28
	v_rcp_f32_e32 v30, v30
	v_rcp_f32_e32 v26, v26
	v_lshlrev_b32_e32 v47, 16, v226
	v_and_b32_e32 v32, 0xffff0000, v226
	v_lshlrev_b32_e32 v48, 16, v227
	v_and_b32_e32 v33, 0xffff0000, v227
	v_lshlrev_b32_e32 v49, 16, v228
	v_and_b32_e32 v34, 0xffff0000, v228
	v_lshlrev_b32_e32 v50, 16, v229
	v_and_b32_e32 v35, 0xffff0000, v229
	v_lshlrev_b32_e32 v52, 16, v221
	v_and_b32_e32 v37, 0xffff0000, v221
	v_lshlrev_b32_e32 v53, 16, v222
	v_and_b32_e32 v38, 0xffff0000, v222
	v_lshlrev_b32_e32 v54, 16, v223
	v_and_b32_e32 v39, 0xffff0000, v223
	v_fmac_f32_e32 v49, v24, v53
	v_fmac_f32_e32 v32, v29, v36
	v_fmac_f32_e32 v34, v25, v38
	v_fmac_f32_e32 v33, v31, v37
	v_fmac_f32_e32 v35, v27, v39
	v_lshl_add_u64 v[24:25], v[250:251], 0, v[40:41]
	v_fmac_f32_e32 v47, v28, v51
	v_fmac_f32_e32 v48, v30, v52
	v_fmac_f32_e32 v50, v26, v54
	v_cvt_pk_bf16_f32 v26, v47, v32
	v_cvt_pk_bf16_f32 v27, v48, v33
	v_cvt_pk_bf16_f32 v28, v49, v34
	v_cvt_pk_bf16_f32 v29, v50, v35
	v_mul_f32_e32 v20, v20, v224
	v_mul_f32_e32 v21, v21, v224
	v_mul_f32_e32 v16, v16, v224
	v_mul_f32_e32 v17, v17, v224
	v_mul_f32_e32 v22, v22, v224
	v_mul_f32_e32 v18, v18, v224
	v_mul_f32_e32 v23, v23, v224
	v_mul_f32_e32 v19, v19, v224
	v_mul_f32_e32 v20, 0xbfb8aa3b, v20
	v_mul_f32_e32 v21, 0xbfb8aa3b, v21
	v_mul_f32_e32 v16, 0xbfb8aa3b, v16
	v_mul_f32_e32 v17, 0xbfb8aa3b, v17
	v_mul_f32_e32 v22, 0xbfb8aa3b, v22
	v_mul_f32_e32 v18, 0xbfb8aa3b, v18
	v_mul_f32_e32 v23, 0xbfb8aa3b, v23
	v_mul_f32_e32 v19, 0xbfb8aa3b, v19
	v_exp_f32_e32 v20, v20
	v_exp_f32_e32 v21, v21
	v_exp_f32_e32 v16, v16
	v_exp_f32_e32 v17, v17
	v_exp_f32_e32 v22, v22
	v_exp_f32_e32 v18, v18
	v_exp_f32_e32 v23, v23
	v_exp_f32_e32 v19, v19
	v_add_f32_e32 v20, 1.0, v20
	v_add_f32_e32 v21, 1.0, v21
	v_add_u32_e32 v38, 0xb0, v148
	v_add_f32_e32 v16, 1.0, v16
	v_add_f32_e32 v17, 1.0, v17
	v_add_f32_e32 v22, 1.0, v22
	v_add_f32_e32 v18, 1.0, v18
	v_add_f32_e32 v23, 1.0, v23
	v_add_f32_e32 v19, 1.0, v19
	v_rcp_f32_e32 v20, v20
	v_rcp_f32_e32 v21, v21
	v_ashrrev_i32_e32 v39, 31, v38
	v_rcp_f32_e32 v16, v16
	v_rcp_f32_e32 v17, v17
	v_rcp_f32_e32 v22, v22
	v_rcp_f32_e32 v18, v18
	v_rcp_f32_e32 v23, v23
	v_rcp_f32_e32 v19, v19
	v_lshlrev_b64 v[24:25], 11, v[38:39]
	v_lshl_add_u64 v[24:25], v[24:25], 0, v[150:151]
	global_store_dwordx4 v[42:43], v[26:29], off
	v_lshlrev_b64 v[24:25], 1, v[24:25]
	v_lshl_add_u64 v[40:41], s[40:41], 0, v[40:41]
	v_lshl_add_u64 v[44:45], s[34:35], 0, v[24:25]
	s_waitcnt vmcnt(10)
	v_lshlrev_b32_e32 v26, 16, v178
	v_and_b32_e32 v27, 0xffff0000, v178
	v_lshlrev_b32_e32 v42, 16, v182
	v_and_b32_e32 v34, 0xffff0000, v182
	v_lshlrev_b32_e32 v28, 16, v179
	v_and_b32_e32 v29, 0xffff0000, v179
	v_lshlrev_b32_e32 v30, 16, v180
	v_and_b32_e32 v31, 0xffff0000, v180
	v_lshlrev_b32_e32 v32, 16, v181
	v_and_b32_e32 v33, 0xffff0000, v181
	v_lshlrev_b32_e32 v43, 16, v183
	v_and_b32_e32 v35, 0xffff0000, v183
	v_lshlrev_b32_e32 v46, 16, v184
	v_and_b32_e32 v36, 0xffff0000, v184
	v_lshlrev_b32_e32 v47, 16, v185
	v_and_b32_e32 v37, 0xffff0000, v185
	v_fmac_f32_e32 v26, v20, v42
	v_fmac_f32_e32 v27, v21, v34
	v_fmac_f32_e32 v30, v16, v46
	v_fmac_f32_e32 v31, v17, v36
	v_fmac_f32_e32 v28, v22, v43
	v_fmac_f32_e32 v32, v18, v47
	v_fmac_f32_e32 v29, v23, v35
	v_fmac_f32_e32 v33, v19, v37
	v_cvt_pk_bf16_f32 v16, v26, v27
	v_cvt_pk_bf16_f32 v17, v28, v29
	v_cvt_pk_bf16_f32 v18, v30, v31
	v_cvt_pk_bf16_f32 v19, v32, v33
	global_store_dwordx4 v[40:41], v[16:19], off
	v_lshl_add_u64 v[20:21], v[250:251], 0, v[24:25]
	v_lshl_add_u64 v[26:27], v[38:39], 2, s[26:27]
	s_nop 0
	v_lshl_add_u64 v[26:27], s[40:41], 0, v[24:25]
	v_or_b32_e32 v24, 0x100, v24
	v_lshl_add_u64 v[28:29], s[34:35], 0, v[24:25]
	s_waitcnt vmcnt(7)
; #define PG8_WAIT_V(n) asm volatile("s_waitcnt vmcnt(" #n ")" ::: "memory")
; #define PG8_BAR __builtin_amdgcn_s_barrier()
; __device__ __forceinline__ f32x4 unpk4(uint2 u) { f32x4 r; r[0] = __uint_as_float(u.x << 16); r[1] = __uint_as_float(u.x & 0xffff0000u); r[2] = __uint_as_float(u.y << 16); r[3] = __uint_as_float(u.y & 0xffff0000u); return r; }
; __device__ __forceinline__ float sigm(float x) { return __builtin_amdgcn_rcpf(1.f + __expf(-x)); }
; __device__ __forceinline__ uint4 pk8(f32x4 a, f32x4 b) { return make_uint4(cvt_pk_bf16(a[0], a[1]), cvt_pk_bf16(a[2], a[3]), cvt_pk_bf16(b[0], b[1]), cvt_pk_bf16(b[2], b[3])); }
; template <class Epi, class Sched>
; __device__ __forceinline__ void gemm_phase(PG8_LAS unsigned char* lds, const Gemm g, const Sched& S, const Epi& E) {
;     ...
;     PG8_WAIT_V(0);
;     if (wr == 0) PG8_BAR;
;     __device__ __forceinline__ void operator()(AccRef acc, const Unit& u, int wr, int wc, int fr, int fq) const {
;     ...
;         for (int ai = 0; ai < 2; ++ai)
; #pragma unroll
;             for (int m = 0; m < 4; ++m) {
;                 const int r = u.pm * 256 + ai * 128 + wr * 64 + m * 16 + fr;
;                 const float s = rinv[r];
;                 const size_t o = (size_t)r * D + c0;
;                 const uint4 pa8 = *(const uint4*)(Pa + o), pb8 = *(const uint4*)(Pb + o);
;                 f32x4 v[2];
; #pragma unroll
;                 for (int n = 0; n < 2; ++n) {
;                     const f32x4 pa = unpk4(n == 0 ? make_uint2(pa8.x, pa8.y) : make_uint2(pa8.z, pa8.w)), pb = unpk4(n == 0 ? make_uint2(pb8.x, pb8.y) : make_uint2(pb8.z, pb8.w));
; #pragma unroll
;                     for (int e = 0; e < 4; ++e) v[n][e] = sigm(acc[ai][0][m][n][e] * s) * pa[e] + sigm(acc[ai][1][m][n][e] * s) * pb[e];
;                 }
;                 *(uint4*)(O + o) = pk8(v[0], v[1]);
	v_lshlrev_b32_e32 v35, 16, v186
	v_and_b32_e32 v20, 0xffff0000, v186
	v_mul_f32_e32 v13, v13, v190
	v_mul_f32_e32 v15, v15, v190
	v_mul_f32_e32 v12, v12, v190
	v_mul_f32_e32 v8, v8, v190
	v_mul_f32_e32 v9, v9, v190
	v_mul_f32_e32 v14, v14, v190
	v_mul_f32_e32 v11, v11, v190
	v_mul_f32_e32 v13, 0xbfb8aa3b, v13
	v_mul_f32_e32 v15, 0xbfb8aa3b, v15
	v_mul_f32_e32 v10, v10, v190
	v_mul_f32_e32 v12, 0xbfb8aa3b, v12
	v_mul_f32_e32 v8, 0xbfb8aa3b, v8
	v_mul_f32_e32 v9, 0xbfb8aa3b, v9
	v_mul_f32_e32 v14, 0xbfb8aa3b, v14
	v_mul_f32_e32 v11, 0xbfb8aa3b, v11
	v_exp_f32_e32 v13, v13
	v_exp_f32_e32 v15, v15
	v_mul_f32_e32 v10, 0xbfb8aa3b, v10
	v_exp_f32_e32 v12, v12
	v_exp_f32_e32 v8, v8
	v_exp_f32_e32 v9, v9
	v_exp_f32_e32 v14, v14
	v_exp_f32_e32 v11, v11
	v_exp_f32_e32 v10, v10
	v_add_f32_e32 v13, 1.0, v13
	v_add_f32_e32 v15, 1.0, v15
	v_add_f32_e32 v12, 1.0, v12
	v_add_f32_e32 v8, 1.0, v8
	v_add_f32_e32 v9, 1.0, v9
	v_add_f32_e32 v14, 1.0, v14
	v_add_f32_e32 v11, 1.0, v11
	v_rcp_f32_e32 v13, v13
	v_rcp_f32_e32 v15, v15
	v_add_f32_e32 v10, 1.0, v10
	v_rcp_f32_e32 v12, v12
	v_rcp_f32_e32 v8, v8
	v_rcp_f32_e32 v9, v9
	v_rcp_f32_e32 v14, v14
	v_rcp_f32_e32 v11, v11
	v_rcp_f32_e32 v10, v10
	v_lshlrev_b32_e32 v31, 16, v192
	v_and_b32_e32 v16, 0xffff0000, v192
	v_lshlrev_b32_e32 v32, 16, v193
	v_and_b32_e32 v17, 0xffff0000, v193
	v_lshlrev_b32_e32 v36, 16, v187
	v_and_b32_e32 v21, 0xffff0000, v187
	v_lshlrev_b32_e32 v33, 16, v194
	v_and_b32_e32 v18, 0xffff0000, v194
	v_lshlrev_b32_e32 v34, 16, v195
	v_and_b32_e32 v19, 0xffff0000, v195
	v_lshlrev_b32_e32 v37, 16, v188
	v_and_b32_e32 v22, 0xffff0000, v188
	v_lshlrev_b32_e32 v38, 16, v189
	v_and_b32_e32 v23, 0xffff0000, v189
	v_fmac_f32_e32 v16, v13, v20
	v_fmac_f32_e32 v17, v15, v21
	v_fmac_f32_e32 v31, v12, v35
	v_fmac_f32_e32 v33, v8, v37
	v_fmac_f32_e32 v18, v9, v22
	v_fmac_f32_e32 v32, v14, v36
	v_fmac_f32_e32 v19, v11, v23
	v_cvt_pk_bf16_f32 v8, v31, v16
	v_cvt_pk_bf16_f32 v9, v32, v17
	v_lshl_add_u64 v[16:17], v[250:251], 0, v[24:25]
	v_fmac_f32_e32 v34, v10, v38
	v_cvt_pk_bf16_f32 v10, v33, v18
	v_cvt_pk_bf16_f32 v11, v34, v19
	v_mul_f32_e32 v4, v4, v190
	v_mul_f32_e32 v0, v0, v190
	v_mul_f32_e32 v5, v5, v190
	v_mul_f32_e32 v1, v1, v190
	v_mul_f32_e32 v6, v6, v190
	v_mul_f32_e32 v2, v2, v190
	v_mul_f32_e32 v7, v7, v190
	v_mul_f32_e32 v3, v3, v190
	v_mul_f32_e32 v4, 0xbfb8aa3b, v4
	v_mul_f32_e32 v0, 0xbfb8aa3b, v0
	v_mul_f32_e32 v5, 0xbfb8aa3b, v5
	v_mul_f32_e32 v1, 0xbfb8aa3b, v1
	v_mul_f32_e32 v6, 0xbfb8aa3b, v6
	v_mul_f32_e32 v2, 0xbfb8aa3b, v2
	v_mul_f32_e32 v7, 0xbfb8aa3b, v7
	v_mul_f32_e32 v3, 0xbfb8aa3b, v3
	v_exp_f32_e32 v4, v4
	v_exp_f32_e32 v0, v0
	v_exp_f32_e32 v5, v5
	v_exp_f32_e32 v1, v1
	v_exp_f32_e32 v6, v6
	v_exp_f32_e32 v2, v2
	v_exp_f32_e32 v7, v7
	v_exp_f32_e32 v3, v3
	v_add_f32_e32 v4, 1.0, v4
	v_add_f32_e32 v0, 1.0, v0
	v_add_f32_e32 v5, 1.0, v5
	v_add_f32_e32 v1, 1.0, v1
	v_add_f32_e32 v6, 1.0, v6
	v_add_f32_e32 v2, 1.0, v2
	v_add_f32_e32 v7, 1.0, v7
	v_add_f32_e32 v3, 1.0, v3
	v_rcp_f32_e32 v4, v4
	v_rcp_f32_e32 v0, v0
	v_rcp_f32_e32 v5, v5
	v_rcp_f32_e32 v1, v1
	v_rcp_f32_e32 v6, v6
	v_rcp_f32_e32 v2, v2
	v_rcp_f32_e32 v7, v7
	v_rcp_f32_e32 v3, v3
	v_lshl_add_u64 v[20:21], s[40:41], 0, v[24:25]
	global_store_dwordx4 v[26:27], v[8:11], off
	s_waitcnt vmcnt(5)
	v_lshlrev_b32_e32 v22, 16, v200
	v_lshlrev_b32_e32 v8, 16, v196
	v_and_b32_e32 v9, 0xffff0000, v196
	v_lshlrev_b32_e32 v10, 16, v197
	v_and_b32_e32 v11, 0xffff0000, v197
	v_lshlrev_b32_e32 v12, 16, v198
	v_and_b32_e32 v13, 0xffff0000, v198
	v_lshlrev_b32_e32 v14, 16, v199
	v_and_b32_e32 v15, 0xffff0000, v199
	v_and_b32_e32 v16, 0xffff0000, v200
	v_lshlrev_b32_e32 v23, 16, v201
	v_and_b32_e32 v17, 0xffff0000, v201
	v_lshlrev_b32_e32 v24, 16, v202
	v_and_b32_e32 v18, 0xffff0000, v202
	v_lshlrev_b32_e32 v25, 16, v203
	v_and_b32_e32 v19, 0xffff0000, v203
	v_fmac_f32_e32 v8, v4, v22
	v_fmac_f32_e32 v12, v0, v24
	v_fmac_f32_e32 v9, v5, v16
	v_fmac_f32_e32 v13, v1, v18
	v_fmac_f32_e32 v10, v6, v23
	v_fmac_f32_e32 v14, v2, v25
	v_fmac_f32_e32 v11, v7, v17
	v_fmac_f32_e32 v15, v3, v19
	v_cvt_pk_bf16_f32 v0, v8, v9
	v_cvt_pk_bf16_f32 v1, v10, v11
	v_cvt_pk_bf16_f32 v2, v12, v13
	v_cvt_pk_bf16_f32 v3, v14, v15
	global_store_dwordx4 v[20:21], v[0:3], off
	s_cbranch_vccz .LBB0_1052
	s_waitcnt vmcnt(0)
	s_cmpk_gt_u32 s3, 0xff
	s_cbranch_scc1 .LBB0_1063
	s_barrier
